# v7 + GEMM K-loop ds_read bases hoisted (no VALU left in K-loops besides MFMA), wait pairs merged, attention lane address parts hoisted per unit
# baseline (speedup 1.0000x reference)
.LBB0_37:
	s_add_u32 s21, s10, 0x100
	v_mov_b32_e32 v0, 0
	s_addc_u32 s90, s11, 0
	s_mov_b32 s22, -2
	v_mov_b32_e32 v1, v0
	v_mov_b32_e32 v2, v0
	v_mov_b32_e32 v3, v0
	v_mov_b32_e32 v4, v0
	v_mov_b32_e32 v5, v0
	v_mov_b32_e32 v6, v0
	v_mov_b32_e32 v7, v0
	v_mov_b32_e32 v16, v0
	v_mov_b32_e32 v17, v0
	v_mov_b32_e32 v18, v0
	v_mov_b32_e32 v19, v0
	v_mov_b32_e32 v20, v0
	v_mov_b32_e32 v21, v0
	v_mov_b32_e32 v22, v0
	v_mov_b32_e32 v23, v0
	v_mov_b32_e32 v32, v0
	v_mov_b32_e32 v33, v0
	v_mov_b32_e32 v34, v0
	v_mov_b32_e32 v35, v0
	v_mov_b32_e32 v36, v0
	v_mov_b32_e32 v37, v0
	v_mov_b32_e32 v38, v0
	v_mov_b32_e32 v39, v0
	v_mov_b32_e32 v48, v0
	v_mov_b32_e32 v49, v0
	v_mov_b32_e32 v50, v0
	v_mov_b32_e32 v51, v0
	v_mov_b32_e32 v52, v0
	v_mov_b32_e32 v53, v0
	v_mov_b32_e32 v54, v0
	v_mov_b32_e32 v55, v0
	v_mov_b32_e32 v8, v0
	v_mov_b32_e32 v9, v0
	v_mov_b32_e32 v10, v0
	v_mov_b32_e32 v11, v0
	v_mov_b32_e32 v12, v0
	v_mov_b32_e32 v13, v0
	v_mov_b32_e32 v14, v0
	v_mov_b32_e32 v15, v0
	v_mov_b32_e32 v24, v0
	v_mov_b32_e32 v25, v0
	v_mov_b32_e32 v26, v0
	v_mov_b32_e32 v27, v0
	v_mov_b32_e32 v28, v0
	v_mov_b32_e32 v29, v0
	v_mov_b32_e32 v30, v0
	v_mov_b32_e32 v31, v0
	v_mov_b32_e32 v40, v0
	v_mov_b32_e32 v41, v0
	v_mov_b32_e32 v42, v0
	v_mov_b32_e32 v43, v0
	v_mov_b32_e32 v44, v0
	v_mov_b32_e32 v45, v0
	v_mov_b32_e32 v46, v0
	v_mov_b32_e32 v47, v0
	v_mov_b32_e32 v56, v0
	v_mov_b32_e32 v57, v0
	v_mov_b32_e32 v58, v0
	v_mov_b32_e32 v59, v0
	v_mov_b32_e32 v60, v0
	v_mov_b32_e32 v61, v0
	v_mov_b32_e32 v62, v0
	v_mov_b32_e32 v63, v0
	v_mov_b32_e32 v64, v0
	v_mov_b32_e32 v65, v0
	v_mov_b32_e32 v66, v0
	v_mov_b32_e32 v67, v0
	v_mov_b32_e32 v68, v0
	v_mov_b32_e32 v69, v0
	v_mov_b32_e32 v70, v0
	v_mov_b32_e32 v71, v0
	v_mov_b32_e32 v80, v0
	v_mov_b32_e32 v81, v0
	v_mov_b32_e32 v82, v0
	v_mov_b32_e32 v83, v0
	v_mov_b32_e32 v84, v0
	v_mov_b32_e32 v85, v0
	v_mov_b32_e32 v86, v0
	v_mov_b32_e32 v87, v0
	v_mov_b32_e32 v96, v0
	v_mov_b32_e32 v97, v0
	v_mov_b32_e32 v98, v0
	v_mov_b32_e32 v99, v0
	v_mov_b32_e32 v100, v0
	v_mov_b32_e32 v101, v0
	v_mov_b32_e32 v102, v0
	v_mov_b32_e32 v103, v0
	v_mov_b32_e32 v112, v0
	v_mov_b32_e32 v113, v0
	v_mov_b32_e32 v114, v0
	v_mov_b32_e32 v115, v0
	v_mov_b32_e32 v116, v0
	v_mov_b32_e32 v117, v0
	v_mov_b32_e32 v118, v0
	v_mov_b32_e32 v119, v0
	v_mov_b32_e32 v72, v0
	v_mov_b32_e32 v73, v0
	v_mov_b32_e32 v74, v0
	v_mov_b32_e32 v75, v0
	v_mov_b32_e32 v76, v0
	v_mov_b32_e32 v77, v0
	v_mov_b32_e32 v78, v0
	v_mov_b32_e32 v79, v0
	v_mov_b32_e32 v88, v0
	v_mov_b32_e32 v89, v0
	v_mov_b32_e32 v90, v0
	v_mov_b32_e32 v91, v0
	v_mov_b32_e32 v92, v0
	v_mov_b32_e32 v93, v0
	v_mov_b32_e32 v94, v0
	v_mov_b32_e32 v95, v0
	v_mov_b32_e32 v104, v0
	v_mov_b32_e32 v105, v0
	v_mov_b32_e32 v106, v0
	v_mov_b32_e32 v107, v0
	v_mov_b32_e32 v108, v0
	v_mov_b32_e32 v109, v0
	v_mov_b32_e32 v110, v0
	v_mov_b32_e32 v111, v0
	v_mov_b32_e32 v120, v0
	v_mov_b32_e32 v121, v0
	v_mov_b32_e32 v122, v0
	v_mov_b32_e32 v123, v0
	v_mov_b32_e32 v124, v0
	v_mov_b32_e32 v125, v0
	v_mov_b32_e32 v126, v0
	v_mov_b32_e32 v127, v0
	v_add_u32_e32 v159, 0x10000, v143
.LBB0_38:
	s_add_u32 s10, s8, 0x100
	s_addc_u32 s11, s9, 0
	s_add_i32 s48, 0, 0x10000
	s_cmp_eq_u32 s22, 40
	s_cselect_b32 s15, s1, s11
	s_cselect_b32 s14, s0, s10
	s_cselect_b32 s13, s37, s90
	s_cselect_b32 s12, s36, s21
	s_add_i32 s49, 0, 0x14000
	ds_read_b128 v[138:141], v159
	ds_read_b128 v[146:149], v159 offset:1024
	ds_read_b128 v[150:153], v159 offset:2048
	ds_read_b128 v[154:157], v159 offset:3072
	ds_read_b128 v[162:165], v159 offset:16384
	ds_read_b128 v[166:169], v159 offset:17408
	ds_read_b128 v[170:173], v159 offset:18432
	ds_read_b128 v[174:177], v159 offset:19456
	s_add_i32 m0, s29, 0xc000
	ds_read_b128 v[178:181], v145
	ds_read_b128 v[182:185], v145 offset:1024
	ds_read_b128 v[186:189], v145 offset:2048
	ds_read_b128 v[190:193], v145 offset:3072
	ds_read_b128 v[194:197], v145 offset:4096
	ds_read_b128 v[198:201], v145 offset:5120
	ds_read_b128 v[202:205], v145 offset:6144
	global_load_lds_dwordx4 v136, s[8:9]
	s_add_i32 m0, s29, 0xe000
	ds_read_b128 v[206:209], v145 offset:7168
	global_load_lds_dwordx4 v134, s[8:9]
	s_waitcnt vmcnt(8) lgkmcnt(0)
	s_barrier
	v_mfma_f32_16x16x32_bf16 v[124:127], v[138:141], v[178:181], v[124:127]
	v_mfma_f32_16x16x32_bf16 v[120:123], v[150:153], v[178:181], v[120:123]
	v_mfma_f32_16x16x32_bf16 v[108:111], v[138:141], v[186:189], v[108:111]
	v_mfma_f32_16x16x32_bf16 v[104:107], v[150:153], v[186:189], v[104:107]
	v_mfma_f32_16x16x32_bf16 v[92:95], v[138:141], v[194:197], v[92:95]
	v_mfma_f32_16x16x32_bf16 v[88:91], v[150:153], v[194:197], v[88:91]
	v_mfma_f32_16x16x32_bf16 v[76:79], v[138:141], v[202:205], v[76:79]
	v_mfma_f32_16x16x32_bf16 v[72:75], v[150:153], v[202:205], v[72:75]
	v_mfma_f32_16x16x32_bf16 v[124:127], v[146:149], v[182:185], v[124:127]
	v_mfma_f32_16x16x32_bf16 v[120:123], v[154:157], v[182:185], v[120:123]
	v_mfma_f32_16x16x32_bf16 v[108:111], v[146:149], v[190:193], v[108:111]
	v_mfma_f32_16x16x32_bf16 v[104:107], v[154:157], v[190:193], v[104:107]
	v_mfma_f32_16x16x32_bf16 v[92:95], v[146:149], v[198:201], v[92:95]
	v_mfma_f32_16x16x32_bf16 v[88:91], v[154:157], v[198:201], v[88:91]
	v_mfma_f32_16x16x32_bf16 v[76:79], v[146:149], v[206:209], v[76:79]
	v_mfma_f32_16x16x32_bf16 v[72:75], v[154:157], v[206:209], v[72:75]
	v_mfma_f32_16x16x32_bf16 v[116:119], v[162:165], v[178:181], v[116:119]
	v_mfma_f32_16x16x32_bf16 v[112:115], v[170:173], v[178:181], v[112:115]
	v_mfma_f32_16x16x32_bf16 v[100:103], v[162:165], v[186:189], v[100:103]
	v_mfma_f32_16x16x32_bf16 v[96:99], v[170:173], v[186:189], v[96:99]
	v_mfma_f32_16x16x32_bf16 v[84:87], v[162:165], v[194:197], v[84:87]
	v_mfma_f32_16x16x32_bf16 v[80:83], v[170:173], v[194:197], v[80:83]
	v_mfma_f32_16x16x32_bf16 v[68:71], v[162:165], v[202:205], v[68:71]
	v_mfma_f32_16x16x32_bf16 v[64:67], v[170:173], v[202:205], v[64:67]
	v_mfma_f32_16x16x32_bf16 v[116:119], v[166:169], v[182:185], v[116:119]
	v_mfma_f32_16x16x32_bf16 v[112:115], v[174:177], v[182:185], v[112:115]
	v_mfma_f32_16x16x32_bf16 v[100:103], v[166:169], v[190:193], v[100:103]
	v_mfma_f32_16x16x32_bf16 v[96:99], v[174:177], v[190:193], v[96:99]
	v_mfma_f32_16x16x32_bf16 v[84:87], v[166:169], v[198:201], v[84:87]
	v_mfma_f32_16x16x32_bf16 v[80:83], v[174:177], v[198:201], v[80:83]
	v_mfma_f32_16x16x32_bf16 v[68:71], v[166:169], v[206:209], v[68:71]
	v_mfma_f32_16x16x32_bf16 v[64:67], v[174:177], v[206:209], v[64:67]
	s_barrier
	s_add_i32 s8, s48, s28
	s_mov_b32 m0, s8
	ds_read_b128 v[178:181], v145 offset:16384
	ds_read_b128 v[182:185], v145 offset:17408
	ds_read_b128 v[186:189], v145 offset:18432
	ds_read_b128 v[190:193], v145 offset:19456
	global_load_lds_dwordx4 v160, s[12:13]
	s_add_i32 m0, s8, 0x2000
	s_add_u32 s8, s12, 0xb0000
	s_addc_u32 s9, s13, 0
	s_add_i32 s48, s49, s28
	global_load_lds_dwordx4 v132, s[12:13]
	s_mov_b32 m0, s48
	ds_read_b128 v[206:209], v145 offset:23552
	global_load_lds_dwordx4 v160, s[8:9]
	s_add_i32 m0, s48, 0x2000
	ds_read_b128 v[202:205], v145 offset:22528
	global_load_lds_dwordx4 v132, s[8:9]
	s_mov_b32 m0, s29
	ds_read_b128 v[198:201], v145 offset:21504
	global_load_lds_dwordx4 v128, s[14:15]
	s_mov_b32 m0, s30
	ds_read_b128 v[194:197], v145 offset:20480
	global_load_lds_dwordx4 v130, s[14:15]
	s_waitcnt vmcnt(8) lgkmcnt(0)
	s_barrier
	v_mfma_f32_16x16x32_bf16 v[60:63], v[138:141], v[178:181], v[60:63]
	v_mfma_f32_16x16x32_bf16 v[56:59], v[150:153], v[178:181], v[56:59]
	v_mfma_f32_16x16x32_bf16 v[44:47], v[138:141], v[186:189], v[44:47]
	v_mfma_f32_16x16x32_bf16 v[40:43], v[150:153], v[186:189], v[40:43]
	v_mfma_f32_16x16x32_bf16 v[28:31], v[138:141], v[194:197], v[28:31]
	v_mfma_f32_16x16x32_bf16 v[24:27], v[150:153], v[194:197], v[24:27]
	v_mfma_f32_16x16x32_bf16 v[12:15], v[138:141], v[202:205], v[12:15]
	v_mfma_f32_16x16x32_bf16 v[8:11], v[150:153], v[202:205], v[8:11]
	v_mfma_f32_16x16x32_bf16 v[60:63], v[146:149], v[182:185], v[60:63]
	v_mfma_f32_16x16x32_bf16 v[56:59], v[154:157], v[182:185], v[56:59]
	v_mfma_f32_16x16x32_bf16 v[44:47], v[146:149], v[190:193], v[44:47]
	v_mfma_f32_16x16x32_bf16 v[40:43], v[154:157], v[190:193], v[40:43]
	v_mfma_f32_16x16x32_bf16 v[28:31], v[146:149], v[198:201], v[28:31]
	v_mfma_f32_16x16x32_bf16 v[24:27], v[154:157], v[198:201], v[24:27]
	v_mfma_f32_16x16x32_bf16 v[12:15], v[146:149], v[206:209], v[12:15]
	v_mfma_f32_16x16x32_bf16 v[8:11], v[154:157], v[206:209], v[8:11]
	v_mfma_f32_16x16x32_bf16 v[52:55], v[162:165], v[178:181], v[52:55]
	v_mfma_f32_16x16x32_bf16 v[48:51], v[170:173], v[178:181], v[48:51]
	v_mfma_f32_16x16x32_bf16 v[36:39], v[162:165], v[186:189], v[36:39]
	v_mfma_f32_16x16x32_bf16 v[32:35], v[170:173], v[186:189], v[32:35]
	v_mfma_f32_16x16x32_bf16 v[20:23], v[162:165], v[194:197], v[20:23]
	v_mfma_f32_16x16x32_bf16 v[16:19], v[170:173], v[194:197], v[16:19]
	v_mfma_f32_16x16x32_bf16 v[4:7], v[162:165], v[202:205], v[4:7]
	v_mfma_f32_16x16x32_bf16 v[0:3], v[170:173], v[202:205], v[0:3]
	v_mfma_f32_16x16x32_bf16 v[52:55], v[166:169], v[182:185], v[52:55]
	v_mfma_f32_16x16x32_bf16 v[48:51], v[174:177], v[182:185], v[48:51]
	v_mfma_f32_16x16x32_bf16 v[36:39], v[166:169], v[190:193], v[36:39]
	v_mfma_f32_16x16x32_bf16 v[32:35], v[174:177], v[190:193], v[32:35]
	v_mfma_f32_16x16x32_bf16 v[20:23], v[166:169], v[198:201], v[20:23]
	v_mfma_f32_16x16x32_bf16 v[16:19], v[174:177], v[198:201], v[16:19]
	v_mfma_f32_16x16x32_bf16 v[4:7], v[166:169], v[206:209], v[4:7]
	v_mfma_f32_16x16x32_bf16 v[0:3], v[174:177], v[206:209], v[0:3]
	s_barrier
	s_add_i32 s48, 0, 0x18000
	s_add_i32 s49, 0, 0x1c000
	ds_read_b128 v[138:141], v159 offset:32768
	ds_read_b128 v[146:149], v159 offset:33792
	ds_read_b128 v[150:153], v159 offset:34816
	ds_read_b128 v[154:157], v159 offset:35840
	ds_read_b128 v[162:165], v159 offset:49152
	ds_read_b128 v[166:169], v159 offset:50176
	ds_read_b128 v[170:173], v159 offset:51200
	ds_read_b128 v[174:177], v159 offset:52224
	s_add_u32 s8, s14, 0xb0000
	s_addc_u32 s9, s15, 0
	s_mov_b32 m0, s31
	ds_read_b128 v[178:181], v145 offset:32768
	ds_read_b128 v[182:185], v145 offset:33792
	ds_read_b128 v[186:189], v145 offset:34816
	ds_read_b128 v[190:193], v145 offset:35840
	ds_read_b128 v[194:197], v145 offset:36864
	ds_read_b128 v[198:201], v145 offset:37888
	ds_read_b128 v[202:205], v145 offset:38912
	global_load_lds_dwordx4 v128, s[8:9]
	s_mov_b32 m0, s33
	ds_read_b128 v[206:209], v145 offset:39936
	global_load_lds_dwordx4 v130, s[8:9]
	s_waitcnt vmcnt(8) lgkmcnt(0)
	s_barrier
	v_mfma_f32_16x16x32_bf16 v[124:127], v[138:141], v[178:181], v[124:127]
	v_mfma_f32_16x16x32_bf16 v[120:123], v[150:153], v[178:181], v[120:123]
	v_mfma_f32_16x16x32_bf16 v[108:111], v[138:141], v[186:189], v[108:111]
	v_mfma_f32_16x16x32_bf16 v[104:107], v[150:153], v[186:189], v[104:107]
	v_mfma_f32_16x16x32_bf16 v[92:95], v[138:141], v[194:197], v[92:95]
	v_mfma_f32_16x16x32_bf16 v[88:91], v[150:153], v[194:197], v[88:91]
	v_mfma_f32_16x16x32_bf16 v[76:79], v[138:141], v[202:205], v[76:79]
	v_mfma_f32_16x16x32_bf16 v[72:75], v[150:153], v[202:205], v[72:75]
	v_mfma_f32_16x16x32_bf16 v[124:127], v[146:149], v[182:185], v[124:127]
	v_mfma_f32_16x16x32_bf16 v[120:123], v[154:157], v[182:185], v[120:123]
	v_mfma_f32_16x16x32_bf16 v[108:111], v[146:149], v[190:193], v[108:111]
	v_mfma_f32_16x16x32_bf16 v[104:107], v[154:157], v[190:193], v[104:107]
	v_mfma_f32_16x16x32_bf16 v[92:95], v[146:149], v[198:201], v[92:95]
	v_mfma_f32_16x16x32_bf16 v[88:91], v[154:157], v[198:201], v[88:91]
	v_mfma_f32_16x16x32_bf16 v[76:79], v[146:149], v[206:209], v[76:79]
	v_mfma_f32_16x16x32_bf16 v[72:75], v[154:157], v[206:209], v[72:75]
	v_mfma_f32_16x16x32_bf16 v[116:119], v[162:165], v[178:181], v[116:119]
	v_mfma_f32_16x16x32_bf16 v[112:115], v[170:173], v[178:181], v[112:115]
	v_mfma_f32_16x16x32_bf16 v[100:103], v[162:165], v[186:189], v[100:103]
	v_mfma_f32_16x16x32_bf16 v[96:99], v[170:173], v[186:189], v[96:99]
	v_mfma_f32_16x16x32_bf16 v[84:87], v[162:165], v[194:197], v[84:87]
	v_mfma_f32_16x16x32_bf16 v[80:83], v[170:173], v[194:197], v[80:83]
	v_mfma_f32_16x16x32_bf16 v[68:71], v[162:165], v[202:205], v[68:71]
	v_mfma_f32_16x16x32_bf16 v[64:67], v[170:173], v[202:205], v[64:67]
	v_mfma_f32_16x16x32_bf16 v[116:119], v[166:169], v[182:185], v[116:119]
	v_mfma_f32_16x16x32_bf16 v[112:115], v[174:177], v[182:185], v[112:115]
	v_mfma_f32_16x16x32_bf16 v[100:103], v[166:169], v[190:193], v[100:103]
	v_mfma_f32_16x16x32_bf16 v[96:99], v[174:177], v[190:193], v[96:99]
	v_mfma_f32_16x16x32_bf16 v[84:87], v[166:169], v[198:201], v[84:87]
	v_mfma_f32_16x16x32_bf16 v[80:83], v[174:177], v[198:201], v[80:83]
	v_mfma_f32_16x16x32_bf16 v[68:71], v[166:169], v[206:209], v[68:71]
	v_mfma_f32_16x16x32_bf16 v[64:67], v[174:177], v[206:209], v[64:67]
	s_barrier
	s_add_i32 s8, s48, s28
	s_add_i32 m0, s8, 0xffffff80
	ds_read_b128 v[178:181], v145 offset:49152
	ds_read_b128 v[182:185], v145 offset:50176
	ds_read_b128 v[186:189], v145 offset:51200
	ds_read_b128 v[190:193], v145 offset:52224
	global_load_lds_dwordx4 v160, s[12:13] offset:128
	s_add_i32 m0, s8, 0x1f80
	s_add_u32 s8, s12, 0xb0080
	s_addc_u32 s9, s13, 0
	global_load_lds_dwordx4 v132, s[12:13] offset:128
	s_add_i32 s12, s49, s28
	s_mov_b32 m0, s12
	ds_read_b128 v[206:209], v145 offset:56320
	global_load_lds_dwordx4 v160, s[8:9]
	s_add_i32 m0, s12, 0x2000
	ds_read_b128 v[202:205], v145 offset:55296
	global_load_lds_dwordx4 v132, s[8:9]
	s_add_i32 m0, s34, 0xffffff80
	ds_read_b128 v[198:201], v145 offset:54272
	global_load_lds_dwordx4 v128, s[14:15] offset:128
	s_add_i32 m0, s35, 0xffffff80
	ds_read_b128 v[194:197], v145 offset:53248
	global_load_lds_dwordx4 v130, s[14:15] offset:128
	s_waitcnt vmcnt(8) lgkmcnt(0)
	s_barrier
	v_mfma_f32_16x16x32_bf16 v[60:63], v[138:141], v[178:181], v[60:63]
	v_mfma_f32_16x16x32_bf16 v[56:59], v[150:153], v[178:181], v[56:59]
	v_mfma_f32_16x16x32_bf16 v[44:47], v[138:141], v[186:189], v[44:47]
	v_mfma_f32_16x16x32_bf16 v[40:43], v[150:153], v[186:189], v[40:43]
	v_mfma_f32_16x16x32_bf16 v[28:31], v[138:141], v[194:197], v[28:31]
	v_mfma_f32_16x16x32_bf16 v[24:27], v[150:153], v[194:197], v[24:27]
	v_mfma_f32_16x16x32_bf16 v[12:15], v[138:141], v[202:205], v[12:15]
	v_mfma_f32_16x16x32_bf16 v[8:11], v[150:153], v[202:205], v[8:11]
	v_mfma_f32_16x16x32_bf16 v[60:63], v[146:149], v[182:185], v[60:63]
	v_mfma_f32_16x16x32_bf16 v[56:59], v[154:157], v[182:185], v[56:59]
	v_mfma_f32_16x16x32_bf16 v[44:47], v[146:149], v[190:193], v[44:47]
	v_mfma_f32_16x16x32_bf16 v[40:43], v[154:157], v[190:193], v[40:43]
	v_mfma_f32_16x16x32_bf16 v[28:31], v[146:149], v[198:201], v[28:31]
	v_mfma_f32_16x16x32_bf16 v[24:27], v[154:157], v[198:201], v[24:27]
	v_mfma_f32_16x16x32_bf16 v[12:15], v[146:149], v[206:209], v[12:15]
	v_mfma_f32_16x16x32_bf16 v[8:11], v[154:157], v[206:209], v[8:11]
	v_mfma_f32_16x16x32_bf16 v[52:55], v[162:165], v[178:181], v[52:55]
	v_mfma_f32_16x16x32_bf16 v[48:51], v[170:173], v[178:181], v[48:51]
	v_mfma_f32_16x16x32_bf16 v[36:39], v[162:165], v[186:189], v[36:39]
	v_mfma_f32_16x16x32_bf16 v[32:35], v[170:173], v[186:189], v[32:35]
	v_mfma_f32_16x16x32_bf16 v[20:23], v[162:165], v[194:197], v[20:23]
	v_mfma_f32_16x16x32_bf16 v[16:19], v[170:173], v[194:197], v[16:19]
	v_mfma_f32_16x16x32_bf16 v[4:7], v[162:165], v[202:205], v[4:7]
	v_mfma_f32_16x16x32_bf16 v[0:3], v[170:173], v[202:205], v[0:3]
	v_mfma_f32_16x16x32_bf16 v[52:55], v[166:169], v[182:185], v[52:55]
	v_mfma_f32_16x16x32_bf16 v[48:51], v[174:177], v[182:185], v[48:51]
	v_mfma_f32_16x16x32_bf16 v[36:39], v[166:169], v[190:193], v[36:39]
	v_mfma_f32_16x16x32_bf16 v[32:35], v[174:177], v[190:193], v[32:35]
	v_mfma_f32_16x16x32_bf16 v[20:23], v[166:169], v[198:201], v[20:23]
	v_mfma_f32_16x16x32_bf16 v[16:19], v[174:177], v[198:201], v[16:19]
	v_mfma_f32_16x16x32_bf16 v[4:7], v[166:169], v[206:209], v[4:7]
	v_mfma_f32_16x16x32_bf16 v[0:3], v[174:177], v[206:209], v[0:3]
	s_barrier
	s_add_i32 s22, s22, 2
	s_add_u32 s21, s21, 0x100
	s_addc_u32 s90, s90, 0
	s_cmp_gt_u32 s22, 41
	s_mov_b64 s[8:9], s[10:11]
	s_cbranch_scc0 .LBB0_38
	v_lshl_add_u32 v140, s44, 8, v142
	v_lshl_or_b32 v138, s45, 8, v144
	v_lshlrev_b32_e32 v139, 12, v140
	v_lshl_add_u32 v139, v138, 2, v139
	v_lshlrev_b32_e32 v141, 11, v140
	v_lshl_add_u32 v138, v138, 1, v141
	s_mov_b64 s[8:9], s[4:5]
	global_load_dwordx4 v[146:149], v138, s[8:9]
	global_load_dwordx4 v[150:153], v138, s[8:9] offset:256
	s_add_u32 s8, s8, 0x8000
	s_addc_u32 s9, s9, 0
	global_load_dwordx4 v[154:157], v138, s[8:9]
	global_load_dwordx4 v[162:165], v138, s[8:9] offset:256
	s_add_u32 s8, s8, 0x8000
	s_addc_u32 s9, s9, 0
	global_load_dwordx4 v[166:169], v138, s[8:9]
	global_load_dwordx4 v[174:177], v138, s[8:9] offset:256
	s_add_u32 s8, s8, 0x8000
	s_addc_u32 s9, s9, 0
	global_load_dwordx4 v[178:181], v138, s[8:9]
	global_load_dwordx4 v[182:185], v138, s[8:9] offset:256
	s_add_u32 s8, s8, 0x28000
	s_addc_u32 s9, s9, 0
	global_load_dwordx4 v[186:189], v138, s[8:9]
	global_load_dwordx4 v[190:193], v138, s[8:9] offset:256
	s_add_u32 s8, s8, 0x8000
	s_addc_u32 s9, s9, 0
	global_load_dwordx4 v[194:197], v138, s[8:9]
	global_load_dwordx4 v[198:201], v138, s[8:9] offset:256
	s_add_u32 s8, s8, 0x8000
	s_addc_u32 s9, s9, 0
	global_load_dwordx4 v[202:205], v138, s[8:9]
	global_load_dwordx4 v[206:209], v138, s[8:9] offset:256
	s_add_u32 s8, s8, 0x8000
	s_addc_u32 s9, s9, 0
	global_load_dwordx4 v[210:213], v138, s[8:9]
	global_load_dwordx4 v[214:217], v138, s[8:9] offset:256
	s_and_b64 vcc, exec, s[6:7]
	s_cbranch_vccz .LBB0_41
	s_barrier

.LBB0_55:
	s_ashr_i32 s37, s36, 31
	s_lshl_b64 s[14:15], s[36:37], 19
	s_add_u32 s44, s24, s14
	s_addc_u32 s45, s25, s15
	s_and_b64 s[14:15], s[38:39], exec
	s_cselect_b32 s20, s45, s13
	s_cselect_b32 s37, s44, s12
	s_ashr_i32 s41, s40, 31
	s_lshl_b64 s[14:15], s[40:41], 19
	s_add_u32 s92, s26, s14
	s_addc_u32 s93, s27, s15
	s_and_b64 s[14:15], s[38:39], exec
	s_cselect_b32 s41, s93, s11
	s_cselect_b32 s91, s92, s10
	s_add_u32 s96, s10, 0x100
	s_addc_u32 s21, s11, 0
	s_add_u32 s10, s12, 0x40080
	v_mov_b32_e32 v4, 0
	s_addc_u32 s11, s13, 0
	s_mov_b32 s22, -2
	v_mov_b32_e32 v5, v4
	v_mov_b32_e32 v6, v4
	v_mov_b32_e32 v7, v4
	v_mov_b32_e32 v8, v4
	v_mov_b32_e32 v9, v4
	v_mov_b32_e32 v10, v4
	v_mov_b32_e32 v11, v4
	v_mov_b32_e32 v20, v4
	v_mov_b32_e32 v21, v4
	v_mov_b32_e32 v22, v4
	v_mov_b32_e32 v23, v4
	v_mov_b32_e32 v24, v4
	v_mov_b32_e32 v25, v4
	v_mov_b32_e32 v26, v4
	v_mov_b32_e32 v27, v4
	v_mov_b32_e32 v36, v4
	v_mov_b32_e32 v37, v4
	v_mov_b32_e32 v38, v4
	v_mov_b32_e32 v39, v4
	v_mov_b32_e32 v40, v4
	v_mov_b32_e32 v41, v4
	v_mov_b32_e32 v42, v4
	v_mov_b32_e32 v43, v4
	v_mov_b32_e32 v52, v4
	v_mov_b32_e32 v53, v4
	v_mov_b32_e32 v54, v4
	v_mov_b32_e32 v55, v4
	v_mov_b32_e32 v56, v4
	v_mov_b32_e32 v57, v4
	v_mov_b32_e32 v58, v4
	v_mov_b32_e32 v59, v4
	v_mov_b32_e32 v0, v4
	v_mov_b32_e32 v1, v4
	v_mov_b32_e32 v2, v4
	v_mov_b32_e32 v3, v4
	v_mov_b32_e32 v12, v4
	v_mov_b32_e32 v13, v4
	v_mov_b32_e32 v14, v4
	v_mov_b32_e32 v15, v4
	v_mov_b32_e32 v16, v4
	v_mov_b32_e32 v17, v4
	v_mov_b32_e32 v18, v4
	v_mov_b32_e32 v19, v4
	v_mov_b32_e32 v28, v4
	v_mov_b32_e32 v29, v4
	v_mov_b32_e32 v30, v4
	v_mov_b32_e32 v31, v4
	v_mov_b32_e32 v32, v4
	v_mov_b32_e32 v33, v4
	v_mov_b32_e32 v34, v4
	v_mov_b32_e32 v35, v4
	v_mov_b32_e32 v44, v4
	v_mov_b32_e32 v45, v4
	v_mov_b32_e32 v46, v4
	v_mov_b32_e32 v47, v4
	v_mov_b32_e32 v48, v4
	v_mov_b32_e32 v49, v4
	v_mov_b32_e32 v50, v4
	v_mov_b32_e32 v51, v4
	v_mov_b32_e32 v60, v4
	v_mov_b32_e32 v61, v4
	v_mov_b32_e32 v62, v4
	v_mov_b32_e32 v63, v4
	v_mov_b32_e32 v68, v4
	v_mov_b32_e32 v69, v4
	v_mov_b32_e32 v70, v4
	v_mov_b32_e32 v71, v4
	v_mov_b32_e32 v72, v4
	v_mov_b32_e32 v73, v4
	v_mov_b32_e32 v74, v4
	v_mov_b32_e32 v75, v4
	v_mov_b32_e32 v80, v4
	v_mov_b32_e32 v81, v4
	v_mov_b32_e32 v82, v4
	v_mov_b32_e32 v83, v4
	v_mov_b32_e32 v88, v4
	v_mov_b32_e32 v89, v4
	v_mov_b32_e32 v90, v4
	v_mov_b32_e32 v91, v4
	v_mov_b32_e32 v96, v4
	v_mov_b32_e32 v97, v4
	v_mov_b32_e32 v98, v4
	v_mov_b32_e32 v99, v4
	v_mov_b32_e32 v104, v4
	v_mov_b32_e32 v105, v4
	v_mov_b32_e32 v106, v4
	v_mov_b32_e32 v107, v4
	v_mov_b32_e32 v112, v4
	v_mov_b32_e32 v113, v4
	v_mov_b32_e32 v114, v4
	v_mov_b32_e32 v115, v4
	v_mov_b32_e32 v120, v4
	v_mov_b32_e32 v121, v4
	v_mov_b32_e32 v122, v4
	v_mov_b32_e32 v123, v4
	v_mov_b32_e32 v64, v4
	v_mov_b32_e32 v65, v4
	v_mov_b32_e32 v66, v4
	v_mov_b32_e32 v67, v4
	v_mov_b32_e32 v76, v4
	v_mov_b32_e32 v77, v4
	v_mov_b32_e32 v78, v4
	v_mov_b32_e32 v79, v4
	v_mov_b32_e32 v84, v4
	v_mov_b32_e32 v85, v4
	v_mov_b32_e32 v86, v4
	v_mov_b32_e32 v87, v4
	v_mov_b32_e32 v92, v4
	v_mov_b32_e32 v93, v4
	v_mov_b32_e32 v94, v4
	v_mov_b32_e32 v95, v4
	v_mov_b32_e32 v100, v4
	v_mov_b32_e32 v101, v4
	v_mov_b32_e32 v102, v4
	v_mov_b32_e32 v103, v4
	v_mov_b32_e32 v108, v4
	v_mov_b32_e32 v109, v4
	v_mov_b32_e32 v110, v4
	v_mov_b32_e32 v111, v4
	v_mov_b32_e32 v116, v4
	v_mov_b32_e32 v117, v4
	v_mov_b32_e32 v118, v4
	v_mov_b32_e32 v119, v4
	v_mov_b32_e32 v124, v4
	v_mov_b32_e32 v125, v4
	v_mov_b32_e32 v126, v4
	v_mov_b32_e32 v127, v4
	v_add_u32_e32 v159, 0x10000, v147
.LBB0_56:
	s_add_u32 s12, s10, 0xfffc0080
	s_addc_u32 s13, s11, -1
	s_add_i32 s48, 0, 0x10000
	s_cmp_eq_u32 s22, 12
	s_cselect_b32 s15, s20, s13
	s_cselect_b32 s14, s37, s12
	s_cselect_b32 s13, s41, s21
	s_cselect_b32 s12, s91, s96
	s_add_i32 s50, 0, 0x14000
	ds_read_b128 v[138:141], v159
	ds_read_b128 v[142:145], v159 offset:1024
	ds_read_b128 v[150:153], v159 offset:2048
	ds_read_b128 v[154:157], v159 offset:3072
	ds_read_b128 v[162:165], v159 offset:16384
	ds_read_b128 v[166:169], v159 offset:17408
	ds_read_b128 v[170:173], v159 offset:18432
	ds_read_b128 v[174:177], v159 offset:19456
	s_add_i32 m0, s30, 0xc000
	ds_read_b128 v[178:181], v149
	ds_read_b128 v[182:185], v149 offset:1024
	ds_read_b128 v[186:189], v149 offset:2048
	ds_read_b128 v[190:193], v149 offset:3072
	ds_read_b128 v[194:197], v149 offset:4096
	ds_read_b128 v[198:201], v149 offset:5120
	ds_read_b128 v[202:205], v149 offset:6144
	global_load_lds_dwordx4 v136, s[10:11]
	s_add_i32 m0, s30, 0xe000
	ds_read_b128 v[206:209], v149 offset:7168
	global_load_lds_dwordx4 v134, s[10:11]
	s_waitcnt vmcnt(8) lgkmcnt(0)
	s_barrier
	v_mfma_f32_16x16x32_bf16 v[124:127], v[138:141], v[178:181], v[124:127]
	v_mfma_f32_16x16x32_bf16 v[116:119], v[150:153], v[178:181], v[116:119]
	v_mfma_f32_16x16x32_bf16 v[108:111], v[138:141], v[186:189], v[108:111]
	v_mfma_f32_16x16x32_bf16 v[100:103], v[150:153], v[186:189], v[100:103]
	v_mfma_f32_16x16x32_bf16 v[92:95], v[138:141], v[194:197], v[92:95]
	v_mfma_f32_16x16x32_bf16 v[84:87], v[150:153], v[194:197], v[84:87]
	v_mfma_f32_16x16x32_bf16 v[76:79], v[138:141], v[202:205], v[76:79]
	v_mfma_f32_16x16x32_bf16 v[64:67], v[150:153], v[202:205], v[64:67]
	v_mfma_f32_16x16x32_bf16 v[124:127], v[142:145], v[182:185], v[124:127]
	v_mfma_f32_16x16x32_bf16 v[116:119], v[154:157], v[182:185], v[116:119]
	v_mfma_f32_16x16x32_bf16 v[108:111], v[142:145], v[190:193], v[108:111]
	v_mfma_f32_16x16x32_bf16 v[100:103], v[154:157], v[190:193], v[100:103]
	v_mfma_f32_16x16x32_bf16 v[92:95], v[142:145], v[198:201], v[92:95]
	v_mfma_f32_16x16x32_bf16 v[84:87], v[154:157], v[198:201], v[84:87]
	v_mfma_f32_16x16x32_bf16 v[76:79], v[142:145], v[206:209], v[76:79]
	v_mfma_f32_16x16x32_bf16 v[64:67], v[154:157], v[206:209], v[64:67]
	v_mfma_f32_16x16x32_bf16 v[120:123], v[162:165], v[178:181], v[120:123]
	v_mfma_f32_16x16x32_bf16 v[112:115], v[170:173], v[178:181], v[112:115]
	v_mfma_f32_16x16x32_bf16 v[104:107], v[162:165], v[186:189], v[104:107]
	v_mfma_f32_16x16x32_bf16 v[96:99], v[170:173], v[186:189], v[96:99]
	v_mfma_f32_16x16x32_bf16 v[88:91], v[162:165], v[194:197], v[88:91]
	v_mfma_f32_16x16x32_bf16 v[80:83], v[170:173], v[194:197], v[80:83]
	v_mfma_f32_16x16x32_bf16 v[72:75], v[162:165], v[202:205], v[72:75]
	v_mfma_f32_16x16x32_bf16 v[68:71], v[170:173], v[202:205], v[68:71]
	v_mfma_f32_16x16x32_bf16 v[120:123], v[166:169], v[182:185], v[120:123]
	v_mfma_f32_16x16x32_bf16 v[112:115], v[174:177], v[182:185], v[112:115]
	v_mfma_f32_16x16x32_bf16 v[104:107], v[166:169], v[190:193], v[104:107]
	v_mfma_f32_16x16x32_bf16 v[96:99], v[174:177], v[190:193], v[96:99]
	v_mfma_f32_16x16x32_bf16 v[88:91], v[166:169], v[198:201], v[88:91]
	v_mfma_f32_16x16x32_bf16 v[80:83], v[174:177], v[198:201], v[80:83]
	v_mfma_f32_16x16x32_bf16 v[72:75], v[166:169], v[206:209], v[72:75]
	v_mfma_f32_16x16x32_bf16 v[68:71], v[174:177], v[206:209], v[68:71]
	s_barrier
	s_add_i32 s48, s48, s28
	s_mov_b32 m0, s48
	ds_read_b128 v[178:181], v149 offset:16384
	ds_read_b128 v[182:185], v149 offset:17408
	ds_read_b128 v[186:189], v149 offset:18432
	ds_read_b128 v[190:193], v149 offset:19456
	global_load_lds_dwordx4 v160, s[12:13]
	s_add_i32 m0, s48, 0x2000
	s_add_u32 s48, s12, 0x40000
	s_addc_u32 s49, s13, 0
	s_add_i32 s50, s50, s28
	global_load_lds_dwordx4 v128, s[12:13]
	s_mov_b32 m0, s50
	ds_read_b128 v[206:209], v149 offset:23552
	global_load_lds_dwordx4 v160, s[48:49]
	s_add_i32 m0, s50, 0x2000
	ds_read_b128 v[202:205], v149 offset:22528
	global_load_lds_dwordx4 v128, s[48:49]
	s_mov_b32 m0, s30
	ds_read_b128 v[198:201], v149 offset:21504
	global_load_lds_dwordx4 v132, s[14:15]
	s_mov_b32 m0, s31
	ds_read_b128 v[194:197], v149 offset:20480
	global_load_lds_dwordx4 v130, s[14:15]
	s_waitcnt vmcnt(8) lgkmcnt(0)
	s_barrier
	v_mfma_f32_16x16x32_bf16 v[60:63], v[138:141], v[178:181], v[60:63]
	v_mfma_f32_16x16x32_bf16 v[48:51], v[150:153], v[178:181], v[48:51]
	v_mfma_f32_16x16x32_bf16 v[44:47], v[138:141], v[186:189], v[44:47]
	v_mfma_f32_16x16x32_bf16 v[32:35], v[150:153], v[186:189], v[32:35]
	v_mfma_f32_16x16x32_bf16 v[28:31], v[138:141], v[194:197], v[28:31]
	v_mfma_f32_16x16x32_bf16 v[16:19], v[150:153], v[194:197], v[16:19]
	v_mfma_f32_16x16x32_bf16 v[12:15], v[138:141], v[202:205], v[12:15]
	v_mfma_f32_16x16x32_bf16 v[0:3], v[150:153], v[202:205], v[0:3]
	v_mfma_f32_16x16x32_bf16 v[60:63], v[142:145], v[182:185], v[60:63]
	v_mfma_f32_16x16x32_bf16 v[48:51], v[154:157], v[182:185], v[48:51]
	v_mfma_f32_16x16x32_bf16 v[44:47], v[142:145], v[190:193], v[44:47]
	v_mfma_f32_16x16x32_bf16 v[32:35], v[154:157], v[190:193], v[32:35]
	v_mfma_f32_16x16x32_bf16 v[28:31], v[142:145], v[198:201], v[28:31]
	v_mfma_f32_16x16x32_bf16 v[16:19], v[154:157], v[198:201], v[16:19]
	v_mfma_f32_16x16x32_bf16 v[12:15], v[142:145], v[206:209], v[12:15]
	v_mfma_f32_16x16x32_bf16 v[0:3], v[154:157], v[206:209], v[0:3]
	v_mfma_f32_16x16x32_bf16 v[56:59], v[162:165], v[178:181], v[56:59]
	v_mfma_f32_16x16x32_bf16 v[52:55], v[170:173], v[178:181], v[52:55]
	v_mfma_f32_16x16x32_bf16 v[40:43], v[162:165], v[186:189], v[40:43]
	v_mfma_f32_16x16x32_bf16 v[36:39], v[170:173], v[186:189], v[36:39]
	v_mfma_f32_16x16x32_bf16 v[24:27], v[162:165], v[194:197], v[24:27]
	v_mfma_f32_16x16x32_bf16 v[20:23], v[170:173], v[194:197], v[20:23]
	v_mfma_f32_16x16x32_bf16 v[8:11], v[162:165], v[202:205], v[8:11]
	v_mfma_f32_16x16x32_bf16 v[4:7], v[170:173], v[202:205], v[4:7]
	v_mfma_f32_16x16x32_bf16 v[56:59], v[166:169], v[182:185], v[56:59]
	v_mfma_f32_16x16x32_bf16 v[52:55], v[174:177], v[182:185], v[52:55]
	v_mfma_f32_16x16x32_bf16 v[40:43], v[166:169], v[190:193], v[40:43]
	v_mfma_f32_16x16x32_bf16 v[36:39], v[174:177], v[190:193], v[36:39]
	v_mfma_f32_16x16x32_bf16 v[24:27], v[166:169], v[198:201], v[24:27]
	v_mfma_f32_16x16x32_bf16 v[20:23], v[174:177], v[198:201], v[20:23]
	v_mfma_f32_16x16x32_bf16 v[8:11], v[166:169], v[206:209], v[8:11]
	v_mfma_f32_16x16x32_bf16 v[4:7], v[174:177], v[206:209], v[4:7]
	s_barrier
	s_add_i32 s48, 0, 0x18000
	s_add_i32 s49, 0, 0x1c000
	ds_read_b128 v[138:141], v159 offset:32768
	ds_read_b128 v[142:145], v159 offset:33792
	ds_read_b128 v[150:153], v159 offset:34816
	ds_read_b128 v[154:157], v159 offset:35840
	ds_read_b128 v[162:165], v159 offset:49152
	ds_read_b128 v[166:169], v159 offset:50176
	ds_read_b128 v[170:173], v159 offset:51200
	ds_read_b128 v[174:177], v159 offset:52224
	s_mov_b64 s[100:101], s[14:15]
	s_add_u32 s14, s14, 0x40000
	s_addc_u32 s15, s15, 0
	s_mov_b32 m0, s33
	ds_read_b128 v[178:181], v149 offset:32768
	ds_read_b128 v[182:185], v149 offset:33792
	ds_read_b128 v[186:189], v149 offset:34816
	ds_read_b128 v[190:193], v149 offset:35840
	ds_read_b128 v[194:197], v149 offset:36864
	ds_read_b128 v[198:201], v149 offset:37888
	ds_read_b128 v[202:205], v149 offset:38912
	global_load_lds_dwordx4 v132, s[14:15]
	s_mov_b32 m0, s34
	ds_read_b128 v[206:209], v149 offset:39936
	global_load_lds_dwordx4 v130, s[14:15]
	s_waitcnt vmcnt(8) lgkmcnt(0)
	s_barrier
	v_mfma_f32_16x16x32_bf16 v[124:127], v[138:141], v[178:181], v[124:127]
	v_mfma_f32_16x16x32_bf16 v[116:119], v[150:153], v[178:181], v[116:119]
	v_mfma_f32_16x16x32_bf16 v[108:111], v[138:141], v[186:189], v[108:111]
	v_mfma_f32_16x16x32_bf16 v[100:103], v[150:153], v[186:189], v[100:103]
	v_mfma_f32_16x16x32_bf16 v[92:95], v[138:141], v[194:197], v[92:95]
	v_mfma_f32_16x16x32_bf16 v[84:87], v[150:153], v[194:197], v[84:87]
	v_mfma_f32_16x16x32_bf16 v[76:79], v[138:141], v[202:205], v[76:79]
	v_mfma_f32_16x16x32_bf16 v[64:67], v[150:153], v[202:205], v[64:67]
	v_mfma_f32_16x16x32_bf16 v[124:127], v[142:145], v[182:185], v[124:127]
	v_mfma_f32_16x16x32_bf16 v[116:119], v[154:157], v[182:185], v[116:119]
	v_mfma_f32_16x16x32_bf16 v[108:111], v[142:145], v[190:193], v[108:111]
	v_mfma_f32_16x16x32_bf16 v[100:103], v[154:157], v[190:193], v[100:103]
	v_mfma_f32_16x16x32_bf16 v[92:95], v[142:145], v[198:201], v[92:95]
	v_mfma_f32_16x16x32_bf16 v[84:87], v[154:157], v[198:201], v[84:87]
	v_mfma_f32_16x16x32_bf16 v[76:79], v[142:145], v[206:209], v[76:79]
	v_mfma_f32_16x16x32_bf16 v[64:67], v[154:157], v[206:209], v[64:67]
	v_mfma_f32_16x16x32_bf16 v[120:123], v[162:165], v[178:181], v[120:123]
	v_mfma_f32_16x16x32_bf16 v[112:115], v[170:173], v[178:181], v[112:115]
	v_mfma_f32_16x16x32_bf16 v[104:107], v[162:165], v[186:189], v[104:107]
	v_mfma_f32_16x16x32_bf16 v[96:99], v[170:173], v[186:189], v[96:99]
	v_mfma_f32_16x16x32_bf16 v[88:91], v[162:165], v[194:197], v[88:91]
	v_mfma_f32_16x16x32_bf16 v[80:83], v[170:173], v[194:197], v[80:83]
	v_mfma_f32_16x16x32_bf16 v[72:75], v[162:165], v[202:205], v[72:75]
	v_mfma_f32_16x16x32_bf16 v[68:71], v[170:173], v[202:205], v[68:71]
	v_mfma_f32_16x16x32_bf16 v[120:123], v[166:169], v[182:185], v[120:123]
	v_mfma_f32_16x16x32_bf16 v[112:115], v[174:177], v[182:185], v[112:115]
	v_mfma_f32_16x16x32_bf16 v[104:107], v[166:169], v[190:193], v[104:107]
	v_mfma_f32_16x16x32_bf16 v[96:99], v[174:177], v[190:193], v[96:99]
	v_mfma_f32_16x16x32_bf16 v[88:91], v[166:169], v[198:201], v[88:91]
	v_mfma_f32_16x16x32_bf16 v[80:83], v[174:177], v[198:201], v[80:83]
	v_mfma_f32_16x16x32_bf16 v[72:75], v[166:169], v[206:209], v[72:75]
	v_mfma_f32_16x16x32_bf16 v[68:71], v[174:177], v[206:209], v[68:71]
	s_barrier
	s_add_i32 s14, s48, s28
	s_add_i32 m0, s14, 0xffffff80
	ds_read_b128 v[178:181], v149 offset:49152
	ds_read_b128 v[182:185], v149 offset:50176
	ds_read_b128 v[186:189], v149 offset:51200
	global_load_lds_dwordx4 v160, s[12:13] offset:128
	s_add_i32 m0, s14, 0x1f80
	ds_read_b128 v[206:209], v149 offset:56320
	global_load_lds_dwordx4 v128, s[12:13] offset:128
	s_add_u32 s12, s12, 0x40080
	s_addc_u32 s13, s13, 0
	s_add_i32 s14, s49, s28
	s_mov_b32 m0, s14
	ds_read_b128 v[202:205], v149 offset:55296
	global_load_lds_dwordx4 v160, s[12:13]
	s_add_i32 m0, s14, 0x2000
	ds_read_b128 v[198:201], v149 offset:54272
	global_load_lds_dwordx4 v128, s[12:13]
	s_add_i32 m0, s35, 0xffffff80
	ds_read_b128 v[194:197], v149 offset:53248
	global_load_lds_dwordx4 v132, s[100:101] offset:128
	s_add_i32 m0, s90, 0xffffff80
	ds_read_b128 v[190:193], v149 offset:52224
	global_load_lds_dwordx4 v130, s[100:101] offset:128
	s_waitcnt vmcnt(8) lgkmcnt(0)
	s_barrier
	v_mfma_f32_16x16x32_bf16 v[60:63], v[138:141], v[178:181], v[60:63]
	v_mfma_f32_16x16x32_bf16 v[48:51], v[150:153], v[178:181], v[48:51]
	v_mfma_f32_16x16x32_bf16 v[44:47], v[138:141], v[186:189], v[44:47]
	v_mfma_f32_16x16x32_bf16 v[32:35], v[150:153], v[186:189], v[32:35]
	v_mfma_f32_16x16x32_bf16 v[28:31], v[138:141], v[194:197], v[28:31]
	v_mfma_f32_16x16x32_bf16 v[16:19], v[150:153], v[194:197], v[16:19]
	v_mfma_f32_16x16x32_bf16 v[12:15], v[138:141], v[202:205], v[12:15]
	v_mfma_f32_16x16x32_bf16 v[0:3], v[150:153], v[202:205], v[0:3]
	v_mfma_f32_16x16x32_bf16 v[60:63], v[142:145], v[182:185], v[60:63]
	v_mfma_f32_16x16x32_bf16 v[48:51], v[154:157], v[182:185], v[48:51]
	v_mfma_f32_16x16x32_bf16 v[44:47], v[142:145], v[190:193], v[44:47]
	v_mfma_f32_16x16x32_bf16 v[32:35], v[154:157], v[190:193], v[32:35]
	v_mfma_f32_16x16x32_bf16 v[28:31], v[142:145], v[198:201], v[28:31]
	v_mfma_f32_16x16x32_bf16 v[16:19], v[154:157], v[198:201], v[16:19]
	v_mfma_f32_16x16x32_bf16 v[12:15], v[142:145], v[206:209], v[12:15]
	v_mfma_f32_16x16x32_bf16 v[0:3], v[154:157], v[206:209], v[0:3]
	v_mfma_f32_16x16x32_bf16 v[56:59], v[162:165], v[178:181], v[56:59]
	v_mfma_f32_16x16x32_bf16 v[52:55], v[170:173], v[178:181], v[52:55]
	v_mfma_f32_16x16x32_bf16 v[40:43], v[162:165], v[186:189], v[40:43]
	v_mfma_f32_16x16x32_bf16 v[36:39], v[170:173], v[186:189], v[36:39]
	v_mfma_f32_16x16x32_bf16 v[24:27], v[162:165], v[194:197], v[24:27]
	v_mfma_f32_16x16x32_bf16 v[20:23], v[170:173], v[194:197], v[20:23]
	v_mfma_f32_16x16x32_bf16 v[8:11], v[162:165], v[202:205], v[8:11]
	v_mfma_f32_16x16x32_bf16 v[4:7], v[170:173], v[202:205], v[4:7]
	v_mfma_f32_16x16x32_bf16 v[56:59], v[166:169], v[182:185], v[56:59]
	v_mfma_f32_16x16x32_bf16 v[52:55], v[174:177], v[182:185], v[52:55]
	v_mfma_f32_16x16x32_bf16 v[40:43], v[166:169], v[190:193], v[40:43]
	v_mfma_f32_16x16x32_bf16 v[36:39], v[174:177], v[190:193], v[36:39]
	v_mfma_f32_16x16x32_bf16 v[24:27], v[166:169], v[198:201], v[24:27]
	v_mfma_f32_16x16x32_bf16 v[20:23], v[174:177], v[198:201], v[20:23]
	v_mfma_f32_16x16x32_bf16 v[8:11], v[166:169], v[206:209], v[8:11]
	v_mfma_f32_16x16x32_bf16 v[4:7], v[174:177], v[206:209], v[4:7]
	s_barrier
	s_add_i32 s22, s22, 2
	s_add_u32 s96, s96, 0x100
	s_addc_u32 s21, s21, 0
	s_add_u32 s10, s10, 0x100
	s_addc_u32 s11, s11, 0
	s_cmp_gt_u32 s22, 13
	s_cbranch_scc0 .LBB0_56
	v_lshl_add_u32 v192, s8, 8, v146
	v_lshlrev_b32_e32 v192, 3, v192
	global_load_dwordx2 v[176:177], v192, s[4:5]
	global_load_dwordx2 v[178:179], v192, s[4:5] offset:128
	global_load_dwordx2 v[180:181], v192, s[4:5] offset:256
	global_load_dwordx2 v[182:183], v192, s[4:5] offset:384
	global_load_dwordx2 v[184:185], v192, s[4:5] offset:1024
	global_load_dwordx2 v[186:187], v192, s[4:5] offset:1152
	global_load_dwordx2 v[188:189], v192, s[4:5] offset:1280
	global_load_dwordx2 v[190:191], v192, s[4:5] offset:1408
	s_and_b64 vcc, exec, s[6:7]
	s_cbranch_vccz .LBB0_59
	s_barrier

.LBB0_83:
	s_ashr_i32 s37, s36, 31
	s_lshl_b64 s[20:21], s[36:37], 19
	s_add_u32 s92, s24, s20
	s_addc_u32 s93, s25, s21
	s_and_b64 s[20:21], s[40:41], exec
	s_cselect_b32 s9, s93, s15
	s_cselect_b32 s20, s92, s14
	s_ashr_i32 s45, s44, 31
	s_lshl_b64 s[48:49], s[44:45], 19
	s_add_u32 s96, s26, s48
	s_addc_u32 s97, s27, s49
	s_and_b64 s[48:49], s[40:41], exec
	s_cselect_b32 s37, s97, s13
	s_cselect_b32 s45, s96, s12
	s_add_u32 s90, s12, 0x100
	s_addc_u32 s21, s13, 0
	s_add_u32 vcc_lo, s14, 0x40080
	v_mov_b32_e32 v0, 0
	s_addc_u32 vcc_hi, s15, 0
	s_mov_b32 s22, -2
	v_mov_b32_e32 v1, v0
	v_mov_b32_e32 v2, v0
	v_mov_b32_e32 v3, v0
	v_mov_b32_e32 v4, v0
	v_mov_b32_e32 v5, v0
	v_mov_b32_e32 v6, v0
	v_mov_b32_e32 v7, v0
	v_mov_b32_e32 v16, v0
	v_mov_b32_e32 v17, v0
	v_mov_b32_e32 v18, v0
	v_mov_b32_e32 v19, v0
	v_mov_b32_e32 v20, v0
	v_mov_b32_e32 v21, v0
	v_mov_b32_e32 v22, v0
	v_mov_b32_e32 v23, v0
	v_mov_b32_e32 v32, v0
	v_mov_b32_e32 v33, v0
	v_mov_b32_e32 v34, v0
	v_mov_b32_e32 v35, v0
	v_mov_b32_e32 v36, v0
	v_mov_b32_e32 v37, v0
	v_mov_b32_e32 v38, v0
	v_mov_b32_e32 v39, v0
	v_mov_b32_e32 v48, v0
	v_mov_b32_e32 v49, v0
	v_mov_b32_e32 v50, v0
	v_mov_b32_e32 v51, v0
	v_mov_b32_e32 v52, v0
	v_mov_b32_e32 v53, v0
	v_mov_b32_e32 v54, v0
	v_mov_b32_e32 v55, v0
	v_mov_b32_e32 v8, v0
	v_mov_b32_e32 v9, v0
	v_mov_b32_e32 v10, v0
	v_mov_b32_e32 v11, v0
	v_mov_b32_e32 v12, v0
	v_mov_b32_e32 v13, v0
	v_mov_b32_e32 v14, v0
	v_mov_b32_e32 v15, v0
	v_mov_b32_e32 v24, v0
	v_mov_b32_e32 v25, v0
	v_mov_b32_e32 v26, v0
	v_mov_b32_e32 v27, v0
	v_mov_b32_e32 v28, v0
	v_mov_b32_e32 v29, v0
	v_mov_b32_e32 v30, v0
	v_mov_b32_e32 v31, v0
	v_mov_b32_e32 v40, v0
	v_mov_b32_e32 v41, v0
	v_mov_b32_e32 v42, v0
	v_mov_b32_e32 v43, v0
	v_mov_b32_e32 v44, v0
	v_mov_b32_e32 v45, v0
	v_mov_b32_e32 v46, v0
	v_mov_b32_e32 v47, v0
	v_mov_b32_e32 v56, v0
	v_mov_b32_e32 v57, v0
	v_mov_b32_e32 v58, v0
	v_mov_b32_e32 v59, v0
	v_mov_b32_e32 v60, v0
	v_mov_b32_e32 v61, v0
	v_mov_b32_e32 v62, v0
	v_mov_b32_e32 v63, v0
	v_mov_b32_e32 v64, v0
	v_mov_b32_e32 v65, v0
	v_mov_b32_e32 v66, v0
	v_mov_b32_e32 v67, v0
	v_mov_b32_e32 v68, v0
	v_mov_b32_e32 v69, v0
	v_mov_b32_e32 v70, v0
	v_mov_b32_e32 v71, v0
	v_mov_b32_e32 v80, v0
	v_mov_b32_e32 v81, v0
	v_mov_b32_e32 v82, v0
	v_mov_b32_e32 v83, v0
	v_mov_b32_e32 v84, v0
	v_mov_b32_e32 v85, v0
	v_mov_b32_e32 v86, v0
	v_mov_b32_e32 v87, v0
	v_mov_b32_e32 v96, v0
	v_mov_b32_e32 v97, v0
	v_mov_b32_e32 v98, v0
	v_mov_b32_e32 v99, v0
	v_mov_b32_e32 v100, v0
	v_mov_b32_e32 v101, v0
	v_mov_b32_e32 v102, v0
	v_mov_b32_e32 v103, v0
	v_mov_b32_e32 v112, v0
	v_mov_b32_e32 v113, v0
	v_mov_b32_e32 v114, v0
	v_mov_b32_e32 v115, v0
	v_mov_b32_e32 v116, v0
	v_mov_b32_e32 v117, v0
	v_mov_b32_e32 v118, v0
	v_mov_b32_e32 v119, v0
	v_mov_b32_e32 v72, v0
	v_mov_b32_e32 v73, v0
	v_mov_b32_e32 v74, v0
	v_mov_b32_e32 v75, v0
	v_mov_b32_e32 v76, v0
	v_mov_b32_e32 v77, v0
	v_mov_b32_e32 v78, v0
	v_mov_b32_e32 v79, v0
	v_mov_b32_e32 v88, v0
	v_mov_b32_e32 v89, v0
	v_mov_b32_e32 v90, v0
	v_mov_b32_e32 v91, v0
	v_mov_b32_e32 v92, v0
	v_mov_b32_e32 v93, v0
	v_mov_b32_e32 v94, v0
	v_mov_b32_e32 v95, v0
	v_mov_b32_e32 v104, v0
	v_mov_b32_e32 v105, v0
	v_mov_b32_e32 v106, v0
	v_mov_b32_e32 v107, v0
	v_mov_b32_e32 v108, v0
	v_mov_b32_e32 v109, v0
	v_mov_b32_e32 v110, v0
	v_mov_b32_e32 v111, v0
	v_mov_b32_e32 v120, v0
	v_mov_b32_e32 v121, v0
	v_mov_b32_e32 v122, v0
	v_mov_b32_e32 v123, v0
	v_mov_b32_e32 v124, v0
	v_mov_b32_e32 v125, v0
	v_mov_b32_e32 v126, v0
	v_mov_b32_e32 v127, v0
	v_add_u32_e32 v159, 0x10000, v143
.LBB0_84:
	s_add_u32 s12, vcc_lo, 0xfffc0080
	s_addc_u32 s13, vcc_hi, -1
	s_add_i32 s48, 0, 0x10000
	s_cmp_eq_u32 s22, 12
	s_cselect_b32 s15, s9, s13
	s_cselect_b32 s14, s20, s12
	s_cselect_b32 s13, s37, s21
	s_cselect_b32 s12, s45, s90
	s_add_i32 s50, 0, 0x14000
	ds_read_b128 v[138:141], v159
	ds_read_b128 v[146:149], v159 offset:1024
	ds_read_b128 v[150:153], v159 offset:2048
	ds_read_b128 v[154:157], v159 offset:3072
	ds_read_b128 v[162:165], v159 offset:16384
	ds_read_b128 v[166:169], v159 offset:17408
	ds_read_b128 v[170:173], v159 offset:18432
	ds_read_b128 v[174:177], v159 offset:19456
	s_add_i32 m0, s11, 0xc000
	ds_read_b128 v[178:181], v145
	ds_read_b128 v[182:185], v145 offset:1024
	ds_read_b128 v[186:189], v145 offset:2048
	ds_read_b128 v[190:193], v145 offset:3072
	ds_read_b128 v[194:197], v145 offset:4096
	ds_read_b128 v[198:201], v145 offset:5120
	ds_read_b128 v[202:205], v145 offset:6144
	global_load_lds_dwordx4 v136, vcc
	s_add_i32 m0, s11, 0xe000
	ds_read_b128 v[206:209], v145 offset:7168
	global_load_lds_dwordx4 v134, vcc
	s_waitcnt vmcnt(8) lgkmcnt(0)
	s_barrier
	v_mfma_f32_16x16x32_bf16 v[124:127], v[138:141], v[178:181], v[124:127]
	v_mfma_f32_16x16x32_bf16 v[120:123], v[150:153], v[178:181], v[120:123]
	v_mfma_f32_16x16x32_bf16 v[108:111], v[138:141], v[186:189], v[108:111]
	v_mfma_f32_16x16x32_bf16 v[104:107], v[150:153], v[186:189], v[104:107]
	v_mfma_f32_16x16x32_bf16 v[92:95], v[138:141], v[194:197], v[92:95]
	v_mfma_f32_16x16x32_bf16 v[88:91], v[150:153], v[194:197], v[88:91]
	v_mfma_f32_16x16x32_bf16 v[76:79], v[138:141], v[202:205], v[76:79]
	v_mfma_f32_16x16x32_bf16 v[72:75], v[150:153], v[202:205], v[72:75]
	v_mfma_f32_16x16x32_bf16 v[124:127], v[146:149], v[182:185], v[124:127]
	v_mfma_f32_16x16x32_bf16 v[120:123], v[154:157], v[182:185], v[120:123]
	v_mfma_f32_16x16x32_bf16 v[108:111], v[146:149], v[190:193], v[108:111]
	v_mfma_f32_16x16x32_bf16 v[104:107], v[154:157], v[190:193], v[104:107]
	v_mfma_f32_16x16x32_bf16 v[92:95], v[146:149], v[198:201], v[92:95]
	v_mfma_f32_16x16x32_bf16 v[88:91], v[154:157], v[198:201], v[88:91]
	v_mfma_f32_16x16x32_bf16 v[76:79], v[146:149], v[206:209], v[76:79]
	v_mfma_f32_16x16x32_bf16 v[72:75], v[154:157], v[206:209], v[72:75]
	v_mfma_f32_16x16x32_bf16 v[116:119], v[162:165], v[178:181], v[116:119]
	v_mfma_f32_16x16x32_bf16 v[112:115], v[170:173], v[178:181], v[112:115]
	v_mfma_f32_16x16x32_bf16 v[100:103], v[162:165], v[186:189], v[100:103]
	v_mfma_f32_16x16x32_bf16 v[96:99], v[170:173], v[186:189], v[96:99]
	v_mfma_f32_16x16x32_bf16 v[84:87], v[162:165], v[194:197], v[84:87]
	v_mfma_f32_16x16x32_bf16 v[80:83], v[170:173], v[194:197], v[80:83]
	v_mfma_f32_16x16x32_bf16 v[68:71], v[162:165], v[202:205], v[68:71]
	v_mfma_f32_16x16x32_bf16 v[64:67], v[170:173], v[202:205], v[64:67]
	v_mfma_f32_16x16x32_bf16 v[116:119], v[166:169], v[182:185], v[116:119]
	v_mfma_f32_16x16x32_bf16 v[112:115], v[174:177], v[182:185], v[112:115]
	v_mfma_f32_16x16x32_bf16 v[100:103], v[166:169], v[190:193], v[100:103]
	v_mfma_f32_16x16x32_bf16 v[96:99], v[174:177], v[190:193], v[96:99]
	v_mfma_f32_16x16x32_bf16 v[84:87], v[166:169], v[198:201], v[84:87]
	v_mfma_f32_16x16x32_bf16 v[80:83], v[174:177], v[198:201], v[80:83]
	v_mfma_f32_16x16x32_bf16 v[68:71], v[166:169], v[206:209], v[68:71]
	v_mfma_f32_16x16x32_bf16 v[64:67], v[174:177], v[206:209], v[64:67]
	s_barrier
	s_add_i32 s48, s48, s28
	s_mov_b32 m0, s48
	ds_read_b128 v[178:181], v145 offset:16384
	ds_read_b128 v[182:185], v145 offset:17408
	ds_read_b128 v[186:189], v145 offset:18432
	ds_read_b128 v[190:193], v145 offset:19456
	global_load_lds_dwordx4 v160, s[12:13]
	s_add_i32 m0, s48, 0x2000
	s_add_u32 s48, s12, 0x40000
	s_addc_u32 s49, s13, 0
	s_add_i32 s50, s50, s28
	global_load_lds_dwordx4 v132, s[12:13]
	s_mov_b32 m0, s50
	ds_read_b128 v[206:209], v145 offset:23552
	global_load_lds_dwordx4 v160, s[48:49]
	s_add_i32 m0, s50, 0x2000
	ds_read_b128 v[202:205], v145 offset:22528
	global_load_lds_dwordx4 v132, s[48:49]
	s_mov_b32 m0, s11
	ds_read_b128 v[198:201], v145 offset:21504
	global_load_lds_dwordx4 v128, s[14:15]
	s_mov_b32 m0, s29
	ds_read_b128 v[194:197], v145 offset:20480
	global_load_lds_dwordx4 v130, s[14:15]
	s_waitcnt vmcnt(8) lgkmcnt(0)
	s_barrier
	v_mfma_f32_16x16x32_bf16 v[60:63], v[138:141], v[178:181], v[60:63]
	v_mfma_f32_16x16x32_bf16 v[56:59], v[150:153], v[178:181], v[56:59]
	v_mfma_f32_16x16x32_bf16 v[44:47], v[138:141], v[186:189], v[44:47]
	v_mfma_f32_16x16x32_bf16 v[40:43], v[150:153], v[186:189], v[40:43]
	v_mfma_f32_16x16x32_bf16 v[28:31], v[138:141], v[194:197], v[28:31]
	v_mfma_f32_16x16x32_bf16 v[24:27], v[150:153], v[194:197], v[24:27]
	v_mfma_f32_16x16x32_bf16 v[12:15], v[138:141], v[202:205], v[12:15]
	v_mfma_f32_16x16x32_bf16 v[8:11], v[150:153], v[202:205], v[8:11]
	v_mfma_f32_16x16x32_bf16 v[60:63], v[146:149], v[182:185], v[60:63]
	v_mfma_f32_16x16x32_bf16 v[56:59], v[154:157], v[182:185], v[56:59]
	v_mfma_f32_16x16x32_bf16 v[44:47], v[146:149], v[190:193], v[44:47]
	v_mfma_f32_16x16x32_bf16 v[40:43], v[154:157], v[190:193], v[40:43]
	v_mfma_f32_16x16x32_bf16 v[28:31], v[146:149], v[198:201], v[28:31]
	v_mfma_f32_16x16x32_bf16 v[24:27], v[154:157], v[198:201], v[24:27]
	v_mfma_f32_16x16x32_bf16 v[12:15], v[146:149], v[206:209], v[12:15]
	v_mfma_f32_16x16x32_bf16 v[8:11], v[154:157], v[206:209], v[8:11]
	v_mfma_f32_16x16x32_bf16 v[52:55], v[162:165], v[178:181], v[52:55]
	v_mfma_f32_16x16x32_bf16 v[48:51], v[170:173], v[178:181], v[48:51]
	v_mfma_f32_16x16x32_bf16 v[36:39], v[162:165], v[186:189], v[36:39]
	v_mfma_f32_16x16x32_bf16 v[32:35], v[170:173], v[186:189], v[32:35]
	v_mfma_f32_16x16x32_bf16 v[20:23], v[162:165], v[194:197], v[20:23]
	v_mfma_f32_16x16x32_bf16 v[16:19], v[170:173], v[194:197], v[16:19]
	v_mfma_f32_16x16x32_bf16 v[4:7], v[162:165], v[202:205], v[4:7]
	v_mfma_f32_16x16x32_bf16 v[0:3], v[170:173], v[202:205], v[0:3]
	v_mfma_f32_16x16x32_bf16 v[52:55], v[166:169], v[182:185], v[52:55]
	v_mfma_f32_16x16x32_bf16 v[48:51], v[174:177], v[182:185], v[48:51]
	v_mfma_f32_16x16x32_bf16 v[36:39], v[166:169], v[190:193], v[36:39]
	v_mfma_f32_16x16x32_bf16 v[32:35], v[174:177], v[190:193], v[32:35]
	v_mfma_f32_16x16x32_bf16 v[20:23], v[166:169], v[198:201], v[20:23]
	v_mfma_f32_16x16x32_bf16 v[16:19], v[174:177], v[198:201], v[16:19]
	v_mfma_f32_16x16x32_bf16 v[4:7], v[166:169], v[206:209], v[4:7]
	v_mfma_f32_16x16x32_bf16 v[0:3], v[174:177], v[206:209], v[0:3]
	s_barrier
	s_add_i32 s48, 0, 0x18000
	s_add_i32 s49, 0, 0x1c000
	ds_read_b128 v[138:141], v159 offset:32768
	ds_read_b128 v[146:149], v159 offset:33792
	ds_read_b128 v[150:153], v159 offset:34816
	ds_read_b128 v[154:157], v159 offset:35840
	ds_read_b128 v[162:165], v159 offset:49152
	ds_read_b128 v[166:169], v159 offset:50176
	ds_read_b128 v[170:173], v159 offset:51200
	ds_read_b128 v[174:177], v159 offset:52224
	s_mov_b64 s[100:101], s[14:15]
	s_add_u32 s14, s14, 0x40000
	s_addc_u32 s15, s15, 0
	s_mov_b32 m0, s30
	ds_read_b128 v[178:181], v145 offset:32768
	ds_read_b128 v[182:185], v145 offset:33792
	ds_read_b128 v[186:189], v145 offset:34816
	ds_read_b128 v[190:193], v145 offset:35840
	ds_read_b128 v[194:197], v145 offset:36864
	ds_read_b128 v[198:201], v145 offset:37888
	ds_read_b128 v[202:205], v145 offset:38912
	global_load_lds_dwordx4 v128, s[14:15]
	s_mov_b32 m0, s31
	ds_read_b128 v[206:209], v145 offset:39936
	global_load_lds_dwordx4 v130, s[14:15]
	s_waitcnt vmcnt(8) lgkmcnt(0)
	s_barrier
	v_mfma_f32_16x16x32_bf16 v[124:127], v[138:141], v[178:181], v[124:127]
	v_mfma_f32_16x16x32_bf16 v[120:123], v[150:153], v[178:181], v[120:123]
	v_mfma_f32_16x16x32_bf16 v[108:111], v[138:141], v[186:189], v[108:111]
	v_mfma_f32_16x16x32_bf16 v[104:107], v[150:153], v[186:189], v[104:107]
	v_mfma_f32_16x16x32_bf16 v[92:95], v[138:141], v[194:197], v[92:95]
	v_mfma_f32_16x16x32_bf16 v[88:91], v[150:153], v[194:197], v[88:91]
	v_mfma_f32_16x16x32_bf16 v[76:79], v[138:141], v[202:205], v[76:79]
	v_mfma_f32_16x16x32_bf16 v[72:75], v[150:153], v[202:205], v[72:75]
	v_mfma_f32_16x16x32_bf16 v[124:127], v[146:149], v[182:185], v[124:127]
	v_mfma_f32_16x16x32_bf16 v[120:123], v[154:157], v[182:185], v[120:123]
	v_mfma_f32_16x16x32_bf16 v[108:111], v[146:149], v[190:193], v[108:111]
	v_mfma_f32_16x16x32_bf16 v[104:107], v[154:157], v[190:193], v[104:107]
	v_mfma_f32_16x16x32_bf16 v[92:95], v[146:149], v[198:201], v[92:95]
	v_mfma_f32_16x16x32_bf16 v[88:91], v[154:157], v[198:201], v[88:91]
	v_mfma_f32_16x16x32_bf16 v[76:79], v[146:149], v[206:209], v[76:79]
	v_mfma_f32_16x16x32_bf16 v[72:75], v[154:157], v[206:209], v[72:75]
	v_mfma_f32_16x16x32_bf16 v[116:119], v[162:165], v[178:181], v[116:119]
	v_mfma_f32_16x16x32_bf16 v[112:115], v[170:173], v[178:181], v[112:115]
	v_mfma_f32_16x16x32_bf16 v[100:103], v[162:165], v[186:189], v[100:103]
	v_mfma_f32_16x16x32_bf16 v[96:99], v[170:173], v[186:189], v[96:99]
	v_mfma_f32_16x16x32_bf16 v[84:87], v[162:165], v[194:197], v[84:87]
	v_mfma_f32_16x16x32_bf16 v[80:83], v[170:173], v[194:197], v[80:83]
	v_mfma_f32_16x16x32_bf16 v[68:71], v[162:165], v[202:205], v[68:71]
	v_mfma_f32_16x16x32_bf16 v[64:67], v[170:173], v[202:205], v[64:67]
	v_mfma_f32_16x16x32_bf16 v[116:119], v[166:169], v[182:185], v[116:119]
	v_mfma_f32_16x16x32_bf16 v[112:115], v[174:177], v[182:185], v[112:115]
	v_mfma_f32_16x16x32_bf16 v[100:103], v[166:169], v[190:193], v[100:103]
	v_mfma_f32_16x16x32_bf16 v[96:99], v[174:177], v[190:193], v[96:99]
	v_mfma_f32_16x16x32_bf16 v[84:87], v[166:169], v[198:201], v[84:87]
	v_mfma_f32_16x16x32_bf16 v[80:83], v[174:177], v[198:201], v[80:83]
	v_mfma_f32_16x16x32_bf16 v[68:71], v[166:169], v[206:209], v[68:71]
	v_mfma_f32_16x16x32_bf16 v[64:67], v[174:177], v[206:209], v[64:67]
	s_barrier
	s_add_i32 s14, s48, s28
	s_add_i32 m0, s14, 0xffffff80
	ds_read_b128 v[178:181], v145 offset:49152
	ds_read_b128 v[182:185], v145 offset:50176
	ds_read_b128 v[186:189], v145 offset:51200
	global_load_lds_dwordx4 v160, s[12:13] offset:128
	s_add_i32 m0, s14, 0x1f80
	ds_read_b128 v[206:209], v145 offset:56320
	global_load_lds_dwordx4 v132, s[12:13] offset:128
	s_add_u32 s12, s12, 0x40080
	s_addc_u32 s13, s13, 0
	s_add_i32 s14, s49, s28
	s_mov_b32 m0, s14
	ds_read_b128 v[202:205], v145 offset:55296
	global_load_lds_dwordx4 v160, s[12:13]
	s_add_i32 m0, s14, 0x2000
	ds_read_b128 v[198:201], v145 offset:54272
	global_load_lds_dwordx4 v132, s[12:13]
	s_add_i32 m0, s33, 0xffffff80
	ds_read_b128 v[194:197], v145 offset:53248
	global_load_lds_dwordx4 v128, s[100:101] offset:128
	s_add_i32 m0, s34, 0xffffff80
	ds_read_b128 v[190:193], v145 offset:52224
	global_load_lds_dwordx4 v130, s[100:101] offset:128
	s_waitcnt vmcnt(8) lgkmcnt(0)
	s_barrier
	v_mfma_f32_16x16x32_bf16 v[60:63], v[138:141], v[178:181], v[60:63]
	v_mfma_f32_16x16x32_bf16 v[56:59], v[150:153], v[178:181], v[56:59]
	v_mfma_f32_16x16x32_bf16 v[44:47], v[138:141], v[186:189], v[44:47]
	v_mfma_f32_16x16x32_bf16 v[40:43], v[150:153], v[186:189], v[40:43]
	v_mfma_f32_16x16x32_bf16 v[28:31], v[138:141], v[194:197], v[28:31]
	v_mfma_f32_16x16x32_bf16 v[24:27], v[150:153], v[194:197], v[24:27]
	v_mfma_f32_16x16x32_bf16 v[12:15], v[138:141], v[202:205], v[12:15]
	v_mfma_f32_16x16x32_bf16 v[8:11], v[150:153], v[202:205], v[8:11]
	v_mfma_f32_16x16x32_bf16 v[60:63], v[146:149], v[182:185], v[60:63]
	v_mfma_f32_16x16x32_bf16 v[56:59], v[154:157], v[182:185], v[56:59]
	v_mfma_f32_16x16x32_bf16 v[44:47], v[146:149], v[190:193], v[44:47]
	v_mfma_f32_16x16x32_bf16 v[40:43], v[154:157], v[190:193], v[40:43]
	v_mfma_f32_16x16x32_bf16 v[28:31], v[146:149], v[198:201], v[28:31]
	v_mfma_f32_16x16x32_bf16 v[24:27], v[154:157], v[198:201], v[24:27]
	v_mfma_f32_16x16x32_bf16 v[12:15], v[146:149], v[206:209], v[12:15]
	v_mfma_f32_16x16x32_bf16 v[8:11], v[154:157], v[206:209], v[8:11]
	v_mfma_f32_16x16x32_bf16 v[52:55], v[162:165], v[178:181], v[52:55]
	v_mfma_f32_16x16x32_bf16 v[48:51], v[170:173], v[178:181], v[48:51]
	v_mfma_f32_16x16x32_bf16 v[36:39], v[162:165], v[186:189], v[36:39]
	v_mfma_f32_16x16x32_bf16 v[32:35], v[170:173], v[186:189], v[32:35]
	v_mfma_f32_16x16x32_bf16 v[20:23], v[162:165], v[194:197], v[20:23]
	v_mfma_f32_16x16x32_bf16 v[16:19], v[170:173], v[194:197], v[16:19]
	v_mfma_f32_16x16x32_bf16 v[4:7], v[162:165], v[202:205], v[4:7]
	v_mfma_f32_16x16x32_bf16 v[0:3], v[170:173], v[202:205], v[0:3]
	v_mfma_f32_16x16x32_bf16 v[52:55], v[166:169], v[182:185], v[52:55]
	v_mfma_f32_16x16x32_bf16 v[48:51], v[174:177], v[182:185], v[48:51]
	v_mfma_f32_16x16x32_bf16 v[36:39], v[166:169], v[190:193], v[36:39]
	v_mfma_f32_16x16x32_bf16 v[32:35], v[174:177], v[190:193], v[32:35]
	v_mfma_f32_16x16x32_bf16 v[20:23], v[166:169], v[198:201], v[20:23]
	v_mfma_f32_16x16x32_bf16 v[16:19], v[174:177], v[198:201], v[16:19]
	v_mfma_f32_16x16x32_bf16 v[4:7], v[166:169], v[206:209], v[4:7]
	v_mfma_f32_16x16x32_bf16 v[0:3], v[174:177], v[206:209], v[0:3]
	s_barrier
	s_add_i32 s22, s22, 2
	s_add_u32 s90, s90, 0x100
	s_addc_u32 s21, s21, 0
	s_add_u32 vcc_lo, vcc_lo, 0x100
	s_addc_u32 vcc_hi, vcc_hi, 0
	s_cmp_gt_u32 s22, 13
	s_cbranch_scc0 .LBB0_84
	v_lshl_add_u32 v140, s8, 8, v142
	v_lshl_or_b32 v138, s10, 8, v144
	v_lshlrev_b32_e32 v141, 11, v140
	v_lshl_add_u32 v138, v138, 1, v141
	v_lshlrev_b32_e32 v139, 3, v140
	s_mov_b64 s[8:9], s[2:3]
	global_load_dwordx4 v[146:149], v138, s[8:9]
	global_load_dwordx4 v[150:153], v138, s[8:9] offset:256
	s_add_u32 s8, s8, 0x8000
	s_addc_u32 s9, s9, 0
	global_load_dwordx4 v[154:157], v138, s[8:9]
	global_load_dwordx4 v[162:165], v138, s[8:9] offset:256
	s_add_u32 s8, s8, 0x8000
	s_addc_u32 s9, s9, 0
	global_load_dwordx4 v[166:169], v138, s[8:9]
	global_load_dwordx4 v[174:177], v138, s[8:9] offset:256
	s_add_u32 s8, s8, 0x8000
	s_addc_u32 s9, s9, 0
	global_load_dwordx4 v[178:181], v138, s[8:9]
	global_load_dwordx4 v[182:185], v138, s[8:9] offset:256
	s_add_u32 s8, s8, 0x28000
	s_addc_u32 s9, s9, 0
	global_load_dwordx4 v[186:189], v138, s[8:9]
	global_load_dwordx4 v[190:193], v138, s[8:9] offset:256
	s_add_u32 s8, s8, 0x8000
	s_addc_u32 s9, s9, 0
	global_load_dwordx4 v[194:197], v138, s[8:9]
	global_load_dwordx4 v[198:201], v138, s[8:9] offset:256
	s_add_u32 s8, s8, 0x8000
	s_addc_u32 s9, s9, 0
	global_load_dwordx4 v[202:205], v138, s[8:9]
	global_load_dwordx4 v[206:209], v138, s[8:9] offset:256
	s_add_u32 s8, s8, 0x8000
	s_addc_u32 s9, s9, 0
	global_load_dwordx4 v[210:213], v138, s[8:9]
	global_load_dwordx4 v[214:217], v138, s[8:9] offset:256
	s_and_b64 vcc, exec, s[6:7]
	s_cbranch_vccz .LBB0_87
	s_barrier

.LBB0_120:
	s_and_b32 s6, s21, 7
	s_lshl_b32 s6, s6, 8
	s_waitcnt vmcnt(0)
	s_add_i32 s10, s20, 1
	s_or_b32 s6, s8, s6
	s_add_u32 s6, s92, s6
	v_mov_b32_e32 v0, 0
	s_addc_u32 s7, s93, s9
	s_mov_b32 s11, 0
	v_mov_b32_e32 v1, v0
	v_mov_b32_e32 v2, v0
	v_mov_b32_e32 v3, v0
	v_mov_b32_e32 v4, v0
	v_mov_b32_e32 v5, v0
	v_mov_b32_e32 v6, v0
	v_mov_b32_e32 v7, v0
	v_mov_b32_e32 v8, v0
	v_mov_b32_e32 v9, v0
	v_mov_b32_e32 v10, v0
	v_mov_b32_e32 v11, v0
	v_mov_b32_e32 v12, v0
	v_mov_b32_e32 v13, v0
	v_mov_b32_e32 v14, v0
	v_mov_b32_e32 v15, v0
	v_mov_b32_e32 v16, v0
	v_mov_b32_e32 v17, v0
	v_mov_b32_e32 v18, v0
	v_mov_b32_e32 v19, v0
	v_mov_b32_e32 v20, v0
	v_mov_b32_e32 v21, v0
	v_mov_b32_e32 v22, v0
	v_mov_b32_e32 v23, v0
	v_mov_b32_e32 v24, v0
	v_mov_b32_e32 v25, v0
	v_mov_b32_e32 v26, v0
	v_mov_b32_e32 v27, v0
	v_mov_b32_e32 v28, v0
	v_mov_b32_e32 v29, v0
	v_mov_b32_e32 v30, v0
	v_mov_b32_e32 v31, v0
	v_mov_b32_e32 v32, v0
	v_mov_b32_e32 v33, v0
	v_mov_b32_e32 v34, v0
	v_mov_b32_e32 v35, v0
	v_mov_b32_e32 v36, v0
	v_mov_b32_e32 v37, v0
	v_mov_b32_e32 v38, v0
	v_mov_b32_e32 v39, v0
	v_mov_b32_e32 v40, v0
	v_mov_b32_e32 v41, v0
	v_mov_b32_e32 v42, v0
	v_mov_b32_e32 v43, v0
	v_mov_b32_e32 v44, v0
	v_mov_b32_e32 v45, v0
	v_mov_b32_e32 v46, v0
	v_mov_b32_e32 v47, v0
	v_mov_b32_e32 v48, v0
	v_mov_b32_e32 v49, v0
	v_mov_b32_e32 v50, v0
	v_mov_b32_e32 v51, v0
	v_mov_b32_e32 v52, v0
	v_mov_b32_e32 v53, v0
	v_mov_b32_e32 v54, v0
	v_mov_b32_e32 v55, v0
	v_mov_b32_e32 v56, v0
	v_mov_b32_e32 v57, v0
	v_mov_b32_e32 v58, v0
	v_mov_b32_e32 v59, v0
	v_mov_b32_e32 v60, v0
	v_mov_b32_e32 v61, v0
	v_mov_b32_e32 v62, v0
	v_mov_b32_e32 v63, v0
	v_mov_b32_e32 v64, v0
	v_mov_b32_e32 v65, v0
	v_mov_b32_e32 v66, v0
	v_mov_b32_e32 v67, v0
	v_mov_b32_e32 v68, v0
	v_mov_b32_e32 v69, v0
	v_mov_b32_e32 v70, v0
	v_mov_b32_e32 v71, v0
	v_mov_b32_e32 v72, v0
	v_mov_b32_e32 v73, v0
	v_mov_b32_e32 v74, v0
	v_mov_b32_e32 v75, v0
	v_mov_b32_e32 v76, v0
	v_mov_b32_e32 v77, v0
	v_mov_b32_e32 v78, v0
	v_mov_b32_e32 v79, v0
	v_mov_b32_e32 v80, v0
	v_mov_b32_e32 v81, v0
	v_mov_b32_e32 v82, v0
	v_mov_b32_e32 v83, v0
	v_mov_b32_e32 v84, v0
	v_mov_b32_e32 v85, v0
	v_mov_b32_e32 v86, v0
	v_mov_b32_e32 v87, v0
	v_mov_b32_e32 v88, v0
	v_mov_b32_e32 v89, v0
	v_mov_b32_e32 v90, v0
	v_mov_b32_e32 v91, v0
	v_mov_b32_e32 v92, v0
	v_mov_b32_e32 v93, v0
	v_mov_b32_e32 v94, v0
	v_mov_b32_e32 v95, v0
	v_mov_b32_e32 v96, v0
	v_mov_b32_e32 v97, v0
	v_mov_b32_e32 v98, v0
	v_mov_b32_e32 v99, v0
	v_mov_b32_e32 v100, v0
	v_mov_b32_e32 v101, v0
	v_mov_b32_e32 v102, v0
	v_mov_b32_e32 v103, v0
	v_mov_b32_e32 v104, v0
	v_mov_b32_e32 v105, v0
	v_mov_b32_e32 v106, v0
	v_mov_b32_e32 v107, v0
	v_mov_b32_e32 v108, v0
	v_mov_b32_e32 v109, v0
	v_mov_b32_e32 v110, v0
	v_mov_b32_e32 v111, v0
	v_mov_b32_e32 v112, v0
	v_mov_b32_e32 v113, v0
	v_mov_b32_e32 v114, v0
	v_mov_b32_e32 v115, v0
	v_mov_b32_e32 v116, v0
	v_mov_b32_e32 v117, v0
	v_mov_b32_e32 v118, v0
	v_mov_b32_e32 v119, v0
	v_mov_b32_e32 v120, v0
	v_mov_b32_e32 v121, v0
	v_mov_b32_e32 v122, v0
	v_mov_b32_e32 v123, v0
	v_mov_b32_e32 v124, v0
	v_mov_b32_e32 v125, v0
	v_mov_b32_e32 v126, v0
	v_mov_b32_e32 v127, v0
	v_mov_b32_e32 v174, v0
	v_mov_b32_e32 v175, v0
	s_waitcnt lgkmcnt(0)
	s_barrier
	v_mov_b32_e32 v128, v218
	v_and_b32_e32 v129, 31, v128
	v_bfe_u32 v130, v128, 5, 1
	v_bfe_u32 v131, v128, 2, 2
	v_and_b32_e32 v132, 16, v128
	v_lshlrev_b32_e32 v128, 2, v128
	v_mul_u32_u24_e32 v136, 0x110, v129
	v_lshlrev_b32_e32 v137, 4, v130
	v_and_or_b32 v128, v128, 12, v132
	v_lshl_or_b32 v129, v130, 2, v131
	v_add3_u32 v165, s28, v136, v137
	v_mul_u32_u24_e32 v162, 0x140, v129
	v_lshlrev_b32_e32 v134, 1, v128
	v_add_u32_e32 v163, v162, v134
	s_branch .LBB0_122
.LBB0_121:
	s_mul_i32 s8, s20, 0x4400
	s_mul_i32 s9, s20, 0x5000
	s_sub_i32 s8, s8, s28
	s_add_i32 s11, s11, 1
	v_add_u32_e32 v164, s8, v165
	v_add_u32_e32 v162, s9, v163
	ds_read_b128 v[128:131], v164
	ds_read_b128 v[132:135], v164 offset:8704
	ds_read_b128 v[136:139], v165
	ds_read_b128 v[176:179], v164 offset:32
	ds_read_b128 v[180:183], v164 offset:8736
	ds_read_b128 v[184:187], v165 offset:32
	s_waitcnt lgkmcnt(3)
	s_setprio 1
	v_mfma_f32_32x32x16_bf16 v[144:159], v[128:131], v[136:139], 0
	v_mfma_f32_32x32x16_bf16 v[128:143], v[132:135], v[136:139], 0
	s_setprio 0
	ds_read_b128 v[188:191], v164 offset:64
	ds_read_b128 v[192:195], v164 offset:8768
	ds_read_b128 v[196:199], v165 offset:64
	s_waitcnt lgkmcnt(3)
	s_setprio 1
	v_mfma_f32_32x32x16_bf16 v[144:159], v[176:179], v[184:187], v[144:159]
	v_mfma_f32_32x32x16_bf16 v[128:143], v[180:183], v[184:187], v[128:143]
	s_setprio 0
	ds_read_b128 v[200:203], v164 offset:96
	ds_read_b128 v[204:207], v164 offset:8800
	ds_read_b128 v[208:211], v165 offset:96
	s_waitcnt lgkmcnt(3)
	s_setprio 1
	v_mfma_f32_32x32x16_bf16 v[144:159], v[188:191], v[196:199], v[144:159]
	v_mfma_f32_32x32x16_bf16 v[128:143], v[192:195], v[196:199], v[128:143]
	s_setprio 0
	s_waitcnt lgkmcnt(0)
	s_setprio 1
	v_mfma_f32_32x32x16_bf16 v[144:159], v[200:203], v[208:211], v[144:159]
	v_mfma_f32_32x32x16_bf16 v[128:143], v[204:207], v[208:211], v[128:143]
	s_setprio 0
	ds_read_b128 v[208:211], v164 offset:128
	ds_read_b128 v[212:215], v164 offset:8832
	ds_read_b128 v[250:253], v165 offset:128
	ds_read_b128 v[166:169], v164 offset:160
	ds_read_b128 v[232:235], v164 offset:8864
	ds_read_b128 v[246:249], v165 offset:160
	ds_read_b64_tr_b16 v[224:225], v162 offset:34816
	ds_read_b64_tr_b16 v[226:227], v162 offset:37376
	ds_read_b64_tr_b16 v[228:229], v162 offset:34880
	ds_read_b64_tr_b16 v[230:231], v162 offset:37440
	s_waitcnt lgkmcnt(7)
	s_setprio 1
	v_mfma_f32_32x32x16_bf16 v[176:191], v[208:211], v[250:253], 0
	v_mfma_f32_32x32x16_bf16 v[192:207], v[212:215], v[250:253], 0
	s_setprio 0
	ds_read_b128 v[208:211], v164 offset:192
	ds_read_b128 v[212:215], v164 offset:8896
	ds_read_b128 v[250:253], v165 offset:192
	v_exp_f32_e32 v144, v144
	v_exp_f32_e32 v145, v145
	s_nop 0
	v_add_f32_e32 v170, v144, v145
	v_cvt_pk_bf16_f32 v144, v144, v145
	s_waitcnt lgkmcnt(7)
	s_setprio 1
	v_mfma_f32_32x32x16_bf16 v[176:191], v[166:169], v[246:249], v[176:191]
	v_mfma_f32_32x32x16_bf16 v[192:207], v[232:235], v[246:249], v[192:207]
	s_setprio 0
	ds_read_b128 v[166:169], v164 offset:224
	ds_read_b128 v[232:235], v164 offset:8928
	ds_read_b128 v[246:249], v165 offset:224
	v_exp_f32_e32 v146, v146
	v_exp_f32_e32 v147, v147
	s_nop 0
	v_add_f32_e32 v171, v146, v147
	v_cvt_pk_bf16_f32 v145, v146, v147
	s_waitcnt lgkmcnt(3)
	s_setprio 1
	v_mfma_f32_32x32x16_bf16 v[176:191], v[208:211], v[250:253], v[176:191]
	v_mfma_f32_32x32x16_bf16 v[192:207], v[212:215], v[250:253], v[192:207]
	s_setprio 0
	v_exp_f32_e32 v148, v148
	v_exp_f32_e32 v149, v149
	s_nop 0
	v_add_f32_e32 v172, v148, v149
	v_cvt_pk_bf16_f32 v146, v148, v149
	s_waitcnt lgkmcnt(0)
	s_setprio 1
	v_mfma_f32_32x32x16_bf16 v[176:191], v[166:169], v[246:249], v[176:191]
	v_mfma_f32_32x32x16_bf16 v[192:207], v[232:235], v[246:249], v[192:207]
	s_setprio 0
	ds_read_b64_tr_b16 v[232:233], v162 offset:34944
	ds_read_b64_tr_b16 v[234:235], v162 offset:37504
	ds_read_b64_tr_b16 v[246:247], v162 offset:35008
	ds_read_b64_tr_b16 v[248:249], v162 offset:37568
	v_exp_f32_e32 v150, v150
	v_exp_f32_e32 v151, v151
	v_add_f32_e32 v173, v150, v151
	v_cvt_pk_bf16_f32 v147, v150, v151
	v_add_f32_e32 v170, v170, v171
	v_add_f32_e32 v172, v172, v173
	v_add_f32_e32 v170, v170, v172
	v_add_f32_e32 v174, v174, v170
	s_waitcnt lgkmcnt(0)
	s_setprio 1
	v_mfma_f32_32x32x16_bf16 v[112:127], v[144:147], v[224:227], v[112:127]
	v_exp_f32_e32 v176, v176
	v_exp_f32_e32 v177, v177
	ds_read_b64_tr_b16 v[208:209], v162 offset:39936
	ds_read_b64_tr_b16 v[210:211], v162 offset:42496
	v_add_f32_e32 v170, v176, v177
	v_cvt_pk_bf16_f32 v176, v176, v177
	v_mfma_f32_32x32x16_bf16 v[96:111], v[144:147], v[228:231], v[96:111]
	v_exp_f32_e32 v178, v178
	v_exp_f32_e32 v179, v179
	s_nop 0
	v_add_f32_e32 v171, v178, v179
	v_cvt_pk_bf16_f32 v177, v178, v179
	v_mfma_f32_32x32x16_bf16 v[80:95], v[144:147], v[232:235], v[80:95]
	v_exp_f32_e32 v180, v180
	v_exp_f32_e32 v181, v181
	ds_read_b64_tr_b16 v[212:213], v162 offset:40000
	ds_read_b64_tr_b16 v[214:215], v162 offset:42560
	v_add_f32_e32 v172, v180, v181
	v_cvt_pk_bf16_f32 v178, v180, v181
	v_mfma_f32_32x32x16_bf16 v[64:79], v[144:147], v[246:249], v[64:79]
	v_exp_f32_e32 v182, v182
	v_exp_f32_e32 v183, v183
	s_nop 0
	v_add_f32_e32 v173, v182, v183
	v_cvt_pk_bf16_f32 v179, v182, v183
	s_setprio 0
	v_add_f32_e32 v170, v170, v171
	v_add_f32_e32 v172, v172, v173
	v_add_f32_e32 v170, v170, v172
	v_add_f32_e32 v175, v175, v170
	s_waitcnt lgkmcnt(4)
	s_setprio 1
	v_mfma_f32_32x32x16_bf16 v[48:63], v[176:179], v[224:227], v[48:63]
	v_exp_f32_e32 v152, v152
	v_exp_f32_e32 v153, v153
	ds_read_b64_tr_b16 v[250:251], v162 offset:40064
	ds_read_b64_tr_b16 v[252:253], v162 offset:42624
	v_add_f32_e32 v170, v152, v153
	v_cvt_pk_bf16_f32 v152, v152, v153
	v_mfma_f32_32x32x16_bf16 v[32:47], v[176:179], v[228:231], v[32:47]
	v_exp_f32_e32 v154, v154
	v_exp_f32_e32 v155, v155
	s_nop 0
	v_add_f32_e32 v171, v154, v155
	v_cvt_pk_bf16_f32 v153, v154, v155
	v_mfma_f32_32x32x16_bf16 v[16:31], v[176:179], v[232:235], v[16:31]
	v_exp_f32_e32 v156, v156
	v_exp_f32_e32 v157, v157
	ds_read_b64_tr_b16 v[166:167], v162 offset:40128
	ds_read_b64_tr_b16 v[168:169], v162 offset:42688
	v_add_f32_e32 v172, v156, v157
	v_cvt_pk_bf16_f32 v154, v156, v157
	v_mfma_f32_32x32x16_bf16 v[0:15], v[176:179], v[246:249], v[0:15]
	v_exp_f32_e32 v158, v158
	v_exp_f32_e32 v159, v159
	s_nop 0
	v_add_f32_e32 v173, v158, v159
	v_cvt_pk_bf16_f32 v155, v158, v159
	s_setprio 0
	v_add_f32_e32 v170, v170, v171
	v_add_f32_e32 v172, v172, v173
	v_add_f32_e32 v170, v170, v172
	v_add_f32_e32 v174, v174, v170
	s_waitcnt lgkmcnt(0)
	s_setprio 1
	v_mfma_f32_32x32x16_bf16 v[112:127], v[152:155], v[208:211], v[112:127]
	v_exp_f32_e32 v184, v184
	v_exp_f32_e32 v185, v185
	ds_read_b64_tr_b16 v[224:225], v162 offset:45056
	ds_read_b64_tr_b16 v[226:227], v162 offset:47616
	v_add_f32_e32 v170, v184, v185
	v_cvt_pk_bf16_f32 v184, v184, v185
	v_mfma_f32_32x32x16_bf16 v[96:111], v[152:155], v[212:215], v[96:111]
	v_exp_f32_e32 v186, v186
	v_exp_f32_e32 v187, v187
	s_nop 0
	v_add_f32_e32 v171, v186, v187
	v_cvt_pk_bf16_f32 v185, v186, v187
	v_mfma_f32_32x32x16_bf16 v[80:95], v[152:155], v[250:253], v[80:95]
	v_exp_f32_e32 v188, v188
	v_exp_f32_e32 v189, v189
	ds_read_b64_tr_b16 v[228:229], v162 offset:45120
	ds_read_b64_tr_b16 v[230:231], v162 offset:47680
	v_add_f32_e32 v172, v188, v189
	v_cvt_pk_bf16_f32 v186, v188, v189
	v_mfma_f32_32x32x16_bf16 v[64:79], v[152:155], v[166:169], v[64:79]
	v_exp_f32_e32 v190, v190
	v_exp_f32_e32 v191, v191
	s_nop 0
	v_add_f32_e32 v173, v190, v191
	v_cvt_pk_bf16_f32 v187, v190, v191
	s_setprio 0
	v_add_f32_e32 v170, v170, v171
	v_add_f32_e32 v172, v172, v173
	v_add_f32_e32 v170, v170, v172
	v_add_f32_e32 v175, v175, v170
	s_waitcnt lgkmcnt(4)
	s_setprio 1
	v_mfma_f32_32x32x16_bf16 v[48:63], v[184:187], v[208:211], v[48:63]
	v_exp_f32_e32 v128, v128
	v_exp_f32_e32 v129, v129
	ds_read_b64_tr_b16 v[232:233], v162 offset:45184
	ds_read_b64_tr_b16 v[234:235], v162 offset:47744
	v_add_f32_e32 v170, v128, v129
	v_cvt_pk_bf16_f32 v128, v128, v129
	v_mfma_f32_32x32x16_bf16 v[32:47], v[184:187], v[212:215], v[32:47]
	v_exp_f32_e32 v130, v130
	v_exp_f32_e32 v131, v131
	s_nop 0
	v_add_f32_e32 v171, v130, v131
	v_cvt_pk_bf16_f32 v129, v130, v131
	v_mfma_f32_32x32x16_bf16 v[16:31], v[184:187], v[250:253], v[16:31]
	v_exp_f32_e32 v132, v132
	v_exp_f32_e32 v133, v133
	ds_read_b64_tr_b16 v[246:247], v162 offset:45248
	ds_read_b64_tr_b16 v[248:249], v162 offset:47808
	v_add_f32_e32 v172, v132, v133
	v_cvt_pk_bf16_f32 v130, v132, v133
	v_mfma_f32_32x32x16_bf16 v[0:15], v[184:187], v[166:169], v[0:15]
	v_exp_f32_e32 v134, v134
	v_exp_f32_e32 v135, v135
	s_nop 0
	v_add_f32_e32 v173, v134, v135
	v_cvt_pk_bf16_f32 v131, v134, v135
	s_setprio 0
	v_add_f32_e32 v170, v170, v171
	v_add_f32_e32 v172, v172, v173
	v_add_f32_e32 v170, v170, v172
	v_add_f32_e32 v174, v174, v170
	s_waitcnt lgkmcnt(0)
	s_setprio 1
	v_mfma_f32_32x32x16_bf16 v[112:127], v[128:131], v[224:227], v[112:127]
	v_exp_f32_e32 v192, v192
	v_exp_f32_e32 v193, v193
	ds_read_b64_tr_b16 v[208:209], v162 offset:50176
	ds_read_b64_tr_b16 v[210:211], v162 offset:52736
	v_add_f32_e32 v170, v192, v193
	v_cvt_pk_bf16_f32 v192, v192, v193
	v_mfma_f32_32x32x16_bf16 v[96:111], v[128:131], v[228:231], v[96:111]
	v_exp_f32_e32 v194, v194
	v_exp_f32_e32 v195, v195
	s_nop 0
	v_add_f32_e32 v171, v194, v195
	v_cvt_pk_bf16_f32 v193, v194, v195
	v_mfma_f32_32x32x16_bf16 v[80:95], v[128:131], v[232:235], v[80:95]
	v_exp_f32_e32 v196, v196
	v_exp_f32_e32 v197, v197
	ds_read_b64_tr_b16 v[212:213], v162 offset:50240
	ds_read_b64_tr_b16 v[214:215], v162 offset:52800
	v_add_f32_e32 v172, v196, v197
	v_cvt_pk_bf16_f32 v194, v196, v197
	v_mfma_f32_32x32x16_bf16 v[64:79], v[128:131], v[246:249], v[64:79]
	v_exp_f32_e32 v198, v198
	v_exp_f32_e32 v199, v199
	s_nop 0
	v_add_f32_e32 v173, v198, v199
	v_cvt_pk_bf16_f32 v195, v198, v199
	s_setprio 0
	v_add_f32_e32 v170, v170, v171
	v_add_f32_e32 v172, v172, v173
	v_add_f32_e32 v170, v170, v172
	v_add_f32_e32 v175, v175, v170
	s_waitcnt lgkmcnt(4)
	s_setprio 1
	v_mfma_f32_32x32x16_bf16 v[48:63], v[192:195], v[224:227], v[48:63]
	v_exp_f32_e32 v136, v136
	v_exp_f32_e32 v137, v137
	ds_read_b64_tr_b16 v[250:251], v162 offset:50304
	ds_read_b64_tr_b16 v[252:253], v162 offset:52864
	v_add_f32_e32 v170, v136, v137
	v_cvt_pk_bf16_f32 v136, v136, v137
	v_mfma_f32_32x32x16_bf16 v[32:47], v[192:195], v[228:231], v[32:47]
	v_exp_f32_e32 v138, v138
	v_exp_f32_e32 v139, v139
	s_nop 0
	v_add_f32_e32 v171, v138, v139
	v_cvt_pk_bf16_f32 v137, v138, v139
	v_mfma_f32_32x32x16_bf16 v[16:31], v[192:195], v[232:235], v[16:31]
	v_exp_f32_e32 v140, v140
	v_exp_f32_e32 v141, v141
	ds_read_b64_tr_b16 v[166:167], v162 offset:50368
	ds_read_b64_tr_b16 v[168:169], v162 offset:52928
	v_add_f32_e32 v172, v140, v141
	v_cvt_pk_bf16_f32 v138, v140, v141
	v_mfma_f32_32x32x16_bf16 v[0:15], v[192:195], v[246:249], v[0:15]
	v_exp_f32_e32 v142, v142
	v_exp_f32_e32 v143, v143
	s_nop 0
	v_add_f32_e32 v173, v142, v143
	v_cvt_pk_bf16_f32 v139, v142, v143
	s_setprio 0
	v_add_f32_e32 v170, v170, v171
	v_add_f32_e32 v172, v172, v173
	v_add_f32_e32 v170, v170, v172
	v_add_f32_e32 v174, v174, v170
	s_waitcnt lgkmcnt(0)
	s_setprio 1
	v_mfma_f32_32x32x16_bf16 v[112:127], v[136:139], v[208:211], v[112:127]
	v_exp_f32_e32 v200, v200
	v_exp_f32_e32 v201, v201
	s_nop 0
	v_add_f32_e32 v170, v200, v201
	v_cvt_pk_bf16_f32 v200, v200, v201
	v_mfma_f32_32x32x16_bf16 v[96:111], v[136:139], v[212:215], v[96:111]
	v_exp_f32_e32 v202, v202
	v_exp_f32_e32 v203, v203
	s_nop 0
	v_add_f32_e32 v171, v202, v203
	v_cvt_pk_bf16_f32 v201, v202, v203
	v_mfma_f32_32x32x16_bf16 v[80:95], v[136:139], v[250:253], v[80:95]
	v_exp_f32_e32 v204, v204
	v_exp_f32_e32 v205, v205
	s_nop 0
	v_add_f32_e32 v172, v204, v205
	v_cvt_pk_bf16_f32 v202, v204, v205
	v_mfma_f32_32x32x16_bf16 v[64:79], v[136:139], v[166:169], v[64:79]
	v_exp_f32_e32 v206, v206
	v_exp_f32_e32 v207, v207
	s_nop 0
	v_add_f32_e32 v173, v206, v207
	v_cvt_pk_bf16_f32 v203, v206, v207
	s_setprio 0
	v_add_f32_e32 v170, v170, v171
	v_add_f32_e32 v172, v172, v173
	v_add_f32_e32 v170, v170, v172
	v_add_f32_e32 v175, v175, v170
	s_waitcnt lgkmcnt(0)
	s_setprio 1
	v_mfma_f32_32x32x16_bf16 v[48:63], v[200:203], v[208:211], v[48:63]
	v_mfma_f32_32x32x16_bf16 v[32:47], v[200:203], v[212:215], v[32:47]
	v_mfma_f32_32x32x16_bf16 v[16:31], v[200:203], v[250:253], v[16:31]
	v_mfma_f32_32x32x16_bf16 v[0:15], v[200:203], v[166:169], v[0:15]
	s_setprio 0
	s_waitcnt vmcnt(0)
	s_add_u32 s6, s6, 0x20000
	s_addc_u32 s7, s7, 0
	s_cmp_eq_u32 s10, s11
	s_barrier
	s_cbranch_scc1 .LBB0_126
.LBB0_122:
	s_and_b32 s20, s11, 1
	s_add_u32 s8, s6, 0xfc000000
	s_addc_u32 s9, s7, -1
	s_xor_b32 s21, s20, 1
	s_mul_i32 s22, s21, 0x4400
	s_add_i32 s22, s22, s37
	s_mov_b32 s48, m0
	s_mov_b32 m0, s22
	s_nop 0
	global_load_lds_dwordx4 v160, s[8:9]
	s_mov_b32 m0, s48
	s_add_i32 s48, s22, 0x2000
	s_mov_b32 s49, m0
	s_mov_b32 m0, s48
	s_nop 0
	global_load_lds_dwordx4 v238, s[8:9]
	s_mov_b32 m0, s49
	s_and_b64 vcc, exec, s[38:39]
	s_cbranch_vccnz .LBB0_124
	s_addk_i32 s22, 0x4000
	s_mov_b32 s48, m0
	s_mov_b32 m0, s22
	s_nop 0
	global_load_lds_dwordx4 v239, s[8:9]
	s_mov_b32 m0, s48

.LBB0_138:
	s_ashr_i32 s41, s40, 31
	s_lshl_b64 s[12:13], s[40:41], 19
	s_add_u32 s12, s25, s12
	s_addc_u32 s13, s26, s13
	s_and_b64 s[14:15], s[38:39], exec
	s_cselect_b32 s9, s13, s93
	s_cselect_b32 s41, s12, s92
	s_ashr_i32 s45, s44, 31
	s_lshl_b64 s[14:15], s[44:45], 19
	s_add_u32 s96, s27, s14
	s_addc_u32 s97, s28, s15
	s_and_b64 s[14:15], s[38:39], exec
	s_cselect_b32 s45, s97, s11
	s_cselect_b32 vcc_lo, s96, s10
	s_add_u32 vcc_hi, s10, 0x100
	s_addc_u32 s21, s11, 0
	s_add_u32 s10, s92, 0x40080
	v_mov_b32_e32 v0, 0
	s_addc_u32 s11, s93, 0
	s_mov_b32 s22, -2
	v_mov_b32_e32 v1, v0
	v_mov_b32_e32 v2, v0
	v_mov_b32_e32 v3, v0
	v_mov_b32_e32 v4, v0
	v_mov_b32_e32 v5, v0
	v_mov_b32_e32 v6, v0
	v_mov_b32_e32 v7, v0
	v_mov_b32_e32 v16, v0
	v_mov_b32_e32 v17, v0
	v_mov_b32_e32 v18, v0
	v_mov_b32_e32 v19, v0
	v_mov_b32_e32 v20, v0
	v_mov_b32_e32 v21, v0
	v_mov_b32_e32 v22, v0
	v_mov_b32_e32 v23, v0
	v_mov_b32_e32 v32, v0
	v_mov_b32_e32 v33, v0
	v_mov_b32_e32 v34, v0
	v_mov_b32_e32 v35, v0
	v_mov_b32_e32 v36, v0
	v_mov_b32_e32 v37, v0
	v_mov_b32_e32 v38, v0
	v_mov_b32_e32 v39, v0
	v_mov_b32_e32 v48, v0
	v_mov_b32_e32 v49, v0
	v_mov_b32_e32 v50, v0
	v_mov_b32_e32 v51, v0
	v_mov_b32_e32 v52, v0
	v_mov_b32_e32 v53, v0
	v_mov_b32_e32 v54, v0
	v_mov_b32_e32 v55, v0
	v_mov_b32_e32 v8, v0
	v_mov_b32_e32 v9, v0
	v_mov_b32_e32 v10, v0
	v_mov_b32_e32 v11, v0
	v_mov_b32_e32 v12, v0
	v_mov_b32_e32 v13, v0
	v_mov_b32_e32 v14, v0
	v_mov_b32_e32 v15, v0
	v_mov_b32_e32 v24, v0
	v_mov_b32_e32 v25, v0
	v_mov_b32_e32 v26, v0
	v_mov_b32_e32 v27, v0
	v_mov_b32_e32 v28, v0
	v_mov_b32_e32 v29, v0
	v_mov_b32_e32 v30, v0
	v_mov_b32_e32 v31, v0
	v_mov_b32_e32 v40, v0
	v_mov_b32_e32 v41, v0
	v_mov_b32_e32 v42, v0
	v_mov_b32_e32 v43, v0
	v_mov_b32_e32 v44, v0
	v_mov_b32_e32 v45, v0
	v_mov_b32_e32 v46, v0
	v_mov_b32_e32 v47, v0
	v_mov_b32_e32 v56, v0
	v_mov_b32_e32 v57, v0
	v_mov_b32_e32 v58, v0
	v_mov_b32_e32 v59, v0
	v_mov_b32_e32 v60, v0
	v_mov_b32_e32 v61, v0
	v_mov_b32_e32 v62, v0
	v_mov_b32_e32 v63, v0
	v_mov_b32_e32 v64, v0
	v_mov_b32_e32 v65, v0
	v_mov_b32_e32 v66, v0
	v_mov_b32_e32 v67, v0
	v_mov_b32_e32 v68, v0
	v_mov_b32_e32 v69, v0
	v_mov_b32_e32 v70, v0
	v_mov_b32_e32 v71, v0
	v_mov_b32_e32 v80, v0
	v_mov_b32_e32 v81, v0
	v_mov_b32_e32 v82, v0
	v_mov_b32_e32 v83, v0
	v_mov_b32_e32 v84, v0
	v_mov_b32_e32 v85, v0
	v_mov_b32_e32 v86, v0
	v_mov_b32_e32 v87, v0
	v_mov_b32_e32 v96, v0
	v_mov_b32_e32 v97, v0
	v_mov_b32_e32 v98, v0
	v_mov_b32_e32 v99, v0
	v_mov_b32_e32 v100, v0
	v_mov_b32_e32 v101, v0
	v_mov_b32_e32 v102, v0
	v_mov_b32_e32 v103, v0
	v_mov_b32_e32 v112, v0
	v_mov_b32_e32 v113, v0
	v_mov_b32_e32 v114, v0
	v_mov_b32_e32 v115, v0
	v_mov_b32_e32 v116, v0
	v_mov_b32_e32 v117, v0
	v_mov_b32_e32 v118, v0
	v_mov_b32_e32 v119, v0
	v_mov_b32_e32 v72, v0
	v_mov_b32_e32 v73, v0
	v_mov_b32_e32 v74, v0
	v_mov_b32_e32 v75, v0
	v_mov_b32_e32 v76, v0
	v_mov_b32_e32 v77, v0
	v_mov_b32_e32 v78, v0
	v_mov_b32_e32 v79, v0
	v_mov_b32_e32 v88, v0
	v_mov_b32_e32 v89, v0
	v_mov_b32_e32 v90, v0
	v_mov_b32_e32 v91, v0
	v_mov_b32_e32 v92, v0
	v_mov_b32_e32 v93, v0
	v_mov_b32_e32 v94, v0
	v_mov_b32_e32 v95, v0
	v_mov_b32_e32 v104, v0
	v_mov_b32_e32 v105, v0
	v_mov_b32_e32 v106, v0
	v_mov_b32_e32 v107, v0
	v_mov_b32_e32 v108, v0
	v_mov_b32_e32 v109, v0
	v_mov_b32_e32 v110, v0
	v_mov_b32_e32 v111, v0
	v_mov_b32_e32 v120, v0
	v_mov_b32_e32 v121, v0
	v_mov_b32_e32 v122, v0
	v_mov_b32_e32 v123, v0
	v_mov_b32_e32 v124, v0
	v_mov_b32_e32 v125, v0
	v_mov_b32_e32 v126, v0
	v_mov_b32_e32 v127, v0
	v_add_u32_e32 v162, 0x10000, v202
.LBB0_139:
	s_add_u32 s14, s10, 0xfffc0080
	s_addc_u32 s15, s11, -1
	s_add_i32 s48, 0, 0x10000
	s_cmp_eq_u32 s22, 12
	s_cselect_b32 s93, s9, s15
	s_cselect_b32 s92, s41, s14
	s_cselect_b32 s15, s45, s21
	s_cselect_b32 s14, vcc_lo, vcc_hi
	s_add_i32 s50, 0, 0x14000
	ds_read_b128 v[128:131], v162
	ds_read_b128 v[132:135], v162 offset:1024
	ds_read_b128 v[136:139], v162 offset:2048
	ds_read_b128 v[140:143], v162 offset:3072
	ds_read_b128 v[144:147], v162 offset:16384
	ds_read_b128 v[148:151], v162 offset:17408
	ds_read_b128 v[152:155], v162 offset:18432
	ds_read_b128 v[156:159], v162 offset:19456
	s_add_i32 m0, s31, 0xc000
	ds_read_b128 v[188:191], v204
	ds_read_b128 v[192:195], v204 offset:1024
	ds_read_b128 v[196:199], v204 offset:2048
	ds_read_b128 v[206:209], v204 offset:3072
	ds_read_b128 v[210:213], v204 offset:4096
	ds_read_b128 v[214:217], v204 offset:5120
	ds_read_b128 v[238:241], v204 offset:6144
	global_load_lds_dwordx4 v186, s[10:11]
	s_add_i32 m0, s31, 0xe000
	ds_read_b128 v[246:249], v204 offset:7168
	global_load_lds_dwordx4 v184, s[10:11]
	s_waitcnt vmcnt(8) lgkmcnt(0)
	s_barrier
	v_mfma_f32_16x16x32_bf16 v[124:127], v[128:131], v[188:191], v[124:127]
	v_mfma_f32_16x16x32_bf16 v[120:123], v[136:139], v[188:191], v[120:123]
	v_mfma_f32_16x16x32_bf16 v[108:111], v[128:131], v[196:199], v[108:111]
	v_mfma_f32_16x16x32_bf16 v[104:107], v[136:139], v[196:199], v[104:107]
	v_mfma_f32_16x16x32_bf16 v[92:95], v[128:131], v[210:213], v[92:95]
	v_mfma_f32_16x16x32_bf16 v[88:91], v[136:139], v[210:213], v[88:91]
	v_mfma_f32_16x16x32_bf16 v[76:79], v[128:131], v[238:241], v[76:79]
	v_mfma_f32_16x16x32_bf16 v[72:75], v[136:139], v[238:241], v[72:75]
	v_mfma_f32_16x16x32_bf16 v[124:127], v[132:135], v[192:195], v[124:127]
	v_mfma_f32_16x16x32_bf16 v[120:123], v[140:143], v[192:195], v[120:123]
	v_mfma_f32_16x16x32_bf16 v[108:111], v[132:135], v[206:209], v[108:111]
	v_mfma_f32_16x16x32_bf16 v[104:107], v[140:143], v[206:209], v[104:107]
	v_mfma_f32_16x16x32_bf16 v[92:95], v[132:135], v[214:217], v[92:95]
	v_mfma_f32_16x16x32_bf16 v[88:91], v[140:143], v[214:217], v[88:91]
	v_mfma_f32_16x16x32_bf16 v[76:79], v[132:135], v[246:249], v[76:79]
	v_mfma_f32_16x16x32_bf16 v[72:75], v[140:143], v[246:249], v[72:75]
	v_mfma_f32_16x16x32_bf16 v[116:119], v[144:147], v[188:191], v[116:119]
	v_mfma_f32_16x16x32_bf16 v[112:115], v[152:155], v[188:191], v[112:115]
	v_mfma_f32_16x16x32_bf16 v[100:103], v[144:147], v[196:199], v[100:103]
	v_mfma_f32_16x16x32_bf16 v[96:99], v[152:155], v[196:199], v[96:99]
	v_mfma_f32_16x16x32_bf16 v[84:87], v[144:147], v[210:213], v[84:87]
	v_mfma_f32_16x16x32_bf16 v[80:83], v[152:155], v[210:213], v[80:83]
	v_mfma_f32_16x16x32_bf16 v[68:71], v[144:147], v[238:241], v[68:71]
	v_mfma_f32_16x16x32_bf16 v[64:67], v[152:155], v[238:241], v[64:67]
	v_mfma_f32_16x16x32_bf16 v[116:119], v[148:151], v[192:195], v[116:119]
	v_mfma_f32_16x16x32_bf16 v[112:115], v[156:159], v[192:195], v[112:115]
	v_mfma_f32_16x16x32_bf16 v[100:103], v[148:151], v[206:209], v[100:103]
	v_mfma_f32_16x16x32_bf16 v[96:99], v[156:159], v[206:209], v[96:99]
	v_mfma_f32_16x16x32_bf16 v[84:87], v[148:151], v[214:217], v[84:87]
	v_mfma_f32_16x16x32_bf16 v[80:83], v[156:159], v[214:217], v[80:83]
	v_mfma_f32_16x16x32_bf16 v[68:71], v[148:151], v[246:249], v[68:71]
	v_mfma_f32_16x16x32_bf16 v[64:67], v[156:159], v[246:249], v[64:67]
	s_barrier
	s_add_i32 s48, s48, s29
	s_mov_b32 m0, s48
	ds_read_b128 v[188:191], v204 offset:16384
	ds_read_b128 v[192:195], v204 offset:17408
	ds_read_b128 v[196:199], v204 offset:18432
	ds_read_b128 v[206:209], v204 offset:19456
	global_load_lds_dwordx4 v178, s[14:15]
	s_add_i32 m0, s48, 0x2000
	s_add_u32 s48, s14, 0x40000
	s_addc_u32 s49, s15, 0
	s_add_i32 s50, s50, s29
	global_load_lds_dwordx4 v174, s[14:15]
	s_mov_b32 m0, s50
	ds_read_b128 v[246:249], v204 offset:23552
	global_load_lds_dwordx4 v178, s[48:49]
	s_add_i32 m0, s50, 0x2000
	ds_read_b128 v[238:241], v204 offset:22528
	global_load_lds_dwordx4 v174, s[48:49]
	s_mov_b32 m0, s31
	ds_read_b128 v[214:217], v204 offset:21504
	global_load_lds_dwordx4 v180, s[92:93]
	s_mov_b32 m0, s34
	ds_read_b128 v[210:213], v204 offset:20480
	global_load_lds_dwordx4 v176, s[92:93]
	s_waitcnt vmcnt(8) lgkmcnt(0)
	s_barrier
	v_mfma_f32_16x16x32_bf16 v[60:63], v[128:131], v[188:191], v[60:63]
	v_mfma_f32_16x16x32_bf16 v[56:59], v[136:139], v[188:191], v[56:59]
	v_mfma_f32_16x16x32_bf16 v[44:47], v[128:131], v[196:199], v[44:47]
	v_mfma_f32_16x16x32_bf16 v[40:43], v[136:139], v[196:199], v[40:43]
	v_mfma_f32_16x16x32_bf16 v[28:31], v[128:131], v[210:213], v[28:31]
	v_mfma_f32_16x16x32_bf16 v[24:27], v[136:139], v[210:213], v[24:27]
	v_mfma_f32_16x16x32_bf16 v[12:15], v[128:131], v[238:241], v[12:15]
	v_mfma_f32_16x16x32_bf16 v[8:11], v[136:139], v[238:241], v[8:11]
	v_mfma_f32_16x16x32_bf16 v[60:63], v[132:135], v[192:195], v[60:63]
	v_mfma_f32_16x16x32_bf16 v[56:59], v[140:143], v[192:195], v[56:59]
	v_mfma_f32_16x16x32_bf16 v[44:47], v[132:135], v[206:209], v[44:47]
	v_mfma_f32_16x16x32_bf16 v[40:43], v[140:143], v[206:209], v[40:43]
	v_mfma_f32_16x16x32_bf16 v[28:31], v[132:135], v[214:217], v[28:31]
	v_mfma_f32_16x16x32_bf16 v[24:27], v[140:143], v[214:217], v[24:27]
	v_mfma_f32_16x16x32_bf16 v[12:15], v[132:135], v[246:249], v[12:15]
	v_mfma_f32_16x16x32_bf16 v[8:11], v[140:143], v[246:249], v[8:11]
	v_mfma_f32_16x16x32_bf16 v[52:55], v[144:147], v[188:191], v[52:55]
	v_mfma_f32_16x16x32_bf16 v[48:51], v[152:155], v[188:191], v[48:51]
	v_mfma_f32_16x16x32_bf16 v[36:39], v[144:147], v[196:199], v[36:39]
	v_mfma_f32_16x16x32_bf16 v[32:35], v[152:155], v[196:199], v[32:35]
	v_mfma_f32_16x16x32_bf16 v[20:23], v[144:147], v[210:213], v[20:23]
	v_mfma_f32_16x16x32_bf16 v[16:19], v[152:155], v[210:213], v[16:19]
	v_mfma_f32_16x16x32_bf16 v[4:7], v[144:147], v[238:241], v[4:7]
	v_mfma_f32_16x16x32_bf16 v[0:3], v[152:155], v[238:241], v[0:3]
	v_mfma_f32_16x16x32_bf16 v[52:55], v[148:151], v[192:195], v[52:55]
	v_mfma_f32_16x16x32_bf16 v[48:51], v[156:159], v[192:195], v[48:51]
	v_mfma_f32_16x16x32_bf16 v[36:39], v[148:151], v[206:209], v[36:39]
	v_mfma_f32_16x16x32_bf16 v[32:35], v[156:159], v[206:209], v[32:35]
	v_mfma_f32_16x16x32_bf16 v[20:23], v[148:151], v[214:217], v[20:23]
	v_mfma_f32_16x16x32_bf16 v[16:19], v[156:159], v[214:217], v[16:19]
	v_mfma_f32_16x16x32_bf16 v[4:7], v[148:151], v[246:249], v[4:7]
	v_mfma_f32_16x16x32_bf16 v[0:3], v[156:159], v[246:249], v[0:3]
	s_barrier
	s_add_i32 s50, 0, 0x18000
	s_add_i32 s51, 0, 0x1c000
	ds_read_b128 v[128:131], v162 offset:32768
	ds_read_b128 v[132:135], v162 offset:33792
	ds_read_b128 v[136:139], v162 offset:34816
	ds_read_b128 v[140:143], v162 offset:35840
	ds_read_b128 v[144:147], v162 offset:49152
	ds_read_b128 v[148:151], v162 offset:50176
	ds_read_b128 v[152:155], v162 offset:51200
	ds_read_b128 v[156:159], v162 offset:52224
	s_add_u32 s48, s92, 0x40000
	s_addc_u32 s49, s93, 0
	s_mov_b32 m0, s35
	ds_read_b128 v[188:191], v204 offset:32768
	ds_read_b128 v[192:195], v204 offset:33792
	ds_read_b128 v[196:199], v204 offset:34816
	ds_read_b128 v[206:209], v204 offset:35840
	ds_read_b128 v[210:213], v204 offset:36864
	ds_read_b128 v[214:217], v204 offset:37888
	ds_read_b128 v[238:241], v204 offset:38912
	global_load_lds_dwordx4 v180, s[48:49]
	s_mov_b32 m0, s90
	ds_read_b128 v[246:249], v204 offset:39936
	global_load_lds_dwordx4 v176, s[48:49]
	s_waitcnt vmcnt(8) lgkmcnt(0)
	s_barrier
	v_mfma_f32_16x16x32_bf16 v[124:127], v[128:131], v[188:191], v[124:127]
	v_mfma_f32_16x16x32_bf16 v[120:123], v[136:139], v[188:191], v[120:123]
	v_mfma_f32_16x16x32_bf16 v[108:111], v[128:131], v[196:199], v[108:111]
	v_mfma_f32_16x16x32_bf16 v[104:107], v[136:139], v[196:199], v[104:107]
	v_mfma_f32_16x16x32_bf16 v[92:95], v[128:131], v[210:213], v[92:95]
	v_mfma_f32_16x16x32_bf16 v[88:91], v[136:139], v[210:213], v[88:91]
	v_mfma_f32_16x16x32_bf16 v[76:79], v[128:131], v[238:241], v[76:79]
	v_mfma_f32_16x16x32_bf16 v[72:75], v[136:139], v[238:241], v[72:75]
	v_mfma_f32_16x16x32_bf16 v[124:127], v[132:135], v[192:195], v[124:127]
	v_mfma_f32_16x16x32_bf16 v[120:123], v[140:143], v[192:195], v[120:123]
	v_mfma_f32_16x16x32_bf16 v[108:111], v[132:135], v[206:209], v[108:111]
	v_mfma_f32_16x16x32_bf16 v[104:107], v[140:143], v[206:209], v[104:107]
	v_mfma_f32_16x16x32_bf16 v[92:95], v[132:135], v[214:217], v[92:95]
	v_mfma_f32_16x16x32_bf16 v[88:91], v[140:143], v[214:217], v[88:91]
	v_mfma_f32_16x16x32_bf16 v[76:79], v[132:135], v[246:249], v[76:79]
	v_mfma_f32_16x16x32_bf16 v[72:75], v[140:143], v[246:249], v[72:75]
	v_mfma_f32_16x16x32_bf16 v[116:119], v[144:147], v[188:191], v[116:119]
	v_mfma_f32_16x16x32_bf16 v[112:115], v[152:155], v[188:191], v[112:115]
	v_mfma_f32_16x16x32_bf16 v[100:103], v[144:147], v[196:199], v[100:103]
	v_mfma_f32_16x16x32_bf16 v[96:99], v[152:155], v[196:199], v[96:99]
	v_mfma_f32_16x16x32_bf16 v[84:87], v[144:147], v[210:213], v[84:87]
	v_mfma_f32_16x16x32_bf16 v[80:83], v[152:155], v[210:213], v[80:83]
	v_mfma_f32_16x16x32_bf16 v[68:71], v[144:147], v[238:241], v[68:71]
	v_mfma_f32_16x16x32_bf16 v[64:67], v[152:155], v[238:241], v[64:67]
	v_mfma_f32_16x16x32_bf16 v[116:119], v[148:151], v[192:195], v[116:119]
	v_mfma_f32_16x16x32_bf16 v[112:115], v[156:159], v[192:195], v[112:115]
	v_mfma_f32_16x16x32_bf16 v[100:103], v[148:151], v[206:209], v[100:103]
	v_mfma_f32_16x16x32_bf16 v[96:99], v[156:159], v[206:209], v[96:99]
	v_mfma_f32_16x16x32_bf16 v[84:87], v[148:151], v[214:217], v[84:87]
	v_mfma_f32_16x16x32_bf16 v[80:83], v[156:159], v[214:217], v[80:83]
	v_mfma_f32_16x16x32_bf16 v[68:71], v[148:151], v[246:249], v[68:71]
	v_mfma_f32_16x16x32_bf16 v[64:67], v[156:159], v[246:249], v[64:67]
	s_barrier
	s_add_i32 s48, s50, s29
	s_add_i32 m0, s48, 0xffffff80
	ds_read_b128 v[188:191], v204 offset:49152
	ds_read_b128 v[192:195], v204 offset:50176
	ds_read_b128 v[196:199], v204 offset:51200
	global_load_lds_dwordx4 v178, s[14:15] offset:128
	s_add_i32 m0, s48, 0x1f80
	ds_read_b128 v[246:249], v204 offset:56320
	global_load_lds_dwordx4 v174, s[14:15] offset:128
	s_add_u32 s14, s14, 0x40080
	s_addc_u32 s15, s15, 0
	s_add_i32 s48, s51, s29
	s_mov_b32 m0, s48
	ds_read_b128 v[238:241], v204 offset:55296
	global_load_lds_dwordx4 v178, s[14:15]
	s_add_i32 m0, s48, 0x2000
	ds_read_b128 v[214:217], v204 offset:54272
	global_load_lds_dwordx4 v174, s[14:15]
	s_add_i32 m0, s19, 0xffffff80
	ds_read_b128 v[210:213], v204 offset:53248
	global_load_lds_dwordx4 v180, s[92:93] offset:128
	s_add_i32 m0, s33, 0xffffff80
	ds_read_b128 v[206:209], v204 offset:52224
	global_load_lds_dwordx4 v176, s[92:93] offset:128
	s_waitcnt vmcnt(8) lgkmcnt(0)
	s_barrier
	v_mfma_f32_16x16x32_bf16 v[60:63], v[128:131], v[188:191], v[60:63]
	v_mfma_f32_16x16x32_bf16 v[56:59], v[136:139], v[188:191], v[56:59]
	v_mfma_f32_16x16x32_bf16 v[44:47], v[128:131], v[196:199], v[44:47]
	v_mfma_f32_16x16x32_bf16 v[40:43], v[136:139], v[196:199], v[40:43]
	v_mfma_f32_16x16x32_bf16 v[28:31], v[128:131], v[210:213], v[28:31]
	v_mfma_f32_16x16x32_bf16 v[24:27], v[136:139], v[210:213], v[24:27]
	v_mfma_f32_16x16x32_bf16 v[12:15], v[128:131], v[238:241], v[12:15]
	v_mfma_f32_16x16x32_bf16 v[8:11], v[136:139], v[238:241], v[8:11]
	v_mfma_f32_16x16x32_bf16 v[60:63], v[132:135], v[192:195], v[60:63]
	v_mfma_f32_16x16x32_bf16 v[56:59], v[140:143], v[192:195], v[56:59]
	v_mfma_f32_16x16x32_bf16 v[44:47], v[132:135], v[206:209], v[44:47]
	v_mfma_f32_16x16x32_bf16 v[40:43], v[140:143], v[206:209], v[40:43]
	v_mfma_f32_16x16x32_bf16 v[28:31], v[132:135], v[214:217], v[28:31]
	v_mfma_f32_16x16x32_bf16 v[24:27], v[140:143], v[214:217], v[24:27]
	v_mfma_f32_16x16x32_bf16 v[12:15], v[132:135], v[246:249], v[12:15]
	v_mfma_f32_16x16x32_bf16 v[8:11], v[140:143], v[246:249], v[8:11]
	v_mfma_f32_16x16x32_bf16 v[52:55], v[144:147], v[188:191], v[52:55]
	v_mfma_f32_16x16x32_bf16 v[48:51], v[152:155], v[188:191], v[48:51]
	v_mfma_f32_16x16x32_bf16 v[36:39], v[144:147], v[196:199], v[36:39]
	v_mfma_f32_16x16x32_bf16 v[32:35], v[152:155], v[196:199], v[32:35]
	v_mfma_f32_16x16x32_bf16 v[20:23], v[144:147], v[210:213], v[20:23]
	v_mfma_f32_16x16x32_bf16 v[16:19], v[152:155], v[210:213], v[16:19]
	v_mfma_f32_16x16x32_bf16 v[4:7], v[144:147], v[238:241], v[4:7]
	v_mfma_f32_16x16x32_bf16 v[0:3], v[152:155], v[238:241], v[0:3]
	v_mfma_f32_16x16x32_bf16 v[52:55], v[148:151], v[192:195], v[52:55]
	v_mfma_f32_16x16x32_bf16 v[48:51], v[156:159], v[192:195], v[48:51]
	v_mfma_f32_16x16x32_bf16 v[36:39], v[148:151], v[206:209], v[36:39]
	v_mfma_f32_16x16x32_bf16 v[32:35], v[156:159], v[206:209], v[32:35]
	v_mfma_f32_16x16x32_bf16 v[20:23], v[148:151], v[214:217], v[20:23]
	v_mfma_f32_16x16x32_bf16 v[16:19], v[156:159], v[214:217], v[16:19]
	v_mfma_f32_16x16x32_bf16 v[4:7], v[148:151], v[246:249], v[4:7]
	v_mfma_f32_16x16x32_bf16 v[0:3], v[156:159], v[246:249], v[0:3]
	s_barrier
	s_add_i32 s22, s22, 2
	s_add_u32 vcc_hi, vcc_hi, 0x100
	s_addc_u32 s21, s21, 0
	s_add_u32 s10, s10, 0x100
	s_addc_u32 s11, s11, 0
	s_cmp_gt_u32 s22, 13
	s_cbranch_scc0 .LBB0_139
	s_and_b64 vcc, exec, s[36:37]
	s_cbranch_vccz .LBB0_142
	s_barrier

.LBB0_177:
	s_add_u32 s21, s10, 0x100
	v_mov_b32_e32 v0, 0
	s_addc_u32 s96, s11, 0
	s_mov_b32 s22, -2
	v_mov_b32_e32 v1, v0
	v_mov_b32_e32 v2, v0
	v_mov_b32_e32 v3, v0
	v_mov_b32_e32 v4, v0
	v_mov_b32_e32 v5, v0
	v_mov_b32_e32 v6, v0
	v_mov_b32_e32 v7, v0
	v_mov_b32_e32 v16, v0
	v_mov_b32_e32 v17, v0
	v_mov_b32_e32 v18, v0
	v_mov_b32_e32 v19, v0
	v_mov_b32_e32 v20, v0
	v_mov_b32_e32 v21, v0
	v_mov_b32_e32 v22, v0
	v_mov_b32_e32 v23, v0
	v_mov_b32_e32 v32, v0
	v_mov_b32_e32 v33, v0
	v_mov_b32_e32 v34, v0
	v_mov_b32_e32 v35, v0
	v_mov_b32_e32 v36, v0
	v_mov_b32_e32 v37, v0
	v_mov_b32_e32 v38, v0
	v_mov_b32_e32 v39, v0
	v_mov_b32_e32 v48, v0
	v_mov_b32_e32 v49, v0
	v_mov_b32_e32 v50, v0
	v_mov_b32_e32 v51, v0
	v_mov_b32_e32 v52, v0
	v_mov_b32_e32 v53, v0
	v_mov_b32_e32 v54, v0
	v_mov_b32_e32 v55, v0
	v_mov_b32_e32 v8, v0
	v_mov_b32_e32 v9, v0
	v_mov_b32_e32 v10, v0
	v_mov_b32_e32 v11, v0
	v_mov_b32_e32 v12, v0
	v_mov_b32_e32 v13, v0
	v_mov_b32_e32 v14, v0
	v_mov_b32_e32 v15, v0
	v_mov_b32_e32 v24, v0
	v_mov_b32_e32 v25, v0
	v_mov_b32_e32 v26, v0
	v_mov_b32_e32 v27, v0
	v_mov_b32_e32 v28, v0
	v_mov_b32_e32 v29, v0
	v_mov_b32_e32 v30, v0
	v_mov_b32_e32 v31, v0
	v_mov_b32_e32 v40, v0
	v_mov_b32_e32 v41, v0
	v_mov_b32_e32 v42, v0
	v_mov_b32_e32 v43, v0
	v_mov_b32_e32 v44, v0
	v_mov_b32_e32 v45, v0
	v_mov_b32_e32 v46, v0
	v_mov_b32_e32 v47, v0
	v_mov_b32_e32 v56, v0
	v_mov_b32_e32 v57, v0
	v_mov_b32_e32 v58, v0
	v_mov_b32_e32 v59, v0
	v_mov_b32_e32 v60, v0
	v_mov_b32_e32 v61, v0
	v_mov_b32_e32 v62, v0
	v_mov_b32_e32 v63, v0
	v_mov_b32_e32 v64, v0
	v_mov_b32_e32 v65, v0
	v_mov_b32_e32 v66, v0
	v_mov_b32_e32 v67, v0
	v_mov_b32_e32 v68, v0
	v_mov_b32_e32 v69, v0
	v_mov_b32_e32 v70, v0
	v_mov_b32_e32 v71, v0
	v_mov_b32_e32 v80, v0
	v_mov_b32_e32 v81, v0
	v_mov_b32_e32 v82, v0
	v_mov_b32_e32 v83, v0
	v_mov_b32_e32 v84, v0
	v_mov_b32_e32 v85, v0
	v_mov_b32_e32 v86, v0
	v_mov_b32_e32 v87, v0
	v_mov_b32_e32 v96, v0
	v_mov_b32_e32 v97, v0
	v_mov_b32_e32 v98, v0
	v_mov_b32_e32 v99, v0
	v_mov_b32_e32 v100, v0
	v_mov_b32_e32 v101, v0
	v_mov_b32_e32 v102, v0
	v_mov_b32_e32 v103, v0
	v_mov_b32_e32 v112, v0
	v_mov_b32_e32 v113, v0
	v_mov_b32_e32 v114, v0
	v_mov_b32_e32 v115, v0
	v_mov_b32_e32 v116, v0
	v_mov_b32_e32 v117, v0
	v_mov_b32_e32 v118, v0
	v_mov_b32_e32 v119, v0
	v_mov_b32_e32 v72, v0
	v_mov_b32_e32 v73, v0
	v_mov_b32_e32 v74, v0
	v_mov_b32_e32 v75, v0
	v_mov_b32_e32 v76, v0
	v_mov_b32_e32 v77, v0
	v_mov_b32_e32 v78, v0
	v_mov_b32_e32 v79, v0
	v_mov_b32_e32 v88, v0
	v_mov_b32_e32 v89, v0
	v_mov_b32_e32 v90, v0
	v_mov_b32_e32 v91, v0
	v_mov_b32_e32 v92, v0
	v_mov_b32_e32 v93, v0
	v_mov_b32_e32 v94, v0
	v_mov_b32_e32 v95, v0
	v_mov_b32_e32 v104, v0
	v_mov_b32_e32 v105, v0
	v_mov_b32_e32 v106, v0
	v_mov_b32_e32 v107, v0
	v_mov_b32_e32 v108, v0
	v_mov_b32_e32 v109, v0
	v_mov_b32_e32 v110, v0
	v_mov_b32_e32 v111, v0
	v_mov_b32_e32 v120, v0
	v_mov_b32_e32 v121, v0
	v_mov_b32_e32 v122, v0
	v_mov_b32_e32 v123, v0
	v_mov_b32_e32 v124, v0
	v_mov_b32_e32 v125, v0
	v_mov_b32_e32 v126, v0
	v_mov_b32_e32 v127, v0
	v_add_u32_e32 v159, 0x10000, v143
.LBB0_178:
	s_add_u32 s10, s8, 0x100
	s_addc_u32 s11, s9, 0
	s_add_i32 s48, 0, 0x10000
	s_cmp_eq_u32 s22, 40
	s_cselect_b32 s15, s1, s11
	s_cselect_b32 s14, s0, s10
	s_cselect_b32 s13, s45, s96
	s_cselect_b32 s12, s44, s21
	s_add_i32 s49, 0, 0x14000
	ds_read_b128 v[138:141], v159
	ds_read_b128 v[146:149], v159 offset:1024
	ds_read_b128 v[150:153], v159 offset:2048
	ds_read_b128 v[154:157], v159 offset:3072
	ds_read_b128 v[174:177], v159 offset:16384
	ds_read_b128 v[178:181], v159 offset:17408
	ds_read_b128 v[182:185], v159 offset:18432
	ds_read_b128 v[186:189], v159 offset:19456
	s_add_i32 m0, s29, 0xc000
	ds_read_b128 v[190:193], v145
	ds_read_b128 v[194:197], v145 offset:1024
	ds_read_b128 v[198:201], v145 offset:2048
	ds_read_b128 v[202:205], v145 offset:3072
	ds_read_b128 v[206:209], v145 offset:4096
	ds_read_b128 v[210:213], v145 offset:5120
	ds_read_b128 v[214:217], v145 offset:6144
	global_load_lds_dwordx4 v136, s[8:9]
	s_add_i32 m0, s29, 0xe000
	ds_read_b128 v[238:241], v145 offset:7168
	global_load_lds_dwordx4 v134, s[8:9]
	s_waitcnt vmcnt(8) lgkmcnt(0)
	s_barrier
	v_mfma_f32_16x16x32_bf16 v[124:127], v[138:141], v[190:193], v[124:127]
	v_mfma_f32_16x16x32_bf16 v[120:123], v[150:153], v[190:193], v[120:123]
	v_mfma_f32_16x16x32_bf16 v[108:111], v[138:141], v[198:201], v[108:111]
	v_mfma_f32_16x16x32_bf16 v[104:107], v[150:153], v[198:201], v[104:107]
	v_mfma_f32_16x16x32_bf16 v[92:95], v[138:141], v[206:209], v[92:95]
	v_mfma_f32_16x16x32_bf16 v[88:91], v[150:153], v[206:209], v[88:91]
	v_mfma_f32_16x16x32_bf16 v[76:79], v[138:141], v[214:217], v[76:79]
	v_mfma_f32_16x16x32_bf16 v[72:75], v[150:153], v[214:217], v[72:75]
	v_mfma_f32_16x16x32_bf16 v[124:127], v[146:149], v[194:197], v[124:127]
	v_mfma_f32_16x16x32_bf16 v[120:123], v[154:157], v[194:197], v[120:123]
	v_mfma_f32_16x16x32_bf16 v[108:111], v[146:149], v[202:205], v[108:111]
	v_mfma_f32_16x16x32_bf16 v[104:107], v[154:157], v[202:205], v[104:107]
	v_mfma_f32_16x16x32_bf16 v[92:95], v[146:149], v[210:213], v[92:95]
	v_mfma_f32_16x16x32_bf16 v[88:91], v[154:157], v[210:213], v[88:91]
	v_mfma_f32_16x16x32_bf16 v[76:79], v[146:149], v[238:241], v[76:79]
	v_mfma_f32_16x16x32_bf16 v[72:75], v[154:157], v[238:241], v[72:75]
	v_mfma_f32_16x16x32_bf16 v[116:119], v[174:177], v[190:193], v[116:119]
	v_mfma_f32_16x16x32_bf16 v[112:115], v[182:185], v[190:193], v[112:115]
	v_mfma_f32_16x16x32_bf16 v[100:103], v[174:177], v[198:201], v[100:103]
	v_mfma_f32_16x16x32_bf16 v[96:99], v[182:185], v[198:201], v[96:99]
	v_mfma_f32_16x16x32_bf16 v[84:87], v[174:177], v[206:209], v[84:87]
	v_mfma_f32_16x16x32_bf16 v[80:83], v[182:185], v[206:209], v[80:83]
	v_mfma_f32_16x16x32_bf16 v[68:71], v[174:177], v[214:217], v[68:71]
	v_mfma_f32_16x16x32_bf16 v[64:67], v[182:185], v[214:217], v[64:67]
	v_mfma_f32_16x16x32_bf16 v[116:119], v[178:181], v[194:197], v[116:119]
	v_mfma_f32_16x16x32_bf16 v[112:115], v[186:189], v[194:197], v[112:115]
	v_mfma_f32_16x16x32_bf16 v[100:103], v[178:181], v[202:205], v[100:103]
	v_mfma_f32_16x16x32_bf16 v[96:99], v[186:189], v[202:205], v[96:99]
	v_mfma_f32_16x16x32_bf16 v[84:87], v[178:181], v[210:213], v[84:87]
	v_mfma_f32_16x16x32_bf16 v[80:83], v[186:189], v[210:213], v[80:83]
	v_mfma_f32_16x16x32_bf16 v[68:71], v[178:181], v[238:241], v[68:71]
	v_mfma_f32_16x16x32_bf16 v[64:67], v[186:189], v[238:241], v[64:67]
	s_barrier
	s_add_i32 s8, s48, s28
	s_mov_b32 m0, s8
	ds_read_b128 v[190:193], v145 offset:16384
	ds_read_b128 v[194:197], v145 offset:17408
	ds_read_b128 v[198:201], v145 offset:18432
	ds_read_b128 v[202:205], v145 offset:19456
	global_load_lds_dwordx4 v160, s[12:13]
	s_add_i32 m0, s8, 0x2000
	s_add_u32 s8, s12, 0xb0000
	s_addc_u32 s9, s13, 0
	s_add_i32 s48, s49, s28
	global_load_lds_dwordx4 v132, s[12:13]
	s_mov_b32 m0, s48
	ds_read_b128 v[238:241], v145 offset:23552
	global_load_lds_dwordx4 v160, s[8:9]
	s_add_i32 m0, s48, 0x2000
	ds_read_b128 v[214:217], v145 offset:22528
	global_load_lds_dwordx4 v132, s[8:9]
	s_mov_b32 m0, s29
	ds_read_b128 v[210:213], v145 offset:21504
	global_load_lds_dwordx4 v128, s[14:15]
	s_mov_b32 m0, s30
	ds_read_b128 v[206:209], v145 offset:20480
	global_load_lds_dwordx4 v130, s[14:15]
	s_waitcnt vmcnt(8) lgkmcnt(0)
	s_barrier
	v_mfma_f32_16x16x32_bf16 v[60:63], v[138:141], v[190:193], v[60:63]
	v_mfma_f32_16x16x32_bf16 v[56:59], v[150:153], v[190:193], v[56:59]
	v_mfma_f32_16x16x32_bf16 v[44:47], v[138:141], v[198:201], v[44:47]
	v_mfma_f32_16x16x32_bf16 v[40:43], v[150:153], v[198:201], v[40:43]
	v_mfma_f32_16x16x32_bf16 v[28:31], v[138:141], v[206:209], v[28:31]
	v_mfma_f32_16x16x32_bf16 v[24:27], v[150:153], v[206:209], v[24:27]
	v_mfma_f32_16x16x32_bf16 v[12:15], v[138:141], v[214:217], v[12:15]
	v_mfma_f32_16x16x32_bf16 v[8:11], v[150:153], v[214:217], v[8:11]
	v_mfma_f32_16x16x32_bf16 v[60:63], v[146:149], v[194:197], v[60:63]
	v_mfma_f32_16x16x32_bf16 v[56:59], v[154:157], v[194:197], v[56:59]
	v_mfma_f32_16x16x32_bf16 v[44:47], v[146:149], v[202:205], v[44:47]
	v_mfma_f32_16x16x32_bf16 v[40:43], v[154:157], v[202:205], v[40:43]
	v_mfma_f32_16x16x32_bf16 v[28:31], v[146:149], v[210:213], v[28:31]
	v_mfma_f32_16x16x32_bf16 v[24:27], v[154:157], v[210:213], v[24:27]
	v_mfma_f32_16x16x32_bf16 v[12:15], v[146:149], v[238:241], v[12:15]
	v_mfma_f32_16x16x32_bf16 v[8:11], v[154:157], v[238:241], v[8:11]
	v_mfma_f32_16x16x32_bf16 v[52:55], v[174:177], v[190:193], v[52:55]
	v_mfma_f32_16x16x32_bf16 v[48:51], v[182:185], v[190:193], v[48:51]
	v_mfma_f32_16x16x32_bf16 v[36:39], v[174:177], v[198:201], v[36:39]
	v_mfma_f32_16x16x32_bf16 v[32:35], v[182:185], v[198:201], v[32:35]
	v_mfma_f32_16x16x32_bf16 v[20:23], v[174:177], v[206:209], v[20:23]
	v_mfma_f32_16x16x32_bf16 v[16:19], v[182:185], v[206:209], v[16:19]
	v_mfma_f32_16x16x32_bf16 v[4:7], v[174:177], v[214:217], v[4:7]
	v_mfma_f32_16x16x32_bf16 v[0:3], v[182:185], v[214:217], v[0:3]
	v_mfma_f32_16x16x32_bf16 v[52:55], v[178:181], v[194:197], v[52:55]
	v_mfma_f32_16x16x32_bf16 v[48:51], v[186:189], v[194:197], v[48:51]
	v_mfma_f32_16x16x32_bf16 v[36:39], v[178:181], v[202:205], v[36:39]
	v_mfma_f32_16x16x32_bf16 v[32:35], v[186:189], v[202:205], v[32:35]
	v_mfma_f32_16x16x32_bf16 v[20:23], v[178:181], v[210:213], v[20:23]
	v_mfma_f32_16x16x32_bf16 v[16:19], v[186:189], v[210:213], v[16:19]
	v_mfma_f32_16x16x32_bf16 v[4:7], v[178:181], v[238:241], v[4:7]
	v_mfma_f32_16x16x32_bf16 v[0:3], v[186:189], v[238:241], v[0:3]
	s_barrier
	s_add_i32 s48, 0, 0x18000
	s_add_i32 s49, 0, 0x1c000
	ds_read_b128 v[138:141], v159 offset:32768
	ds_read_b128 v[146:149], v159 offset:33792
	ds_read_b128 v[150:153], v159 offset:34816
	ds_read_b128 v[154:157], v159 offset:35840
	ds_read_b128 v[174:177], v159 offset:49152
	ds_read_b128 v[178:181], v159 offset:50176
	ds_read_b128 v[182:185], v159 offset:51200
	ds_read_b128 v[186:189], v159 offset:52224
	s_add_u32 s8, s14, 0xb0000
	s_addc_u32 s9, s15, 0
	s_mov_b32 m0, s31
	ds_read_b128 v[190:193], v145 offset:32768
	ds_read_b128 v[194:197], v145 offset:33792
	ds_read_b128 v[198:201], v145 offset:34816
	ds_read_b128 v[202:205], v145 offset:35840
	ds_read_b128 v[206:209], v145 offset:36864
	ds_read_b128 v[210:213], v145 offset:37888
	ds_read_b128 v[214:217], v145 offset:38912
	global_load_lds_dwordx4 v128, s[8:9]
	s_mov_b32 m0, s33
	ds_read_b128 v[238:241], v145 offset:39936
	global_load_lds_dwordx4 v130, s[8:9]
	s_waitcnt vmcnt(8) lgkmcnt(0)
	s_barrier
	v_mfma_f32_16x16x32_bf16 v[124:127], v[138:141], v[190:193], v[124:127]
	v_mfma_f32_16x16x32_bf16 v[120:123], v[150:153], v[190:193], v[120:123]
	v_mfma_f32_16x16x32_bf16 v[108:111], v[138:141], v[198:201], v[108:111]
	v_mfma_f32_16x16x32_bf16 v[104:107], v[150:153], v[198:201], v[104:107]
	v_mfma_f32_16x16x32_bf16 v[92:95], v[138:141], v[206:209], v[92:95]
	v_mfma_f32_16x16x32_bf16 v[88:91], v[150:153], v[206:209], v[88:91]
	v_mfma_f32_16x16x32_bf16 v[76:79], v[138:141], v[214:217], v[76:79]
	v_mfma_f32_16x16x32_bf16 v[72:75], v[150:153], v[214:217], v[72:75]
	v_mfma_f32_16x16x32_bf16 v[124:127], v[146:149], v[194:197], v[124:127]
	v_mfma_f32_16x16x32_bf16 v[120:123], v[154:157], v[194:197], v[120:123]
	v_mfma_f32_16x16x32_bf16 v[108:111], v[146:149], v[202:205], v[108:111]
	v_mfma_f32_16x16x32_bf16 v[104:107], v[154:157], v[202:205], v[104:107]
	v_mfma_f32_16x16x32_bf16 v[92:95], v[146:149], v[210:213], v[92:95]
	v_mfma_f32_16x16x32_bf16 v[88:91], v[154:157], v[210:213], v[88:91]
	v_mfma_f32_16x16x32_bf16 v[76:79], v[146:149], v[238:241], v[76:79]
	v_mfma_f32_16x16x32_bf16 v[72:75], v[154:157], v[238:241], v[72:75]
	v_mfma_f32_16x16x32_bf16 v[116:119], v[174:177], v[190:193], v[116:119]
	v_mfma_f32_16x16x32_bf16 v[112:115], v[182:185], v[190:193], v[112:115]
	v_mfma_f32_16x16x32_bf16 v[100:103], v[174:177], v[198:201], v[100:103]
	v_mfma_f32_16x16x32_bf16 v[96:99], v[182:185], v[198:201], v[96:99]
	v_mfma_f32_16x16x32_bf16 v[84:87], v[174:177], v[206:209], v[84:87]
	v_mfma_f32_16x16x32_bf16 v[80:83], v[182:185], v[206:209], v[80:83]
	v_mfma_f32_16x16x32_bf16 v[68:71], v[174:177], v[214:217], v[68:71]
	v_mfma_f32_16x16x32_bf16 v[64:67], v[182:185], v[214:217], v[64:67]
	v_mfma_f32_16x16x32_bf16 v[116:119], v[178:181], v[194:197], v[116:119]
	v_mfma_f32_16x16x32_bf16 v[112:115], v[186:189], v[194:197], v[112:115]
	v_mfma_f32_16x16x32_bf16 v[100:103], v[178:181], v[202:205], v[100:103]
	v_mfma_f32_16x16x32_bf16 v[96:99], v[186:189], v[202:205], v[96:99]
	v_mfma_f32_16x16x32_bf16 v[84:87], v[178:181], v[210:213], v[84:87]
	v_mfma_f32_16x16x32_bf16 v[80:83], v[186:189], v[210:213], v[80:83]
	v_mfma_f32_16x16x32_bf16 v[68:71], v[178:181], v[238:241], v[68:71]
	v_mfma_f32_16x16x32_bf16 v[64:67], v[186:189], v[238:241], v[64:67]
	s_barrier
	s_add_i32 s8, s48, s28
	s_add_i32 m0, s8, 0xffffff80
	ds_read_b128 v[190:193], v145 offset:49152
	ds_read_b128 v[194:197], v145 offset:50176
	ds_read_b128 v[198:201], v145 offset:51200
	ds_read_b128 v[202:205], v145 offset:52224
	global_load_lds_dwordx4 v160, s[12:13] offset:128
	s_add_i32 m0, s8, 0x1f80
	s_add_u32 s8, s12, 0xb0080
	s_addc_u32 s9, s13, 0
	global_load_lds_dwordx4 v132, s[12:13] offset:128
	s_add_i32 s12, s49, s28
	s_mov_b32 m0, s12
	ds_read_b128 v[238:241], v145 offset:56320
	global_load_lds_dwordx4 v160, s[8:9]
	s_add_i32 m0, s12, 0x2000
	ds_read_b128 v[214:217], v145 offset:55296
	global_load_lds_dwordx4 v132, s[8:9]
	s_add_i32 m0, s34, 0xffffff80
	ds_read_b128 v[210:213], v145 offset:54272
	global_load_lds_dwordx4 v128, s[14:15] offset:128
	s_add_i32 m0, s35, 0xffffff80
	ds_read_b128 v[206:209], v145 offset:53248
	global_load_lds_dwordx4 v130, s[14:15] offset:128
	s_waitcnt vmcnt(8) lgkmcnt(0)
	s_barrier
	v_mfma_f32_16x16x32_bf16 v[60:63], v[138:141], v[190:193], v[60:63]
	v_mfma_f32_16x16x32_bf16 v[56:59], v[150:153], v[190:193], v[56:59]
	v_mfma_f32_16x16x32_bf16 v[44:47], v[138:141], v[198:201], v[44:47]
	v_mfma_f32_16x16x32_bf16 v[40:43], v[150:153], v[198:201], v[40:43]
	v_mfma_f32_16x16x32_bf16 v[28:31], v[138:141], v[206:209], v[28:31]
	v_mfma_f32_16x16x32_bf16 v[24:27], v[150:153], v[206:209], v[24:27]
	v_mfma_f32_16x16x32_bf16 v[12:15], v[138:141], v[214:217], v[12:15]
	v_mfma_f32_16x16x32_bf16 v[8:11], v[150:153], v[214:217], v[8:11]
	v_mfma_f32_16x16x32_bf16 v[60:63], v[146:149], v[194:197], v[60:63]
	v_mfma_f32_16x16x32_bf16 v[56:59], v[154:157], v[194:197], v[56:59]
	v_mfma_f32_16x16x32_bf16 v[44:47], v[146:149], v[202:205], v[44:47]
	v_mfma_f32_16x16x32_bf16 v[40:43], v[154:157], v[202:205], v[40:43]
	v_mfma_f32_16x16x32_bf16 v[28:31], v[146:149], v[210:213], v[28:31]
	v_mfma_f32_16x16x32_bf16 v[24:27], v[154:157], v[210:213], v[24:27]
	v_mfma_f32_16x16x32_bf16 v[12:15], v[146:149], v[238:241], v[12:15]
	v_mfma_f32_16x16x32_bf16 v[8:11], v[154:157], v[238:241], v[8:11]
	v_mfma_f32_16x16x32_bf16 v[52:55], v[174:177], v[190:193], v[52:55]
	v_mfma_f32_16x16x32_bf16 v[48:51], v[182:185], v[190:193], v[48:51]
	v_mfma_f32_16x16x32_bf16 v[36:39], v[174:177], v[198:201], v[36:39]
	v_mfma_f32_16x16x32_bf16 v[32:35], v[182:185], v[198:201], v[32:35]
	v_mfma_f32_16x16x32_bf16 v[20:23], v[174:177], v[206:209], v[20:23]
	v_mfma_f32_16x16x32_bf16 v[16:19], v[182:185], v[206:209], v[16:19]
	v_mfma_f32_16x16x32_bf16 v[4:7], v[174:177], v[214:217], v[4:7]
	v_mfma_f32_16x16x32_bf16 v[0:3], v[182:185], v[214:217], v[0:3]
	v_mfma_f32_16x16x32_bf16 v[52:55], v[178:181], v[194:197], v[52:55]
	v_mfma_f32_16x16x32_bf16 v[48:51], v[186:189], v[194:197], v[48:51]
	v_mfma_f32_16x16x32_bf16 v[36:39], v[178:181], v[202:205], v[36:39]
	v_mfma_f32_16x16x32_bf16 v[32:35], v[186:189], v[202:205], v[32:35]
	v_mfma_f32_16x16x32_bf16 v[20:23], v[178:181], v[210:213], v[20:23]
	v_mfma_f32_16x16x32_bf16 v[16:19], v[186:189], v[210:213], v[16:19]
	v_mfma_f32_16x16x32_bf16 v[4:7], v[178:181], v[238:241], v[4:7]
	v_mfma_f32_16x16x32_bf16 v[0:3], v[186:189], v[238:241], v[0:3]
	s_barrier
	s_add_i32 s22, s22, 2
	s_add_u32 s21, s21, 0x100
	s_addc_u32 s96, s96, 0
	s_cmp_gt_u32 s22, 41
	s_mov_b64 s[8:9], s[10:11]
	s_cbranch_scc0 .LBB0_178
	v_lshl_add_u32 v140, s20, 8, v142
	v_lshl_or_b32 v138, s93, 8, v144
	v_lshlrev_b32_e32 v141, 11, v140
	v_lshl_add_u32 v138, v138, 1, v141
	v_lshlrev_b32_e32 v139, 3, v140
	s_mov_b64 s[8:9], s[4:5]
	global_load_dwordx4 v[146:149], v138, s[8:9]
	global_load_dwordx4 v[150:153], v138, s[8:9] offset:256
	s_add_u32 s8, s8, 0x8000
	s_addc_u32 s9, s9, 0
	global_load_dwordx4 v[154:157], v138, s[8:9]
	global_load_dwordx4 v[162:165], v138, s[8:9] offset:256
	s_add_u32 s8, s8, 0x8000
	s_addc_u32 s9, s9, 0
	global_load_dwordx4 v[166:169], v138, s[8:9]
	global_load_dwordx4 v[174:177], v138, s[8:9] offset:256
	s_add_u32 s8, s8, 0x8000
	s_addc_u32 s9, s9, 0
	global_load_dwordx4 v[178:181], v138, s[8:9]
	global_load_dwordx4 v[182:185], v138, s[8:9] offset:256
	s_add_u32 s8, s8, 0x28000
	s_addc_u32 s9, s9, 0
	global_load_dwordx4 v[186:189], v138, s[8:9]
	global_load_dwordx4 v[190:193], v138, s[8:9] offset:256
	s_add_u32 s8, s8, 0x8000
	s_addc_u32 s9, s9, 0
	global_load_dwordx4 v[194:197], v138, s[8:9]
	global_load_dwordx4 v[198:201], v138, s[8:9] offset:256
	s_add_u32 s8, s8, 0x8000
	s_addc_u32 s9, s9, 0
	global_load_dwordx4 v[202:205], v138, s[8:9]
	global_load_dwordx4 v[206:209], v138, s[8:9] offset:256
	s_add_u32 s8, s8, 0x8000
	s_addc_u32 s9, s9, 0
	global_load_dwordx4 v[210:213], v138, s[8:9]
	global_load_dwordx4 v[214:217], v138, s[8:9] offset:256
	s_and_b64 vcc, exec, s[36:37]
	s_cbranch_vccz .LBB0_181
	s_barrier

.LBB0_211:
	s_ashr_i32 s37, s36, 31
	s_lshl_b64 s[14:15], s[36:37], 19
	s_add_u32 s44, s24, s14
	s_addc_u32 s45, s25, s15
	s_and_b64 s[14:15], s[38:39], exec
	s_cselect_b32 s20, s45, s13
	s_cselect_b32 s37, s44, s12
	s_ashr_i32 s41, s40, 31
	s_lshl_b64 s[14:15], s[40:41], 19
	s_add_u32 s92, s26, s14
	s_addc_u32 s93, s27, s15
	s_and_b64 s[14:15], s[38:39], exec
	s_cselect_b32 s41, s93, s11
	s_cselect_b32 s91, s92, s10
	s_add_u32 s96, s10, 0x100
	s_addc_u32 s97, s11, 0
	s_add_u32 s10, s12, 0x40080
	v_mov_b32_e32 v4, 0
	s_addc_u32 s11, s13, 0
	s_mov_b32 s21, -2
	v_mov_b32_e32 v5, v4
	v_mov_b32_e32 v6, v4
	v_mov_b32_e32 v7, v4
	v_mov_b32_e32 v8, v4
	v_mov_b32_e32 v9, v4
	v_mov_b32_e32 v10, v4
	v_mov_b32_e32 v11, v4
	v_mov_b32_e32 v20, v4
	v_mov_b32_e32 v21, v4
	v_mov_b32_e32 v22, v4
	v_mov_b32_e32 v23, v4
	v_mov_b32_e32 v24, v4
	v_mov_b32_e32 v25, v4
	v_mov_b32_e32 v26, v4
	v_mov_b32_e32 v27, v4
	v_mov_b32_e32 v36, v4
	v_mov_b32_e32 v37, v4
	v_mov_b32_e32 v38, v4
	v_mov_b32_e32 v39, v4
	v_mov_b32_e32 v40, v4
	v_mov_b32_e32 v41, v4
	v_mov_b32_e32 v42, v4
	v_mov_b32_e32 v43, v4
	v_mov_b32_e32 v52, v4
	v_mov_b32_e32 v53, v4
	v_mov_b32_e32 v54, v4
	v_mov_b32_e32 v55, v4
	v_mov_b32_e32 v56, v4
	v_mov_b32_e32 v57, v4
	v_mov_b32_e32 v58, v4
	v_mov_b32_e32 v59, v4
	v_mov_b32_e32 v0, v4
	v_mov_b32_e32 v1, v4
	v_mov_b32_e32 v2, v4
	v_mov_b32_e32 v3, v4
	v_mov_b32_e32 v12, v4
	v_mov_b32_e32 v13, v4
	v_mov_b32_e32 v14, v4
	v_mov_b32_e32 v15, v4
	v_mov_b32_e32 v16, v4
	v_mov_b32_e32 v17, v4
	v_mov_b32_e32 v18, v4
	v_mov_b32_e32 v19, v4
	v_mov_b32_e32 v28, v4
	v_mov_b32_e32 v29, v4
	v_mov_b32_e32 v30, v4
	v_mov_b32_e32 v31, v4
	v_mov_b32_e32 v32, v4
	v_mov_b32_e32 v33, v4
	v_mov_b32_e32 v34, v4
	v_mov_b32_e32 v35, v4
	v_mov_b32_e32 v44, v4
	v_mov_b32_e32 v45, v4
	v_mov_b32_e32 v46, v4
	v_mov_b32_e32 v47, v4
	v_mov_b32_e32 v48, v4
	v_mov_b32_e32 v49, v4
	v_mov_b32_e32 v50, v4
	v_mov_b32_e32 v51, v4
	v_mov_b32_e32 v60, v4
	v_mov_b32_e32 v61, v4
	v_mov_b32_e32 v62, v4
	v_mov_b32_e32 v63, v4
	v_mov_b32_e32 v68, v4
	v_mov_b32_e32 v69, v4
	v_mov_b32_e32 v70, v4
	v_mov_b32_e32 v71, v4
	v_mov_b32_e32 v72, v4
	v_mov_b32_e32 v73, v4
	v_mov_b32_e32 v74, v4
	v_mov_b32_e32 v75, v4
	v_mov_b32_e32 v80, v4
	v_mov_b32_e32 v81, v4
	v_mov_b32_e32 v82, v4
	v_mov_b32_e32 v83, v4
	v_mov_b32_e32 v88, v4
	v_mov_b32_e32 v89, v4
	v_mov_b32_e32 v90, v4
	v_mov_b32_e32 v91, v4
	v_mov_b32_e32 v96, v4
	v_mov_b32_e32 v97, v4
	v_mov_b32_e32 v98, v4
	v_mov_b32_e32 v99, v4
	v_mov_b32_e32 v104, v4
	v_mov_b32_e32 v105, v4
	v_mov_b32_e32 v106, v4
	v_mov_b32_e32 v107, v4
	v_mov_b32_e32 v112, v4
	v_mov_b32_e32 v113, v4
	v_mov_b32_e32 v114, v4
	v_mov_b32_e32 v115, v4
	v_mov_b32_e32 v120, v4
	v_mov_b32_e32 v121, v4
	v_mov_b32_e32 v122, v4
	v_mov_b32_e32 v123, v4
	v_mov_b32_e32 v64, v4
	v_mov_b32_e32 v65, v4
	v_mov_b32_e32 v66, v4
	v_mov_b32_e32 v67, v4
	v_mov_b32_e32 v76, v4
	v_mov_b32_e32 v77, v4
	v_mov_b32_e32 v78, v4
	v_mov_b32_e32 v79, v4
	v_mov_b32_e32 v84, v4
	v_mov_b32_e32 v85, v4
	v_mov_b32_e32 v86, v4
	v_mov_b32_e32 v87, v4
	v_mov_b32_e32 v92, v4
	v_mov_b32_e32 v93, v4
	v_mov_b32_e32 v94, v4
	v_mov_b32_e32 v95, v4
	v_mov_b32_e32 v100, v4
	v_mov_b32_e32 v101, v4
	v_mov_b32_e32 v102, v4
	v_mov_b32_e32 v103, v4
	v_mov_b32_e32 v108, v4
	v_mov_b32_e32 v109, v4
	v_mov_b32_e32 v110, v4
	v_mov_b32_e32 v111, v4
	v_mov_b32_e32 v116, v4
	v_mov_b32_e32 v117, v4
	v_mov_b32_e32 v118, v4
	v_mov_b32_e32 v119, v4
	v_mov_b32_e32 v124, v4
	v_mov_b32_e32 v125, v4
	v_mov_b32_e32 v126, v4
	v_mov_b32_e32 v127, v4
	v_add_u32_e32 v159, 0x10000, v147
.LBB0_212:
	s_add_u32 s12, s10, 0xfffc0080
	s_addc_u32 s13, s11, -1
	s_add_i32 s22, 0, 0x10000
	s_cmp_eq_u32 s21, 12
	s_cselect_b32 s15, s20, s13
	s_cselect_b32 s14, s37, s12
	s_cselect_b32 s13, s41, s97
	s_cselect_b32 s12, s91, s96
	s_add_i32 s50, 0, 0x14000
	ds_read_b128 v[138:141], v159
	ds_read_b128 v[142:145], v159 offset:1024
	ds_read_b128 v[150:153], v159 offset:2048
	ds_read_b128 v[154:157], v159 offset:3072
	ds_read_b128 v[174:177], v159 offset:16384
	ds_read_b128 v[178:181], v159 offset:17408
	ds_read_b128 v[182:185], v159 offset:18432
	ds_read_b128 v[186:189], v159 offset:19456
	s_add_i32 m0, s30, 0xc000
	ds_read_b128 v[190:193], v149
	ds_read_b128 v[194:197], v149 offset:1024
	ds_read_b128 v[198:201], v149 offset:2048
	ds_read_b128 v[202:205], v149 offset:3072
	ds_read_b128 v[206:209], v149 offset:4096
	ds_read_b128 v[210:213], v149 offset:5120
	ds_read_b128 v[214:217], v149 offset:6144
	global_load_lds_dwordx4 v136, s[10:11]
	s_add_i32 m0, s30, 0xe000
	ds_read_b128 v[238:241], v149 offset:7168
	global_load_lds_dwordx4 v134, s[10:11]
	s_waitcnt vmcnt(8) lgkmcnt(0)
	s_barrier
	v_mfma_f32_16x16x32_bf16 v[124:127], v[138:141], v[190:193], v[124:127]
	v_mfma_f32_16x16x32_bf16 v[116:119], v[150:153], v[190:193], v[116:119]
	v_mfma_f32_16x16x32_bf16 v[108:111], v[138:141], v[198:201], v[108:111]
	v_mfma_f32_16x16x32_bf16 v[100:103], v[150:153], v[198:201], v[100:103]
	v_mfma_f32_16x16x32_bf16 v[92:95], v[138:141], v[206:209], v[92:95]
	v_mfma_f32_16x16x32_bf16 v[84:87], v[150:153], v[206:209], v[84:87]
	v_mfma_f32_16x16x32_bf16 v[76:79], v[138:141], v[214:217], v[76:79]
	v_mfma_f32_16x16x32_bf16 v[64:67], v[150:153], v[214:217], v[64:67]
	v_mfma_f32_16x16x32_bf16 v[124:127], v[142:145], v[194:197], v[124:127]
	v_mfma_f32_16x16x32_bf16 v[116:119], v[154:157], v[194:197], v[116:119]
	v_mfma_f32_16x16x32_bf16 v[108:111], v[142:145], v[202:205], v[108:111]
	v_mfma_f32_16x16x32_bf16 v[100:103], v[154:157], v[202:205], v[100:103]
	v_mfma_f32_16x16x32_bf16 v[92:95], v[142:145], v[210:213], v[92:95]
	v_mfma_f32_16x16x32_bf16 v[84:87], v[154:157], v[210:213], v[84:87]
	v_mfma_f32_16x16x32_bf16 v[76:79], v[142:145], v[238:241], v[76:79]
	v_mfma_f32_16x16x32_bf16 v[64:67], v[154:157], v[238:241], v[64:67]
	v_mfma_f32_16x16x32_bf16 v[120:123], v[174:177], v[190:193], v[120:123]
	v_mfma_f32_16x16x32_bf16 v[112:115], v[182:185], v[190:193], v[112:115]
	v_mfma_f32_16x16x32_bf16 v[104:107], v[174:177], v[198:201], v[104:107]
	v_mfma_f32_16x16x32_bf16 v[96:99], v[182:185], v[198:201], v[96:99]
	v_mfma_f32_16x16x32_bf16 v[88:91], v[174:177], v[206:209], v[88:91]
	v_mfma_f32_16x16x32_bf16 v[80:83], v[182:185], v[206:209], v[80:83]
	v_mfma_f32_16x16x32_bf16 v[72:75], v[174:177], v[214:217], v[72:75]
	v_mfma_f32_16x16x32_bf16 v[68:71], v[182:185], v[214:217], v[68:71]
	v_mfma_f32_16x16x32_bf16 v[120:123], v[178:181], v[194:197], v[120:123]
	v_mfma_f32_16x16x32_bf16 v[112:115], v[186:189], v[194:197], v[112:115]
	v_mfma_f32_16x16x32_bf16 v[104:107], v[178:181], v[202:205], v[104:107]
	v_mfma_f32_16x16x32_bf16 v[96:99], v[186:189], v[202:205], v[96:99]
	v_mfma_f32_16x16x32_bf16 v[88:91], v[178:181], v[210:213], v[88:91]
	v_mfma_f32_16x16x32_bf16 v[80:83], v[186:189], v[210:213], v[80:83]
	v_mfma_f32_16x16x32_bf16 v[72:75], v[178:181], v[238:241], v[72:75]
	v_mfma_f32_16x16x32_bf16 v[68:71], v[186:189], v[238:241], v[68:71]
	s_barrier
	s_add_i32 s22, s22, s28
	s_mov_b32 m0, s22
	ds_read_b128 v[190:193], v149 offset:16384
	ds_read_b128 v[194:197], v149 offset:17408
	ds_read_b128 v[198:201], v149 offset:18432
	ds_read_b128 v[202:205], v149 offset:19456
	global_load_lds_dwordx4 v160, s[12:13]
	s_add_i32 m0, s22, 0x2000
	s_add_u32 s48, s12, 0x40000
	s_addc_u32 s49, s13, 0
	s_add_i32 s22, s50, s28
	global_load_lds_dwordx4 v128, s[12:13]
	s_mov_b32 m0, s22
	ds_read_b128 v[238:241], v149 offset:23552
	global_load_lds_dwordx4 v160, s[48:49]
	s_add_i32 m0, s22, 0x2000
	ds_read_b128 v[214:217], v149 offset:22528
	global_load_lds_dwordx4 v128, s[48:49]
	s_mov_b32 m0, s30
	ds_read_b128 v[210:213], v149 offset:21504
	global_load_lds_dwordx4 v132, s[14:15]
	s_mov_b32 m0, s31
	ds_read_b128 v[206:209], v149 offset:20480
	global_load_lds_dwordx4 v130, s[14:15]
	s_waitcnt vmcnt(8) lgkmcnt(0)
	s_barrier
	v_mfma_f32_16x16x32_bf16 v[60:63], v[138:141], v[190:193], v[60:63]
	v_mfma_f32_16x16x32_bf16 v[48:51], v[150:153], v[190:193], v[48:51]
	v_mfma_f32_16x16x32_bf16 v[44:47], v[138:141], v[198:201], v[44:47]
	v_mfma_f32_16x16x32_bf16 v[32:35], v[150:153], v[198:201], v[32:35]
	v_mfma_f32_16x16x32_bf16 v[28:31], v[138:141], v[206:209], v[28:31]
	v_mfma_f32_16x16x32_bf16 v[16:19], v[150:153], v[206:209], v[16:19]
	v_mfma_f32_16x16x32_bf16 v[12:15], v[138:141], v[214:217], v[12:15]
	v_mfma_f32_16x16x32_bf16 v[0:3], v[150:153], v[214:217], v[0:3]
	v_mfma_f32_16x16x32_bf16 v[60:63], v[142:145], v[194:197], v[60:63]
	v_mfma_f32_16x16x32_bf16 v[48:51], v[154:157], v[194:197], v[48:51]
	v_mfma_f32_16x16x32_bf16 v[44:47], v[142:145], v[202:205], v[44:47]
	v_mfma_f32_16x16x32_bf16 v[32:35], v[154:157], v[202:205], v[32:35]
	v_mfma_f32_16x16x32_bf16 v[28:31], v[142:145], v[210:213], v[28:31]
	v_mfma_f32_16x16x32_bf16 v[16:19], v[154:157], v[210:213], v[16:19]
	v_mfma_f32_16x16x32_bf16 v[12:15], v[142:145], v[238:241], v[12:15]
	v_mfma_f32_16x16x32_bf16 v[0:3], v[154:157], v[238:241], v[0:3]
	v_mfma_f32_16x16x32_bf16 v[56:59], v[174:177], v[190:193], v[56:59]
	v_mfma_f32_16x16x32_bf16 v[52:55], v[182:185], v[190:193], v[52:55]
	v_mfma_f32_16x16x32_bf16 v[40:43], v[174:177], v[198:201], v[40:43]
	v_mfma_f32_16x16x32_bf16 v[36:39], v[182:185], v[198:201], v[36:39]
	v_mfma_f32_16x16x32_bf16 v[24:27], v[174:177], v[206:209], v[24:27]
	v_mfma_f32_16x16x32_bf16 v[20:23], v[182:185], v[206:209], v[20:23]
	v_mfma_f32_16x16x32_bf16 v[8:11], v[174:177], v[214:217], v[8:11]
	v_mfma_f32_16x16x32_bf16 v[4:7], v[182:185], v[214:217], v[4:7]
	v_mfma_f32_16x16x32_bf16 v[56:59], v[178:181], v[194:197], v[56:59]
	v_mfma_f32_16x16x32_bf16 v[52:55], v[186:189], v[194:197], v[52:55]
	v_mfma_f32_16x16x32_bf16 v[40:43], v[178:181], v[202:205], v[40:43]
	v_mfma_f32_16x16x32_bf16 v[36:39], v[186:189], v[202:205], v[36:39]
	v_mfma_f32_16x16x32_bf16 v[24:27], v[178:181], v[210:213], v[24:27]
	v_mfma_f32_16x16x32_bf16 v[20:23], v[186:189], v[210:213], v[20:23]
	v_mfma_f32_16x16x32_bf16 v[8:11], v[178:181], v[238:241], v[8:11]
	v_mfma_f32_16x16x32_bf16 v[4:7], v[186:189], v[238:241], v[4:7]
	s_barrier
	s_add_i32 s22, 0, 0x18000
	s_add_i32 s48, 0, 0x1c000
	ds_read_b128 v[138:141], v159 offset:32768
	ds_read_b128 v[142:145], v159 offset:33792
	ds_read_b128 v[150:153], v159 offset:34816
	ds_read_b128 v[154:157], v159 offset:35840
	ds_read_b128 v[174:177], v159 offset:49152
	ds_read_b128 v[178:181], v159 offset:50176
	ds_read_b128 v[182:185], v159 offset:51200
	ds_read_b128 v[186:189], v159 offset:52224
	s_mov_b64 s[100:101], s[14:15]
	s_add_u32 s14, s14, 0x40000
	s_addc_u32 s15, s15, 0
	s_mov_b32 m0, s33
	ds_read_b128 v[190:193], v149 offset:32768
	ds_read_b128 v[194:197], v149 offset:33792
	ds_read_b128 v[198:201], v149 offset:34816
	ds_read_b128 v[202:205], v149 offset:35840
	ds_read_b128 v[206:209], v149 offset:36864
	ds_read_b128 v[210:213], v149 offset:37888
	ds_read_b128 v[214:217], v149 offset:38912
	global_load_lds_dwordx4 v132, s[14:15]
	s_mov_b32 m0, s34
	ds_read_b128 v[238:241], v149 offset:39936
	global_load_lds_dwordx4 v130, s[14:15]
	s_waitcnt vmcnt(8) lgkmcnt(0)
	s_barrier
	v_mfma_f32_16x16x32_bf16 v[124:127], v[138:141], v[190:193], v[124:127]
	v_mfma_f32_16x16x32_bf16 v[116:119], v[150:153], v[190:193], v[116:119]
	v_mfma_f32_16x16x32_bf16 v[108:111], v[138:141], v[198:201], v[108:111]
	v_mfma_f32_16x16x32_bf16 v[100:103], v[150:153], v[198:201], v[100:103]
	v_mfma_f32_16x16x32_bf16 v[92:95], v[138:141], v[206:209], v[92:95]
	v_mfma_f32_16x16x32_bf16 v[84:87], v[150:153], v[206:209], v[84:87]
	v_mfma_f32_16x16x32_bf16 v[76:79], v[138:141], v[214:217], v[76:79]
	v_mfma_f32_16x16x32_bf16 v[64:67], v[150:153], v[214:217], v[64:67]
	v_mfma_f32_16x16x32_bf16 v[124:127], v[142:145], v[194:197], v[124:127]
	v_mfma_f32_16x16x32_bf16 v[116:119], v[154:157], v[194:197], v[116:119]
	v_mfma_f32_16x16x32_bf16 v[108:111], v[142:145], v[202:205], v[108:111]
	v_mfma_f32_16x16x32_bf16 v[100:103], v[154:157], v[202:205], v[100:103]
	v_mfma_f32_16x16x32_bf16 v[92:95], v[142:145], v[210:213], v[92:95]
	v_mfma_f32_16x16x32_bf16 v[84:87], v[154:157], v[210:213], v[84:87]
	v_mfma_f32_16x16x32_bf16 v[76:79], v[142:145], v[238:241], v[76:79]
	v_mfma_f32_16x16x32_bf16 v[64:67], v[154:157], v[238:241], v[64:67]
	v_mfma_f32_16x16x32_bf16 v[120:123], v[174:177], v[190:193], v[120:123]
	v_mfma_f32_16x16x32_bf16 v[112:115], v[182:185], v[190:193], v[112:115]
	v_mfma_f32_16x16x32_bf16 v[104:107], v[174:177], v[198:201], v[104:107]
	v_mfma_f32_16x16x32_bf16 v[96:99], v[182:185], v[198:201], v[96:99]
	v_mfma_f32_16x16x32_bf16 v[88:91], v[174:177], v[206:209], v[88:91]
	v_mfma_f32_16x16x32_bf16 v[80:83], v[182:185], v[206:209], v[80:83]
	v_mfma_f32_16x16x32_bf16 v[72:75], v[174:177], v[214:217], v[72:75]
	v_mfma_f32_16x16x32_bf16 v[68:71], v[182:185], v[214:217], v[68:71]
	v_mfma_f32_16x16x32_bf16 v[120:123], v[178:181], v[194:197], v[120:123]
	v_mfma_f32_16x16x32_bf16 v[112:115], v[186:189], v[194:197], v[112:115]
	v_mfma_f32_16x16x32_bf16 v[104:107], v[178:181], v[202:205], v[104:107]
	v_mfma_f32_16x16x32_bf16 v[96:99], v[186:189], v[202:205], v[96:99]
	v_mfma_f32_16x16x32_bf16 v[88:91], v[178:181], v[210:213], v[88:91]
	v_mfma_f32_16x16x32_bf16 v[80:83], v[186:189], v[210:213], v[80:83]
	v_mfma_f32_16x16x32_bf16 v[72:75], v[178:181], v[238:241], v[72:75]
	v_mfma_f32_16x16x32_bf16 v[68:71], v[186:189], v[238:241], v[68:71]
	s_barrier
	s_add_i32 s14, s22, s28
	s_add_i32 m0, s14, 0xffffff80
	ds_read_b128 v[190:193], v149 offset:49152
	ds_read_b128 v[194:197], v149 offset:50176
	ds_read_b128 v[198:201], v149 offset:51200
	global_load_lds_dwordx4 v160, s[12:13] offset:128
	s_add_i32 m0, s14, 0x1f80
	ds_read_b128 v[238:241], v149 offset:56320
	global_load_lds_dwordx4 v128, s[12:13] offset:128
	s_add_u32 s12, s12, 0x40080
	s_addc_u32 s13, s13, 0
	s_add_i32 s14, s48, s28
	s_mov_b32 m0, s14
	ds_read_b128 v[214:217], v149 offset:55296
	global_load_lds_dwordx4 v160, s[12:13]
	s_add_i32 m0, s14, 0x2000
	ds_read_b128 v[210:213], v149 offset:54272
	global_load_lds_dwordx4 v128, s[12:13]
	s_add_i32 m0, s35, 0xffffff80
	ds_read_b128 v[206:209], v149 offset:53248
	global_load_lds_dwordx4 v132, s[100:101] offset:128
	s_add_i32 m0, s90, 0xffffff80
	ds_read_b128 v[202:205], v149 offset:52224
	global_load_lds_dwordx4 v130, s[100:101] offset:128
	s_waitcnt vmcnt(8) lgkmcnt(0)
	s_barrier
	v_mfma_f32_16x16x32_bf16 v[60:63], v[138:141], v[190:193], v[60:63]
	v_mfma_f32_16x16x32_bf16 v[48:51], v[150:153], v[190:193], v[48:51]
	v_mfma_f32_16x16x32_bf16 v[44:47], v[138:141], v[198:201], v[44:47]
	v_mfma_f32_16x16x32_bf16 v[32:35], v[150:153], v[198:201], v[32:35]
	v_mfma_f32_16x16x32_bf16 v[28:31], v[138:141], v[206:209], v[28:31]
	v_mfma_f32_16x16x32_bf16 v[16:19], v[150:153], v[206:209], v[16:19]
	v_mfma_f32_16x16x32_bf16 v[12:15], v[138:141], v[214:217], v[12:15]
	v_mfma_f32_16x16x32_bf16 v[0:3], v[150:153], v[214:217], v[0:3]
	v_mfma_f32_16x16x32_bf16 v[60:63], v[142:145], v[194:197], v[60:63]
	v_mfma_f32_16x16x32_bf16 v[48:51], v[154:157], v[194:197], v[48:51]
	v_mfma_f32_16x16x32_bf16 v[44:47], v[142:145], v[202:205], v[44:47]
	v_mfma_f32_16x16x32_bf16 v[32:35], v[154:157], v[202:205], v[32:35]
	v_mfma_f32_16x16x32_bf16 v[28:31], v[142:145], v[210:213], v[28:31]
	v_mfma_f32_16x16x32_bf16 v[16:19], v[154:157], v[210:213], v[16:19]
	v_mfma_f32_16x16x32_bf16 v[12:15], v[142:145], v[238:241], v[12:15]
	v_mfma_f32_16x16x32_bf16 v[0:3], v[154:157], v[238:241], v[0:3]
	v_mfma_f32_16x16x32_bf16 v[56:59], v[174:177], v[190:193], v[56:59]
	v_mfma_f32_16x16x32_bf16 v[52:55], v[182:185], v[190:193], v[52:55]
	v_mfma_f32_16x16x32_bf16 v[40:43], v[174:177], v[198:201], v[40:43]
	v_mfma_f32_16x16x32_bf16 v[36:39], v[182:185], v[198:201], v[36:39]
	v_mfma_f32_16x16x32_bf16 v[24:27], v[174:177], v[206:209], v[24:27]
	v_mfma_f32_16x16x32_bf16 v[20:23], v[182:185], v[206:209], v[20:23]
	v_mfma_f32_16x16x32_bf16 v[8:11], v[174:177], v[214:217], v[8:11]
	v_mfma_f32_16x16x32_bf16 v[4:7], v[182:185], v[214:217], v[4:7]
	v_mfma_f32_16x16x32_bf16 v[56:59], v[178:181], v[194:197], v[56:59]
	v_mfma_f32_16x16x32_bf16 v[52:55], v[186:189], v[194:197], v[52:55]
	v_mfma_f32_16x16x32_bf16 v[40:43], v[178:181], v[202:205], v[40:43]
	v_mfma_f32_16x16x32_bf16 v[36:39], v[186:189], v[202:205], v[36:39]
	v_mfma_f32_16x16x32_bf16 v[24:27], v[178:181], v[210:213], v[24:27]
	v_mfma_f32_16x16x32_bf16 v[20:23], v[186:189], v[210:213], v[20:23]
	v_mfma_f32_16x16x32_bf16 v[8:11], v[178:181], v[238:241], v[8:11]
	v_mfma_f32_16x16x32_bf16 v[4:7], v[186:189], v[238:241], v[4:7]
	s_barrier
	s_add_i32 s21, s21, 2
	s_add_u32 s96, s96, 0x100
	s_addc_u32 s97, s97, 0
	s_add_u32 s10, s10, 0x100
	s_addc_u32 s11, s11, 0
	s_cmp_gt_u32 s21, 13
	s_cbranch_scc0 .LBB0_212
	v_lshl_add_u32 v192, s8, 8, v146
	v_lshlrev_b32_e32 v192, 3, v192
	global_load_dwordx2 v[176:177], v192, s[4:5]
	global_load_dwordx2 v[178:179], v192, s[4:5] offset:128
	global_load_dwordx2 v[180:181], v192, s[4:5] offset:256
	global_load_dwordx2 v[182:183], v192, s[4:5] offset:384
	global_load_dwordx2 v[184:185], v192, s[4:5] offset:1024
	global_load_dwordx2 v[186:187], v192, s[4:5] offset:1152
	global_load_dwordx2 v[188:189], v192, s[4:5] offset:1280
	global_load_dwordx2 v[190:191], v192, s[4:5] offset:1408
	s_and_b64 vcc, exec, s[6:7]
	s_cbranch_vccz .LBB0_215
	s_barrier

.LBB0_309:
	s_ashr_i32 s9, s8, 31
	s_lshl_b64 s[14:15], s[8:9], 19
	s_add_u32 s14, s24, s14
	s_addc_u32 s15, s25, s15
	s_and_b64 s[20:21], s[40:41], exec
	s_cselect_b32 s9, s15, s93
	s_cselect_b32 s20, s14, s92
	s_ashr_i32 s11, s10, 31
	s_lshl_b64 s[90:91], s[10:11], 19
	s_add_u32 s96, s26, s90
	s_addc_u32 s97, s27, s91
	s_and_b64 s[90:91], s[40:41], exec
	s_cselect_b32 s11, s97, s13
	s_cselect_b32 s45, s96, s12
	s_add_u32 s90, s12, 0x100
	s_addc_u32 s91, s13, 0
	s_add_u32 vcc_lo, s92, 0x40080
	v_mov_b32_e32 v0, 0
	s_addc_u32 vcc_hi, s93, 0
	s_mov_b32 s21, -2
	v_mov_b32_e32 v1, v0
	v_mov_b32_e32 v2, v0
	v_mov_b32_e32 v3, v0
	v_mov_b32_e32 v4, v0
	v_mov_b32_e32 v5, v0
	v_mov_b32_e32 v6, v0
	v_mov_b32_e32 v7, v0
	v_mov_b32_e32 v16, v0
	v_mov_b32_e32 v17, v0
	v_mov_b32_e32 v18, v0
	v_mov_b32_e32 v19, v0
	v_mov_b32_e32 v20, v0
	v_mov_b32_e32 v21, v0
	v_mov_b32_e32 v22, v0
	v_mov_b32_e32 v23, v0
	v_mov_b32_e32 v32, v0
	v_mov_b32_e32 v33, v0
	v_mov_b32_e32 v34, v0
	v_mov_b32_e32 v35, v0
	v_mov_b32_e32 v36, v0
	v_mov_b32_e32 v37, v0
	v_mov_b32_e32 v38, v0
	v_mov_b32_e32 v39, v0
	v_mov_b32_e32 v48, v0
	v_mov_b32_e32 v49, v0
	v_mov_b32_e32 v50, v0
	v_mov_b32_e32 v51, v0
	v_mov_b32_e32 v52, v0
	v_mov_b32_e32 v53, v0
	v_mov_b32_e32 v54, v0
	v_mov_b32_e32 v55, v0
	v_mov_b32_e32 v8, v0
	v_mov_b32_e32 v9, v0
	v_mov_b32_e32 v10, v0
	v_mov_b32_e32 v11, v0
	v_mov_b32_e32 v12, v0
	v_mov_b32_e32 v13, v0
	v_mov_b32_e32 v14, v0
	v_mov_b32_e32 v15, v0
	v_mov_b32_e32 v24, v0
	v_mov_b32_e32 v25, v0
	v_mov_b32_e32 v26, v0
	v_mov_b32_e32 v27, v0
	v_mov_b32_e32 v28, v0
	v_mov_b32_e32 v29, v0
	v_mov_b32_e32 v30, v0
	v_mov_b32_e32 v31, v0
	v_mov_b32_e32 v40, v0
	v_mov_b32_e32 v41, v0
	v_mov_b32_e32 v42, v0
	v_mov_b32_e32 v43, v0
	v_mov_b32_e32 v44, v0
	v_mov_b32_e32 v45, v0
	v_mov_b32_e32 v46, v0
	v_mov_b32_e32 v47, v0
	v_mov_b32_e32 v56, v0
	v_mov_b32_e32 v57, v0
	v_mov_b32_e32 v58, v0
	v_mov_b32_e32 v59, v0
	v_mov_b32_e32 v60, v0
	v_mov_b32_e32 v61, v0
	v_mov_b32_e32 v62, v0
	v_mov_b32_e32 v63, v0
	v_mov_b32_e32 v64, v0
	v_mov_b32_e32 v65, v0
	v_mov_b32_e32 v66, v0
	v_mov_b32_e32 v67, v0
	v_mov_b32_e32 v68, v0
	v_mov_b32_e32 v69, v0
	v_mov_b32_e32 v70, v0
	v_mov_b32_e32 v71, v0
	v_mov_b32_e32 v80, v0
	v_mov_b32_e32 v81, v0
	v_mov_b32_e32 v82, v0
	v_mov_b32_e32 v83, v0
	v_mov_b32_e32 v84, v0
	v_mov_b32_e32 v85, v0
	v_mov_b32_e32 v86, v0
	v_mov_b32_e32 v87, v0
	v_mov_b32_e32 v96, v0
	v_mov_b32_e32 v97, v0
	v_mov_b32_e32 v98, v0
	v_mov_b32_e32 v99, v0
	v_mov_b32_e32 v100, v0
	v_mov_b32_e32 v101, v0
	v_mov_b32_e32 v102, v0
	v_mov_b32_e32 v103, v0
	v_mov_b32_e32 v112, v0
	v_mov_b32_e32 v113, v0
	v_mov_b32_e32 v114, v0
	v_mov_b32_e32 v115, v0
	v_mov_b32_e32 v116, v0
	v_mov_b32_e32 v117, v0
	v_mov_b32_e32 v118, v0
	v_mov_b32_e32 v119, v0
	v_mov_b32_e32 v72, v0
	v_mov_b32_e32 v73, v0
	v_mov_b32_e32 v74, v0
	v_mov_b32_e32 v75, v0
	v_mov_b32_e32 v76, v0
	v_mov_b32_e32 v77, v0
	v_mov_b32_e32 v78, v0
	v_mov_b32_e32 v79, v0
	v_mov_b32_e32 v88, v0
	v_mov_b32_e32 v89, v0
	v_mov_b32_e32 v90, v0
	v_mov_b32_e32 v91, v0
	v_mov_b32_e32 v92, v0
	v_mov_b32_e32 v93, v0
	v_mov_b32_e32 v94, v0
	v_mov_b32_e32 v95, v0
	v_mov_b32_e32 v104, v0
	v_mov_b32_e32 v105, v0
	v_mov_b32_e32 v106, v0
	v_mov_b32_e32 v107, v0
	v_mov_b32_e32 v108, v0
	v_mov_b32_e32 v109, v0
	v_mov_b32_e32 v110, v0
	v_mov_b32_e32 v111, v0
	v_mov_b32_e32 v120, v0
	v_mov_b32_e32 v121, v0
	v_mov_b32_e32 v122, v0
	v_mov_b32_e32 v123, v0
	v_mov_b32_e32 v124, v0
	v_mov_b32_e32 v125, v0
	v_mov_b32_e32 v126, v0
	v_mov_b32_e32 v127, v0
	v_add_u32_e32 v159, 0x10000, v143
.LBB0_310:
	s_add_u32 s12, vcc_lo, 0xfffc0080
	s_addc_u32 s13, vcc_hi, -1
	s_add_i32 s22, 0, 0x10000
	s_cmp_eq_u32 s21, 12
	s_cselect_b32 s93, s9, s13
	s_cselect_b32 s92, s20, s12
	s_cselect_b32 s13, s11, s91
	s_cselect_b32 s12, s45, s90
	s_add_i32 s50, 0, 0x14000
	ds_read_b128 v[138:141], v159
	ds_read_b128 v[146:149], v159 offset:1024
	ds_read_b128 v[150:153], v159 offset:2048
	ds_read_b128 v[154:157], v159 offset:3072
	ds_read_b128 v[174:177], v159 offset:16384
	ds_read_b128 v[178:181], v159 offset:17408
	ds_read_b128 v[182:185], v159 offset:18432
	ds_read_b128 v[186:189], v159 offset:19456
	s_add_i32 m0, s29, 0xc000
	ds_read_b128 v[190:193], v145
	ds_read_b128 v[194:197], v145 offset:1024
	ds_read_b128 v[198:201], v145 offset:2048
	ds_read_b128 v[202:205], v145 offset:3072
	ds_read_b128 v[206:209], v145 offset:4096
	ds_read_b128 v[210:213], v145 offset:5120
	ds_read_b128 v[214:217], v145 offset:6144
	global_load_lds_dwordx4 v136, vcc
	s_add_i32 m0, s29, 0xe000
	ds_read_b128 v[238:241], v145 offset:7168
	global_load_lds_dwordx4 v134, vcc
	s_waitcnt vmcnt(8) lgkmcnt(0)
	s_barrier
	v_mfma_f32_16x16x32_bf16 v[124:127], v[138:141], v[190:193], v[124:127]
	v_mfma_f32_16x16x32_bf16 v[120:123], v[150:153], v[190:193], v[120:123]
	v_mfma_f32_16x16x32_bf16 v[108:111], v[138:141], v[198:201], v[108:111]
	v_mfma_f32_16x16x32_bf16 v[104:107], v[150:153], v[198:201], v[104:107]
	v_mfma_f32_16x16x32_bf16 v[92:95], v[138:141], v[206:209], v[92:95]
	v_mfma_f32_16x16x32_bf16 v[88:91], v[150:153], v[206:209], v[88:91]
	v_mfma_f32_16x16x32_bf16 v[76:79], v[138:141], v[214:217], v[76:79]
	v_mfma_f32_16x16x32_bf16 v[72:75], v[150:153], v[214:217], v[72:75]
	v_mfma_f32_16x16x32_bf16 v[124:127], v[146:149], v[194:197], v[124:127]
	v_mfma_f32_16x16x32_bf16 v[120:123], v[154:157], v[194:197], v[120:123]
	v_mfma_f32_16x16x32_bf16 v[108:111], v[146:149], v[202:205], v[108:111]
	v_mfma_f32_16x16x32_bf16 v[104:107], v[154:157], v[202:205], v[104:107]
	v_mfma_f32_16x16x32_bf16 v[92:95], v[146:149], v[210:213], v[92:95]
	v_mfma_f32_16x16x32_bf16 v[88:91], v[154:157], v[210:213], v[88:91]
	v_mfma_f32_16x16x32_bf16 v[76:79], v[146:149], v[238:241], v[76:79]
	v_mfma_f32_16x16x32_bf16 v[72:75], v[154:157], v[238:241], v[72:75]
	v_mfma_f32_16x16x32_bf16 v[116:119], v[174:177], v[190:193], v[116:119]
	v_mfma_f32_16x16x32_bf16 v[112:115], v[182:185], v[190:193], v[112:115]
	v_mfma_f32_16x16x32_bf16 v[100:103], v[174:177], v[198:201], v[100:103]
	v_mfma_f32_16x16x32_bf16 v[96:99], v[182:185], v[198:201], v[96:99]
	v_mfma_f32_16x16x32_bf16 v[84:87], v[174:177], v[206:209], v[84:87]
	v_mfma_f32_16x16x32_bf16 v[80:83], v[182:185], v[206:209], v[80:83]
	v_mfma_f32_16x16x32_bf16 v[68:71], v[174:177], v[214:217], v[68:71]
	v_mfma_f32_16x16x32_bf16 v[64:67], v[182:185], v[214:217], v[64:67]
	v_mfma_f32_16x16x32_bf16 v[116:119], v[178:181], v[194:197], v[116:119]
	v_mfma_f32_16x16x32_bf16 v[112:115], v[186:189], v[194:197], v[112:115]
	v_mfma_f32_16x16x32_bf16 v[100:103], v[178:181], v[202:205], v[100:103]
	v_mfma_f32_16x16x32_bf16 v[96:99], v[186:189], v[202:205], v[96:99]
	v_mfma_f32_16x16x32_bf16 v[84:87], v[178:181], v[210:213], v[84:87]
	v_mfma_f32_16x16x32_bf16 v[80:83], v[186:189], v[210:213], v[80:83]
	v_mfma_f32_16x16x32_bf16 v[68:71], v[178:181], v[238:241], v[68:71]
	v_mfma_f32_16x16x32_bf16 v[64:67], v[186:189], v[238:241], v[64:67]
	s_barrier
	s_add_i32 s22, s22, s28
	s_mov_b32 m0, s22
	ds_read_b128 v[190:193], v145 offset:16384
	ds_read_b128 v[194:197], v145 offset:17408
	ds_read_b128 v[198:201], v145 offset:18432
	ds_read_b128 v[202:205], v145 offset:19456
	global_load_lds_dwordx4 v160, s[12:13]
	s_add_i32 m0, s22, 0x2000
	s_add_u32 s48, s12, 0x40000
	s_addc_u32 s49, s13, 0
	s_add_i32 s22, s50, s28
	global_load_lds_dwordx4 v132, s[12:13]
	s_mov_b32 m0, s22
	ds_read_b128 v[238:241], v145 offset:23552
	global_load_lds_dwordx4 v160, s[48:49]
	s_add_i32 m0, s22, 0x2000
	ds_read_b128 v[214:217], v145 offset:22528
	global_load_lds_dwordx4 v132, s[48:49]
	s_mov_b32 m0, s29
	ds_read_b128 v[210:213], v145 offset:21504
	global_load_lds_dwordx4 v128, s[92:93]
	s_mov_b32 m0, s30
	ds_read_b128 v[206:209], v145 offset:20480
	global_load_lds_dwordx4 v130, s[92:93]
	s_waitcnt vmcnt(8) lgkmcnt(0)
	s_barrier
	v_mfma_f32_16x16x32_bf16 v[60:63], v[138:141], v[190:193], v[60:63]
	v_mfma_f32_16x16x32_bf16 v[56:59], v[150:153], v[190:193], v[56:59]
	v_mfma_f32_16x16x32_bf16 v[44:47], v[138:141], v[198:201], v[44:47]
	v_mfma_f32_16x16x32_bf16 v[40:43], v[150:153], v[198:201], v[40:43]
	v_mfma_f32_16x16x32_bf16 v[28:31], v[138:141], v[206:209], v[28:31]
	v_mfma_f32_16x16x32_bf16 v[24:27], v[150:153], v[206:209], v[24:27]
	v_mfma_f32_16x16x32_bf16 v[12:15], v[138:141], v[214:217], v[12:15]
	v_mfma_f32_16x16x32_bf16 v[8:11], v[150:153], v[214:217], v[8:11]
	v_mfma_f32_16x16x32_bf16 v[60:63], v[146:149], v[194:197], v[60:63]
	v_mfma_f32_16x16x32_bf16 v[56:59], v[154:157], v[194:197], v[56:59]
	v_mfma_f32_16x16x32_bf16 v[44:47], v[146:149], v[202:205], v[44:47]
	v_mfma_f32_16x16x32_bf16 v[40:43], v[154:157], v[202:205], v[40:43]
	v_mfma_f32_16x16x32_bf16 v[28:31], v[146:149], v[210:213], v[28:31]
	v_mfma_f32_16x16x32_bf16 v[24:27], v[154:157], v[210:213], v[24:27]
	v_mfma_f32_16x16x32_bf16 v[12:15], v[146:149], v[238:241], v[12:15]
	v_mfma_f32_16x16x32_bf16 v[8:11], v[154:157], v[238:241], v[8:11]
	v_mfma_f32_16x16x32_bf16 v[52:55], v[174:177], v[190:193], v[52:55]
	v_mfma_f32_16x16x32_bf16 v[48:51], v[182:185], v[190:193], v[48:51]
	v_mfma_f32_16x16x32_bf16 v[36:39], v[174:177], v[198:201], v[36:39]
	v_mfma_f32_16x16x32_bf16 v[32:35], v[182:185], v[198:201], v[32:35]
	v_mfma_f32_16x16x32_bf16 v[20:23], v[174:177], v[206:209], v[20:23]
	v_mfma_f32_16x16x32_bf16 v[16:19], v[182:185], v[206:209], v[16:19]
	v_mfma_f32_16x16x32_bf16 v[4:7], v[174:177], v[214:217], v[4:7]
	v_mfma_f32_16x16x32_bf16 v[0:3], v[182:185], v[214:217], v[0:3]
	v_mfma_f32_16x16x32_bf16 v[52:55], v[178:181], v[194:197], v[52:55]
	v_mfma_f32_16x16x32_bf16 v[48:51], v[186:189], v[194:197], v[48:51]
	v_mfma_f32_16x16x32_bf16 v[36:39], v[178:181], v[202:205], v[36:39]
	v_mfma_f32_16x16x32_bf16 v[32:35], v[186:189], v[202:205], v[32:35]
	v_mfma_f32_16x16x32_bf16 v[20:23], v[178:181], v[210:213], v[20:23]
	v_mfma_f32_16x16x32_bf16 v[16:19], v[186:189], v[210:213], v[16:19]
	v_mfma_f32_16x16x32_bf16 v[4:7], v[178:181], v[238:241], v[4:7]
	v_mfma_f32_16x16x32_bf16 v[0:3], v[186:189], v[238:241], v[0:3]
	s_barrier
	s_add_i32 s22, 0, 0x18000
	s_add_i32 s50, 0, 0x1c000
	ds_read_b128 v[138:141], v159 offset:32768
	ds_read_b128 v[146:149], v159 offset:33792
	ds_read_b128 v[150:153], v159 offset:34816
	ds_read_b128 v[154:157], v159 offset:35840
	ds_read_b128 v[174:177], v159 offset:49152
	ds_read_b128 v[178:181], v159 offset:50176
	ds_read_b128 v[182:185], v159 offset:51200
	ds_read_b128 v[186:189], v159 offset:52224
	s_add_u32 s48, s92, 0x40000
	s_addc_u32 s49, s93, 0
	s_mov_b32 m0, s31
	ds_read_b128 v[190:193], v145 offset:32768
	ds_read_b128 v[194:197], v145 offset:33792
	ds_read_b128 v[198:201], v145 offset:34816
	ds_read_b128 v[202:205], v145 offset:35840
	ds_read_b128 v[206:209], v145 offset:36864
	ds_read_b128 v[210:213], v145 offset:37888
	ds_read_b128 v[214:217], v145 offset:38912
	global_load_lds_dwordx4 v128, s[48:49]
	s_mov_b32 m0, s33
	ds_read_b128 v[238:241], v145 offset:39936
	global_load_lds_dwordx4 v130, s[48:49]
	s_waitcnt vmcnt(8) lgkmcnt(0)
	s_barrier
	v_mfma_f32_16x16x32_bf16 v[124:127], v[138:141], v[190:193], v[124:127]
	v_mfma_f32_16x16x32_bf16 v[120:123], v[150:153], v[190:193], v[120:123]
	v_mfma_f32_16x16x32_bf16 v[108:111], v[138:141], v[198:201], v[108:111]
	v_mfma_f32_16x16x32_bf16 v[104:107], v[150:153], v[198:201], v[104:107]
	v_mfma_f32_16x16x32_bf16 v[92:95], v[138:141], v[206:209], v[92:95]
	v_mfma_f32_16x16x32_bf16 v[88:91], v[150:153], v[206:209], v[88:91]
	v_mfma_f32_16x16x32_bf16 v[76:79], v[138:141], v[214:217], v[76:79]
	v_mfma_f32_16x16x32_bf16 v[72:75], v[150:153], v[214:217], v[72:75]
	v_mfma_f32_16x16x32_bf16 v[124:127], v[146:149], v[194:197], v[124:127]
	v_mfma_f32_16x16x32_bf16 v[120:123], v[154:157], v[194:197], v[120:123]
	v_mfma_f32_16x16x32_bf16 v[108:111], v[146:149], v[202:205], v[108:111]
	v_mfma_f32_16x16x32_bf16 v[104:107], v[154:157], v[202:205], v[104:107]
	v_mfma_f32_16x16x32_bf16 v[92:95], v[146:149], v[210:213], v[92:95]
	v_mfma_f32_16x16x32_bf16 v[88:91], v[154:157], v[210:213], v[88:91]
	v_mfma_f32_16x16x32_bf16 v[76:79], v[146:149], v[238:241], v[76:79]
	v_mfma_f32_16x16x32_bf16 v[72:75], v[154:157], v[238:241], v[72:75]
	v_mfma_f32_16x16x32_bf16 v[116:119], v[174:177], v[190:193], v[116:119]
	v_mfma_f32_16x16x32_bf16 v[112:115], v[182:185], v[190:193], v[112:115]
	v_mfma_f32_16x16x32_bf16 v[100:103], v[174:177], v[198:201], v[100:103]
	v_mfma_f32_16x16x32_bf16 v[96:99], v[182:185], v[198:201], v[96:99]
	v_mfma_f32_16x16x32_bf16 v[84:87], v[174:177], v[206:209], v[84:87]
	v_mfma_f32_16x16x32_bf16 v[80:83], v[182:185], v[206:209], v[80:83]
	v_mfma_f32_16x16x32_bf16 v[68:71], v[174:177], v[214:217], v[68:71]
	v_mfma_f32_16x16x32_bf16 v[64:67], v[182:185], v[214:217], v[64:67]
	v_mfma_f32_16x16x32_bf16 v[116:119], v[178:181], v[194:197], v[116:119]
	v_mfma_f32_16x16x32_bf16 v[112:115], v[186:189], v[194:197], v[112:115]
	v_mfma_f32_16x16x32_bf16 v[100:103], v[178:181], v[202:205], v[100:103]
	v_mfma_f32_16x16x32_bf16 v[96:99], v[186:189], v[202:205], v[96:99]
	v_mfma_f32_16x16x32_bf16 v[84:87], v[178:181], v[210:213], v[84:87]
	v_mfma_f32_16x16x32_bf16 v[80:83], v[186:189], v[210:213], v[80:83]
	v_mfma_f32_16x16x32_bf16 v[68:71], v[178:181], v[238:241], v[68:71]
	v_mfma_f32_16x16x32_bf16 v[64:67], v[186:189], v[238:241], v[64:67]
	s_barrier
	s_add_i32 s22, s22, s28
	s_add_i32 m0, s22, 0xffffff80
	ds_read_b128 v[190:193], v145 offset:49152
	ds_read_b128 v[194:197], v145 offset:50176
	ds_read_b128 v[198:201], v145 offset:51200
	global_load_lds_dwordx4 v160, s[12:13] offset:128
	s_add_i32 m0, s22, 0x1f80
	ds_read_b128 v[238:241], v145 offset:56320
	global_load_lds_dwordx4 v132, s[12:13] offset:128
	s_add_u32 s12, s12, 0x40080
	s_addc_u32 s13, s13, 0
	s_add_i32 s22, s50, s28
	s_mov_b32 m0, s22
	ds_read_b128 v[214:217], v145 offset:55296
	global_load_lds_dwordx4 v160, s[12:13]
	s_add_i32 m0, s22, 0x2000
	ds_read_b128 v[210:213], v145 offset:54272
	global_load_lds_dwordx4 v132, s[12:13]
	s_add_i32 m0, s34, 0xffffff80
	ds_read_b128 v[206:209], v145 offset:53248
	global_load_lds_dwordx4 v128, s[92:93] offset:128
	s_add_i32 m0, s35, 0xffffff80
	ds_read_b128 v[202:205], v145 offset:52224
	global_load_lds_dwordx4 v130, s[92:93] offset:128
	s_waitcnt vmcnt(8) lgkmcnt(0)
	s_barrier
	v_mfma_f32_16x16x32_bf16 v[60:63], v[138:141], v[190:193], v[60:63]
	v_mfma_f32_16x16x32_bf16 v[56:59], v[150:153], v[190:193], v[56:59]
	v_mfma_f32_16x16x32_bf16 v[44:47], v[138:141], v[198:201], v[44:47]
	v_mfma_f32_16x16x32_bf16 v[40:43], v[150:153], v[198:201], v[40:43]
	v_mfma_f32_16x16x32_bf16 v[28:31], v[138:141], v[206:209], v[28:31]
	v_mfma_f32_16x16x32_bf16 v[24:27], v[150:153], v[206:209], v[24:27]
	v_mfma_f32_16x16x32_bf16 v[12:15], v[138:141], v[214:217], v[12:15]
	v_mfma_f32_16x16x32_bf16 v[8:11], v[150:153], v[214:217], v[8:11]
	v_mfma_f32_16x16x32_bf16 v[60:63], v[146:149], v[194:197], v[60:63]
	v_mfma_f32_16x16x32_bf16 v[56:59], v[154:157], v[194:197], v[56:59]
	v_mfma_f32_16x16x32_bf16 v[44:47], v[146:149], v[202:205], v[44:47]
	v_mfma_f32_16x16x32_bf16 v[40:43], v[154:157], v[202:205], v[40:43]
	v_mfma_f32_16x16x32_bf16 v[28:31], v[146:149], v[210:213], v[28:31]
	v_mfma_f32_16x16x32_bf16 v[24:27], v[154:157], v[210:213], v[24:27]
	v_mfma_f32_16x16x32_bf16 v[12:15], v[146:149], v[238:241], v[12:15]
	v_mfma_f32_16x16x32_bf16 v[8:11], v[154:157], v[238:241], v[8:11]
	v_mfma_f32_16x16x32_bf16 v[52:55], v[174:177], v[190:193], v[52:55]
	v_mfma_f32_16x16x32_bf16 v[48:51], v[182:185], v[190:193], v[48:51]
	v_mfma_f32_16x16x32_bf16 v[36:39], v[174:177], v[198:201], v[36:39]
	v_mfma_f32_16x16x32_bf16 v[32:35], v[182:185], v[198:201], v[32:35]
	v_mfma_f32_16x16x32_bf16 v[20:23], v[174:177], v[206:209], v[20:23]
	v_mfma_f32_16x16x32_bf16 v[16:19], v[182:185], v[206:209], v[16:19]
	v_mfma_f32_16x16x32_bf16 v[4:7], v[174:177], v[214:217], v[4:7]
	v_mfma_f32_16x16x32_bf16 v[0:3], v[182:185], v[214:217], v[0:3]
	v_mfma_f32_16x16x32_bf16 v[52:55], v[178:181], v[194:197], v[52:55]
	v_mfma_f32_16x16x32_bf16 v[48:51], v[186:189], v[194:197], v[48:51]
	v_mfma_f32_16x16x32_bf16 v[36:39], v[178:181], v[202:205], v[36:39]
	v_mfma_f32_16x16x32_bf16 v[32:35], v[186:189], v[202:205], v[32:35]
	v_mfma_f32_16x16x32_bf16 v[20:23], v[178:181], v[210:213], v[20:23]
	v_mfma_f32_16x16x32_bf16 v[16:19], v[186:189], v[210:213], v[16:19]
	v_mfma_f32_16x16x32_bf16 v[4:7], v[178:181], v[238:241], v[4:7]
	v_mfma_f32_16x16x32_bf16 v[0:3], v[186:189], v[238:241], v[0:3]
	s_barrier
	s_add_i32 s21, s21, 2
	s_add_u32 s90, s90, 0x100
	s_addc_u32 s91, s91, 0
	s_add_u32 vcc_lo, vcc_lo, 0x100
	s_addc_u32 vcc_hi, vcc_hi, 0
	s_cmp_gt_u32 s21, 13
	s_cbranch_scc0 .LBB0_310
	v_lshl_add_u32 v140, s36, 8, v142
	v_lshl_or_b32 v138, s44, 8, v144
	v_lshlrev_b32_e32 v141, 11, v140
	v_lshl_add_u32 v138, v138, 1, v141
	v_lshlrev_b32_e32 v139, 3, v140
	s_mov_b64 s[12:13], s[2:3]
	global_load_dwordx4 v[146:149], v138, s[12:13]
	global_load_dwordx4 v[150:153], v138, s[12:13] offset:256
	s_add_u32 s12, s12, 0x8000
	s_addc_u32 s13, s13, 0
	global_load_dwordx4 v[154:157], v138, s[12:13]
	global_load_dwordx4 v[162:165], v138, s[12:13] offset:256
	s_add_u32 s12, s12, 0x8000
	s_addc_u32 s13, s13, 0
	global_load_dwordx4 v[166:169], v138, s[12:13]
	global_load_dwordx4 v[174:177], v138, s[12:13] offset:256
	s_add_u32 s12, s12, 0x8000
	s_addc_u32 s13, s13, 0
	global_load_dwordx4 v[178:181], v138, s[12:13]
	global_load_dwordx4 v[182:185], v138, s[12:13] offset:256
	s_add_u32 s12, s12, 0x28000
	s_addc_u32 s13, s13, 0
	global_load_dwordx4 v[186:189], v138, s[12:13]
	global_load_dwordx4 v[190:193], v138, s[12:13] offset:256
	s_add_u32 s12, s12, 0x8000
	s_addc_u32 s13, s13, 0
	global_load_dwordx4 v[194:197], v138, s[12:13]
	global_load_dwordx4 v[198:201], v138, s[12:13] offset:256
	s_add_u32 s12, s12, 0x8000
	s_addc_u32 s13, s13, 0
	global_load_dwordx4 v[202:205], v138, s[12:13]
	global_load_dwordx4 v[206:209], v138, s[12:13] offset:256
	s_add_u32 s12, s12, 0x8000
	s_addc_u32 s13, s13, 0
	global_load_dwordx4 v[210:213], v138, s[12:13]
	global_load_dwordx4 v[214:217], v138, s[12:13] offset:256
	s_and_b64 vcc, exec, s[6:7]
	s_cbranch_vccz .LBB0_313
	s_barrier

.LBB0_398:
	s_ashr_i32 s7, s6, 31
	s_lshl_b64 s[2:3], s[6:7], 19
	s_add_u32 s2, s13, s2
	s_addc_u32 s3, s14, s3
	s_and_b64 s[4:5], s[38:39], exec
	s_cselect_b32 s7, s3, s9
	s_cselect_b32 s19, s2, s8
	s_ashr_i32 s97, s96, 31
	s_lshl_b64 s[4:5], s[96:97], 19
	s_add_u32 s4, s15, s4
	s_addc_u32 s5, s24, s5
	s_and_b64 s[10:11], s[38:39], exec
	s_cselect_b32 s20, s5, s1
	s_cselect_b32 s33, s4, s0
	s_add_u32 s90, s0, 0x100
	s_addc_u32 s91, s1, 0
	s_add_u32 s0, s8, 0x40080
	v_mov_b32_e32 v0, 0
	s_addc_u32 s1, s9, 0
	s_mov_b32 s21, -2
	v_mov_b32_e32 v1, v0
	v_mov_b32_e32 v2, v0
	v_mov_b32_e32 v3, v0
	v_mov_b32_e32 v8, v0
	v_mov_b32_e32 v9, v0
	v_mov_b32_e32 v10, v0
	v_mov_b32_e32 v11, v0
	v_mov_b32_e32 v16, v0
	v_mov_b32_e32 v17, v0
	v_mov_b32_e32 v18, v0
	v_mov_b32_e32 v19, v0
	v_mov_b32_e32 v24, v0
	v_mov_b32_e32 v25, v0
	v_mov_b32_e32 v26, v0
	v_mov_b32_e32 v27, v0
	v_mov_b32_e32 v32, v0
	v_mov_b32_e32 v33, v0
	v_mov_b32_e32 v34, v0
	v_mov_b32_e32 v35, v0
	v_mov_b32_e32 v40, v0
	v_mov_b32_e32 v41, v0
	v_mov_b32_e32 v42, v0
	v_mov_b32_e32 v43, v0
	v_mov_b32_e32 v48, v0
	v_mov_b32_e32 v49, v0
	v_mov_b32_e32 v50, v0
	v_mov_b32_e32 v51, v0
	v_mov_b32_e32 v56, v0
	v_mov_b32_e32 v57, v0
	v_mov_b32_e32 v58, v0
	v_mov_b32_e32 v59, v0
	v_mov_b32_e32 v4, v0
	v_mov_b32_e32 v5, v0
	v_mov_b32_e32 v6, v0
	v_mov_b32_e32 v7, v0
	v_mov_b32_e32 v12, v0
	v_mov_b32_e32 v13, v0
	v_mov_b32_e32 v14, v0
	v_mov_b32_e32 v15, v0
	v_mov_b32_e32 v20, v0
	v_mov_b32_e32 v21, v0
	v_mov_b32_e32 v22, v0
	v_mov_b32_e32 v23, v0
	v_mov_b32_e32 v28, v0
	v_mov_b32_e32 v29, v0
	v_mov_b32_e32 v30, v0
	v_mov_b32_e32 v31, v0
	v_mov_b32_e32 v36, v0
	v_mov_b32_e32 v37, v0
	v_mov_b32_e32 v38, v0
	v_mov_b32_e32 v39, v0
	v_mov_b32_e32 v44, v0
	v_mov_b32_e32 v45, v0
	v_mov_b32_e32 v46, v0
	v_mov_b32_e32 v47, v0
	v_mov_b32_e32 v52, v0
	v_mov_b32_e32 v53, v0
	v_mov_b32_e32 v54, v0
	v_mov_b32_e32 v55, v0
	v_mov_b32_e32 v60, v0
	v_mov_b32_e32 v61, v0
	v_mov_b32_e32 v62, v0
	v_mov_b32_e32 v63, v0
	v_mov_b32_e32 v64, v0
	v_mov_b32_e32 v65, v0
	v_mov_b32_e32 v66, v0
	v_mov_b32_e32 v67, v0
	v_mov_b32_e32 v72, v0
	v_mov_b32_e32 v73, v0
	v_mov_b32_e32 v74, v0
	v_mov_b32_e32 v75, v0
	v_mov_b32_e32 v80, v0
	v_mov_b32_e32 v81, v0
	v_mov_b32_e32 v82, v0
	v_mov_b32_e32 v83, v0
	v_mov_b32_e32 v88, v0
	v_mov_b32_e32 v89, v0
	v_mov_b32_e32 v90, v0
	v_mov_b32_e32 v91, v0
	v_mov_b32_e32 v96, v0
	v_mov_b32_e32 v97, v0
	v_mov_b32_e32 v98, v0
	v_mov_b32_e32 v99, v0
	v_mov_b32_e32 v104, v0
	v_mov_b32_e32 v105, v0
	v_mov_b32_e32 v106, v0
	v_mov_b32_e32 v107, v0
	v_mov_b32_e32 v112, v0
	v_mov_b32_e32 v113, v0
	v_mov_b32_e32 v114, v0
	v_mov_b32_e32 v115, v0
	v_mov_b32_e32 v120, v0
	v_mov_b32_e32 v121, v0
	v_mov_b32_e32 v122, v0
	v_mov_b32_e32 v123, v0
	v_mov_b32_e32 v68, v0
	v_mov_b32_e32 v69, v0
	v_mov_b32_e32 v70, v0
	v_mov_b32_e32 v71, v0
	v_mov_b32_e32 v76, v0
	v_mov_b32_e32 v77, v0
	v_mov_b32_e32 v78, v0
	v_mov_b32_e32 v79, v0
	v_mov_b32_e32 v84, v0
	v_mov_b32_e32 v85, v0
	v_mov_b32_e32 v86, v0
	v_mov_b32_e32 v87, v0
	v_mov_b32_e32 v92, v0
	v_mov_b32_e32 v93, v0
	v_mov_b32_e32 v94, v0
	v_mov_b32_e32 v95, v0
	v_mov_b32_e32 v100, v0
	v_mov_b32_e32 v101, v0
	v_mov_b32_e32 v102, v0
	v_mov_b32_e32 v103, v0
	v_mov_b32_e32 v108, v0
	v_mov_b32_e32 v109, v0
	v_mov_b32_e32 v110, v0
	v_mov_b32_e32 v111, v0
	v_mov_b32_e32 v116, v0
	v_mov_b32_e32 v117, v0
	v_mov_b32_e32 v118, v0
	v_mov_b32_e32 v119, v0
	v_mov_b32_e32 v124, v0
	v_mov_b32_e32 v125, v0
	v_mov_b32_e32 v126, v0
	v_mov_b32_e32 v127, v0
	v_add_u32_e32 v163, 0x10000, v157
.LBB0_399:
	s_add_u32 s8, s0, 0xfffc0080
	s_addc_u32 s9, s1, -1
	s_add_i32 s22, 0, 0x10000
	s_cmp_eq_u32 s21, 12
	s_cselect_b32 s11, s7, s9
	s_cselect_b32 s10, s19, s8
	s_cselect_b32 s9, s20, s91
	s_cselect_b32 s8, s33, s90
	s_add_i32 s48, 0, 0x14000
	ds_read_b128 v[128:131], v163
	ds_read_b128 v[144:147], v163 offset:1024
	ds_read_b128 v[148:151], v163 offset:2048
	ds_read_b128 v[152:155], v163 offset:3072
	ds_read_b128 v[176:179], v163 offset:16384
	ds_read_b128 v[180:183], v163 offset:17408
	ds_read_b128 v[184:187], v163 offset:18432
	ds_read_b128 v[188:191], v163 offset:19456
	s_add_i32 m0, s27, 0xc000
	ds_read_b128 v[192:195], v159
	ds_read_b128 v[196:199], v159 offset:1024
	ds_read_b128 v[200:203], v159 offset:2048
	ds_read_b128 v[204:207], v159 offset:3072
	ds_read_b128 v[208:211], v159 offset:4096
	ds_read_b128 v[212:215], v159 offset:5120
	ds_read_b128 v[238:241], v159 offset:6144
	global_load_lds_dwordx4 v142, s[0:1]
	s_add_i32 m0, s27, 0xe000
	ds_read_b128 v[246:249], v159 offset:7168
	global_load_lds_dwordx4 v140, s[0:1]
	s_waitcnt vmcnt(8) lgkmcnt(0)
	s_barrier
	v_mfma_f32_16x16x32_bf16 v[124:127], v[128:131], v[192:195], v[124:127]
	v_mfma_f32_16x16x32_bf16 v[116:119], v[148:151], v[192:195], v[116:119]
	v_mfma_f32_16x16x32_bf16 v[108:111], v[128:131], v[200:203], v[108:111]
	v_mfma_f32_16x16x32_bf16 v[100:103], v[148:151], v[200:203], v[100:103]
	v_mfma_f32_16x16x32_bf16 v[92:95], v[128:131], v[208:211], v[92:95]
	v_mfma_f32_16x16x32_bf16 v[84:87], v[148:151], v[208:211], v[84:87]
	v_mfma_f32_16x16x32_bf16 v[76:79], v[128:131], v[238:241], v[76:79]
	v_mfma_f32_16x16x32_bf16 v[68:71], v[148:151], v[238:241], v[68:71]
	v_mfma_f32_16x16x32_bf16 v[124:127], v[144:147], v[196:199], v[124:127]
	v_mfma_f32_16x16x32_bf16 v[116:119], v[152:155], v[196:199], v[116:119]
	v_mfma_f32_16x16x32_bf16 v[108:111], v[144:147], v[204:207], v[108:111]
	v_mfma_f32_16x16x32_bf16 v[100:103], v[152:155], v[204:207], v[100:103]
	v_mfma_f32_16x16x32_bf16 v[92:95], v[144:147], v[212:215], v[92:95]
	v_mfma_f32_16x16x32_bf16 v[84:87], v[152:155], v[212:215], v[84:87]
	v_mfma_f32_16x16x32_bf16 v[76:79], v[144:147], v[246:249], v[76:79]
	v_mfma_f32_16x16x32_bf16 v[68:71], v[152:155], v[246:249], v[68:71]
	v_mfma_f32_16x16x32_bf16 v[120:123], v[176:179], v[192:195], v[120:123]
	v_mfma_f32_16x16x32_bf16 v[112:115], v[184:187], v[192:195], v[112:115]
	v_mfma_f32_16x16x32_bf16 v[104:107], v[176:179], v[200:203], v[104:107]
	v_mfma_f32_16x16x32_bf16 v[96:99], v[184:187], v[200:203], v[96:99]
	v_mfma_f32_16x16x32_bf16 v[88:91], v[176:179], v[208:211], v[88:91]
	v_mfma_f32_16x16x32_bf16 v[80:83], v[184:187], v[208:211], v[80:83]
	v_mfma_f32_16x16x32_bf16 v[72:75], v[176:179], v[238:241], v[72:75]
	v_mfma_f32_16x16x32_bf16 v[64:67], v[184:187], v[238:241], v[64:67]
	v_mfma_f32_16x16x32_bf16 v[120:123], v[180:183], v[196:199], v[120:123]
	v_mfma_f32_16x16x32_bf16 v[112:115], v[188:191], v[196:199], v[112:115]
	v_mfma_f32_16x16x32_bf16 v[104:107], v[180:183], v[204:207], v[104:107]
	v_mfma_f32_16x16x32_bf16 v[96:99], v[188:191], v[204:207], v[96:99]
	v_mfma_f32_16x16x32_bf16 v[88:91], v[180:183], v[212:215], v[88:91]
	v_mfma_f32_16x16x32_bf16 v[80:83], v[188:191], v[212:215], v[80:83]
	v_mfma_f32_16x16x32_bf16 v[72:75], v[180:183], v[246:249], v[72:75]
	v_mfma_f32_16x16x32_bf16 v[64:67], v[188:191], v[246:249], v[64:67]
	s_barrier
	s_add_i32 s22, s22, s25
	s_mov_b32 m0, s22
	ds_read_b128 v[192:195], v159 offset:16384
	ds_read_b128 v[196:199], v159 offset:17408
	ds_read_b128 v[200:203], v159 offset:18432
	ds_read_b128 v[204:207], v159 offset:19456
	global_load_lds_dwordx4 v136, s[8:9]
	s_add_i32 m0, s22, 0x2000
	s_add_u32 vcc_lo, s8, 0x40000
	s_addc_u32 vcc_hi, s9, 0
	s_add_i32 s22, s48, s25
	global_load_lds_dwordx4 v132, s[8:9]
	s_mov_b32 m0, s22
	ds_read_b128 v[246:249], v159 offset:23552
	global_load_lds_dwordx4 v136, vcc
	s_add_i32 m0, s22, 0x2000
	ds_read_b128 v[238:241], v159 offset:22528
	global_load_lds_dwordx4 v132, vcc
	s_mov_b32 m0, s27
	ds_read_b128 v[212:215], v159 offset:21504
	global_load_lds_dwordx4 v138, s[10:11]
	s_mov_b32 m0, s45
	ds_read_b128 v[208:211], v159 offset:20480
	global_load_lds_dwordx4 v134, s[10:11]
	s_waitcnt vmcnt(8) lgkmcnt(0)
	s_barrier
	v_mfma_f32_16x16x32_bf16 v[60:63], v[128:131], v[192:195], v[60:63]
	v_mfma_f32_16x16x32_bf16 v[52:55], v[148:151], v[192:195], v[52:55]
	v_mfma_f32_16x16x32_bf16 v[44:47], v[128:131], v[200:203], v[44:47]
	v_mfma_f32_16x16x32_bf16 v[36:39], v[148:151], v[200:203], v[36:39]
	v_mfma_f32_16x16x32_bf16 v[28:31], v[128:131], v[208:211], v[28:31]
	v_mfma_f32_16x16x32_bf16 v[20:23], v[148:151], v[208:211], v[20:23]
	v_mfma_f32_16x16x32_bf16 v[12:15], v[128:131], v[238:241], v[12:15]
	v_mfma_f32_16x16x32_bf16 v[4:7], v[148:151], v[238:241], v[4:7]
	v_mfma_f32_16x16x32_bf16 v[60:63], v[144:147], v[196:199], v[60:63]
	v_mfma_f32_16x16x32_bf16 v[52:55], v[152:155], v[196:199], v[52:55]
	v_mfma_f32_16x16x32_bf16 v[44:47], v[144:147], v[204:207], v[44:47]
	v_mfma_f32_16x16x32_bf16 v[36:39], v[152:155], v[204:207], v[36:39]
	v_mfma_f32_16x16x32_bf16 v[28:31], v[144:147], v[212:215], v[28:31]
	v_mfma_f32_16x16x32_bf16 v[20:23], v[152:155], v[212:215], v[20:23]
	v_mfma_f32_16x16x32_bf16 v[12:15], v[144:147], v[246:249], v[12:15]
	v_mfma_f32_16x16x32_bf16 v[4:7], v[152:155], v[246:249], v[4:7]
	v_mfma_f32_16x16x32_bf16 v[56:59], v[176:179], v[192:195], v[56:59]
	v_mfma_f32_16x16x32_bf16 v[48:51], v[184:187], v[192:195], v[48:51]
	v_mfma_f32_16x16x32_bf16 v[40:43], v[176:179], v[200:203], v[40:43]
	v_mfma_f32_16x16x32_bf16 v[32:35], v[184:187], v[200:203], v[32:35]
	v_mfma_f32_16x16x32_bf16 v[24:27], v[176:179], v[208:211], v[24:27]
	v_mfma_f32_16x16x32_bf16 v[16:19], v[184:187], v[208:211], v[16:19]
	v_mfma_f32_16x16x32_bf16 v[8:11], v[176:179], v[238:241], v[8:11]
	v_mfma_f32_16x16x32_bf16 v[0:3], v[184:187], v[238:241], v[0:3]
	v_mfma_f32_16x16x32_bf16 v[56:59], v[180:183], v[196:199], v[56:59]
	v_mfma_f32_16x16x32_bf16 v[48:51], v[188:191], v[196:199], v[48:51]
	v_mfma_f32_16x16x32_bf16 v[40:43], v[180:183], v[204:207], v[40:43]
	v_mfma_f32_16x16x32_bf16 v[32:35], v[188:191], v[204:207], v[32:35]
	v_mfma_f32_16x16x32_bf16 v[24:27], v[180:183], v[212:215], v[24:27]
	v_mfma_f32_16x16x32_bf16 v[16:19], v[188:191], v[212:215], v[16:19]
	v_mfma_f32_16x16x32_bf16 v[8:11], v[180:183], v[246:249], v[8:11]
	v_mfma_f32_16x16x32_bf16 v[0:3], v[188:191], v[246:249], v[0:3]
	s_barrier
	s_add_i32 s22, 0, 0x18000
	s_add_i32 s48, 0, 0x1c000
	ds_read_b128 v[128:131], v163 offset:32768
	ds_read_b128 v[144:147], v163 offset:33792
	ds_read_b128 v[148:151], v163 offset:34816
	ds_read_b128 v[152:155], v163 offset:35840
	ds_read_b128 v[176:179], v163 offset:49152
	ds_read_b128 v[180:183], v163 offset:50176
	ds_read_b128 v[184:187], v163 offset:51200
	ds_read_b128 v[188:191], v163 offset:52224
	s_mov_b64 s[100:101], s[10:11]
	s_add_u32 s10, s10, 0x40000
	s_addc_u32 s11, s11, 0
	s_mov_b32 m0, s28
	ds_read_b128 v[192:195], v159 offset:32768
	ds_read_b128 v[196:199], v159 offset:33792
	ds_read_b128 v[200:203], v159 offset:34816
	ds_read_b128 v[204:207], v159 offset:35840
	ds_read_b128 v[208:211], v159 offset:36864
	ds_read_b128 v[212:215], v159 offset:37888
	ds_read_b128 v[238:241], v159 offset:38912
	global_load_lds_dwordx4 v138, s[10:11]
	s_mov_b32 m0, s29
	ds_read_b128 v[246:249], v159 offset:39936
	global_load_lds_dwordx4 v134, s[10:11]
	s_waitcnt vmcnt(8) lgkmcnt(0)
	s_barrier
	v_mfma_f32_16x16x32_bf16 v[124:127], v[128:131], v[192:195], v[124:127]
	v_mfma_f32_16x16x32_bf16 v[116:119], v[148:151], v[192:195], v[116:119]
	v_mfma_f32_16x16x32_bf16 v[108:111], v[128:131], v[200:203], v[108:111]
	v_mfma_f32_16x16x32_bf16 v[100:103], v[148:151], v[200:203], v[100:103]
	v_mfma_f32_16x16x32_bf16 v[92:95], v[128:131], v[208:211], v[92:95]
	v_mfma_f32_16x16x32_bf16 v[84:87], v[148:151], v[208:211], v[84:87]
	v_mfma_f32_16x16x32_bf16 v[76:79], v[128:131], v[238:241], v[76:79]
	v_mfma_f32_16x16x32_bf16 v[68:71], v[148:151], v[238:241], v[68:71]
	v_mfma_f32_16x16x32_bf16 v[124:127], v[144:147], v[196:199], v[124:127]
	v_mfma_f32_16x16x32_bf16 v[116:119], v[152:155], v[196:199], v[116:119]
	v_mfma_f32_16x16x32_bf16 v[108:111], v[144:147], v[204:207], v[108:111]
	v_mfma_f32_16x16x32_bf16 v[100:103], v[152:155], v[204:207], v[100:103]
	v_mfma_f32_16x16x32_bf16 v[92:95], v[144:147], v[212:215], v[92:95]
	v_mfma_f32_16x16x32_bf16 v[84:87], v[152:155], v[212:215], v[84:87]
	v_mfma_f32_16x16x32_bf16 v[76:79], v[144:147], v[246:249], v[76:79]
	v_mfma_f32_16x16x32_bf16 v[68:71], v[152:155], v[246:249], v[68:71]
	v_mfma_f32_16x16x32_bf16 v[120:123], v[176:179], v[192:195], v[120:123]
	v_mfma_f32_16x16x32_bf16 v[112:115], v[184:187], v[192:195], v[112:115]
	v_mfma_f32_16x16x32_bf16 v[104:107], v[176:179], v[200:203], v[104:107]
	v_mfma_f32_16x16x32_bf16 v[96:99], v[184:187], v[200:203], v[96:99]
	v_mfma_f32_16x16x32_bf16 v[88:91], v[176:179], v[208:211], v[88:91]
	v_mfma_f32_16x16x32_bf16 v[80:83], v[184:187], v[208:211], v[80:83]
	v_mfma_f32_16x16x32_bf16 v[72:75], v[176:179], v[238:241], v[72:75]
	v_mfma_f32_16x16x32_bf16 v[64:67], v[184:187], v[238:241], v[64:67]
	v_mfma_f32_16x16x32_bf16 v[120:123], v[180:183], v[196:199], v[120:123]
	v_mfma_f32_16x16x32_bf16 v[112:115], v[188:191], v[196:199], v[112:115]
	v_mfma_f32_16x16x32_bf16 v[104:107], v[180:183], v[204:207], v[104:107]
	v_mfma_f32_16x16x32_bf16 v[96:99], v[188:191], v[204:207], v[96:99]
	v_mfma_f32_16x16x32_bf16 v[88:91], v[180:183], v[212:215], v[88:91]
	v_mfma_f32_16x16x32_bf16 v[80:83], v[188:191], v[212:215], v[80:83]
	v_mfma_f32_16x16x32_bf16 v[72:75], v[180:183], v[246:249], v[72:75]
	v_mfma_f32_16x16x32_bf16 v[64:67], v[188:191], v[246:249], v[64:67]
	s_barrier
	s_add_i32 s10, s22, s25
	s_add_i32 m0, s10, 0xffffff80
	ds_read_b128 v[192:195], v159 offset:49152
	ds_read_b128 v[196:199], v159 offset:50176
	ds_read_b128 v[200:203], v159 offset:51200
	global_load_lds_dwordx4 v136, s[8:9] offset:128
	s_add_i32 m0, s10, 0x1f80
	ds_read_b128 v[246:249], v159 offset:56320
	global_load_lds_dwordx4 v132, s[8:9] offset:128
	s_add_u32 s8, s8, 0x40080
	s_addc_u32 s9, s9, 0
	s_add_i32 s10, s48, s25
	s_mov_b32 m0, s10
	ds_read_b128 v[238:241], v159 offset:55296
	global_load_lds_dwordx4 v136, s[8:9]
	s_add_i32 m0, s10, 0x2000
	ds_read_b128 v[212:215], v159 offset:54272
	global_load_lds_dwordx4 v132, s[8:9]
	s_add_i32 m0, s30, 0xffffff80
	ds_read_b128 v[208:211], v159 offset:53248
	global_load_lds_dwordx4 v138, s[100:101] offset:128
	s_add_i32 m0, s31, 0xffffff80
	ds_read_b128 v[204:207], v159 offset:52224
	global_load_lds_dwordx4 v134, s[100:101] offset:128
	s_waitcnt vmcnt(8) lgkmcnt(0)
	s_barrier
	v_mfma_f32_16x16x32_bf16 v[60:63], v[128:131], v[192:195], v[60:63]
	v_mfma_f32_16x16x32_bf16 v[52:55], v[148:151], v[192:195], v[52:55]
	v_mfma_f32_16x16x32_bf16 v[44:47], v[128:131], v[200:203], v[44:47]
	v_mfma_f32_16x16x32_bf16 v[36:39], v[148:151], v[200:203], v[36:39]
	v_mfma_f32_16x16x32_bf16 v[28:31], v[128:131], v[208:211], v[28:31]
	v_mfma_f32_16x16x32_bf16 v[20:23], v[148:151], v[208:211], v[20:23]
	v_mfma_f32_16x16x32_bf16 v[12:15], v[128:131], v[238:241], v[12:15]
	v_mfma_f32_16x16x32_bf16 v[4:7], v[148:151], v[238:241], v[4:7]
	v_mfma_f32_16x16x32_bf16 v[60:63], v[144:147], v[196:199], v[60:63]
	v_mfma_f32_16x16x32_bf16 v[52:55], v[152:155], v[196:199], v[52:55]
	v_mfma_f32_16x16x32_bf16 v[44:47], v[144:147], v[204:207], v[44:47]
	v_mfma_f32_16x16x32_bf16 v[36:39], v[152:155], v[204:207], v[36:39]
	v_mfma_f32_16x16x32_bf16 v[28:31], v[144:147], v[212:215], v[28:31]
	v_mfma_f32_16x16x32_bf16 v[20:23], v[152:155], v[212:215], v[20:23]
	v_mfma_f32_16x16x32_bf16 v[12:15], v[144:147], v[246:249], v[12:15]
	v_mfma_f32_16x16x32_bf16 v[4:7], v[152:155], v[246:249], v[4:7]
	v_mfma_f32_16x16x32_bf16 v[56:59], v[176:179], v[192:195], v[56:59]
	v_mfma_f32_16x16x32_bf16 v[48:51], v[184:187], v[192:195], v[48:51]
	v_mfma_f32_16x16x32_bf16 v[40:43], v[176:179], v[200:203], v[40:43]
	v_mfma_f32_16x16x32_bf16 v[32:35], v[184:187], v[200:203], v[32:35]
	v_mfma_f32_16x16x32_bf16 v[24:27], v[176:179], v[208:211], v[24:27]
	v_mfma_f32_16x16x32_bf16 v[16:19], v[184:187], v[208:211], v[16:19]
	v_mfma_f32_16x16x32_bf16 v[8:11], v[176:179], v[238:241], v[8:11]
	v_mfma_f32_16x16x32_bf16 v[0:3], v[184:187], v[238:241], v[0:3]
	v_mfma_f32_16x16x32_bf16 v[56:59], v[180:183], v[196:199], v[56:59]
	v_mfma_f32_16x16x32_bf16 v[48:51], v[188:191], v[196:199], v[48:51]
	v_mfma_f32_16x16x32_bf16 v[40:43], v[180:183], v[204:207], v[40:43]
	v_mfma_f32_16x16x32_bf16 v[32:35], v[188:191], v[204:207], v[32:35]
	v_mfma_f32_16x16x32_bf16 v[24:27], v[180:183], v[212:215], v[24:27]
	v_mfma_f32_16x16x32_bf16 v[16:19], v[188:191], v[212:215], v[16:19]
	v_mfma_f32_16x16x32_bf16 v[8:11], v[180:183], v[246:249], v[8:11]
	v_mfma_f32_16x16x32_bf16 v[0:3], v[188:191], v[246:249], v[0:3]
	s_barrier
	s_add_i32 s21, s21, 2
	s_add_u32 s90, s90, 0x100
	s_addc_u32 s91, s91, 0
	s_add_u32 s0, s0, 0x100
	s_addc_u32 s1, s1, 0
	s_cmp_gt_u32 s21, 13
	s_cbranch_scc0 .LBB0_399
	v_lshl_add_u32 v212, s44, 8, v156
	v_lshlrev_b32_e32 v212, 3, v212
	global_load_dwordx2 v[196:197], v212, s[36:37]
	global_load_dwordx2 v[198:199], v212, s[36:37] offset:128
	global_load_dwordx2 v[200:201], v212, s[36:37] offset:256
	global_load_dwordx2 v[202:203], v212, s[36:37] offset:384
	global_load_dwordx2 v[204:205], v212, s[36:37] offset:1024
	global_load_dwordx2 v[206:207], v212, s[36:37] offset:1152
	global_load_dwordx2 v[208:209], v212, s[36:37] offset:1280
	global_load_dwordx2 v[210:211], v212, s[36:37] offset:1408
	s_and_b64 vcc, exec, s[92:93]
	s_cbranch_vccnz .LBB0_404
	s_cmp_gt_i32 s35, 3
	s_mov_b64 s[0:1], -1
	s_cbranch_scc1 .LBB0_405

.LBB0_438:
	s_add_u32 s21, s10, 0x100
	v_mov_b32_e32 v0, 0
	s_addc_u32 s92, s11, 0
	s_mov_b32 s22, -2
	v_mov_b32_e32 v1, v0
	v_mov_b32_e32 v2, v0
	v_mov_b32_e32 v3, v0
	v_mov_b32_e32 v4, v0
	v_mov_b32_e32 v5, v0
	v_mov_b32_e32 v6, v0
	v_mov_b32_e32 v7, v0
	v_mov_b32_e32 v16, v0
	v_mov_b32_e32 v17, v0
	v_mov_b32_e32 v18, v0
	v_mov_b32_e32 v19, v0
	v_mov_b32_e32 v20, v0
	v_mov_b32_e32 v21, v0
	v_mov_b32_e32 v22, v0
	v_mov_b32_e32 v23, v0
	v_mov_b32_e32 v32, v0
	v_mov_b32_e32 v33, v0
	v_mov_b32_e32 v34, v0
	v_mov_b32_e32 v35, v0
	v_mov_b32_e32 v36, v0
	v_mov_b32_e32 v37, v0
	v_mov_b32_e32 v38, v0
	v_mov_b32_e32 v39, v0
	v_mov_b32_e32 v48, v0
	v_mov_b32_e32 v49, v0
	v_mov_b32_e32 v50, v0
	v_mov_b32_e32 v51, v0
	v_mov_b32_e32 v52, v0
	v_mov_b32_e32 v53, v0
	v_mov_b32_e32 v54, v0
	v_mov_b32_e32 v55, v0
	v_mov_b32_e32 v8, v0
	v_mov_b32_e32 v9, v0
	v_mov_b32_e32 v10, v0
	v_mov_b32_e32 v11, v0
	v_mov_b32_e32 v12, v0
	v_mov_b32_e32 v13, v0
	v_mov_b32_e32 v14, v0
	v_mov_b32_e32 v15, v0
	v_mov_b32_e32 v24, v0
	v_mov_b32_e32 v25, v0
	v_mov_b32_e32 v26, v0
	v_mov_b32_e32 v27, v0
	v_mov_b32_e32 v28, v0
	v_mov_b32_e32 v29, v0
	v_mov_b32_e32 v30, v0
	v_mov_b32_e32 v31, v0
	v_mov_b32_e32 v40, v0
	v_mov_b32_e32 v41, v0
	v_mov_b32_e32 v42, v0
	v_mov_b32_e32 v43, v0
	v_mov_b32_e32 v44, v0
	v_mov_b32_e32 v45, v0
	v_mov_b32_e32 v46, v0
	v_mov_b32_e32 v47, v0
	v_mov_b32_e32 v56, v0
	v_mov_b32_e32 v57, v0
	v_mov_b32_e32 v58, v0
	v_mov_b32_e32 v59, v0
	v_mov_b32_e32 v60, v0
	v_mov_b32_e32 v61, v0
	v_mov_b32_e32 v62, v0
	v_mov_b32_e32 v63, v0
	v_mov_b32_e32 v64, v0
	v_mov_b32_e32 v65, v0
	v_mov_b32_e32 v66, v0
	v_mov_b32_e32 v67, v0
	v_mov_b32_e32 v68, v0
	v_mov_b32_e32 v69, v0
	v_mov_b32_e32 v70, v0
	v_mov_b32_e32 v71, v0
	v_mov_b32_e32 v80, v0
	v_mov_b32_e32 v81, v0
	v_mov_b32_e32 v82, v0
	v_mov_b32_e32 v83, v0
	v_mov_b32_e32 v84, v0
	v_mov_b32_e32 v85, v0
	v_mov_b32_e32 v86, v0
	v_mov_b32_e32 v87, v0
	v_mov_b32_e32 v96, v0
	v_mov_b32_e32 v97, v0
	v_mov_b32_e32 v98, v0
	v_mov_b32_e32 v99, v0
	v_mov_b32_e32 v100, v0
	v_mov_b32_e32 v101, v0
	v_mov_b32_e32 v102, v0
	v_mov_b32_e32 v103, v0
	v_mov_b32_e32 v112, v0
	v_mov_b32_e32 v113, v0
	v_mov_b32_e32 v114, v0
	v_mov_b32_e32 v115, v0
	v_mov_b32_e32 v116, v0
	v_mov_b32_e32 v117, v0
	v_mov_b32_e32 v118, v0
	v_mov_b32_e32 v119, v0
	v_mov_b32_e32 v72, v0
	v_mov_b32_e32 v73, v0
	v_mov_b32_e32 v74, v0
	v_mov_b32_e32 v75, v0
	v_mov_b32_e32 v76, v0
	v_mov_b32_e32 v77, v0
	v_mov_b32_e32 v78, v0
	v_mov_b32_e32 v79, v0
	v_mov_b32_e32 v88, v0
	v_mov_b32_e32 v89, v0
	v_mov_b32_e32 v90, v0
	v_mov_b32_e32 v91, v0
	v_mov_b32_e32 v92, v0
	v_mov_b32_e32 v93, v0
	v_mov_b32_e32 v94, v0
	v_mov_b32_e32 v95, v0
	v_mov_b32_e32 v104, v0
	v_mov_b32_e32 v105, v0
	v_mov_b32_e32 v106, v0
	v_mov_b32_e32 v107, v0
	v_mov_b32_e32 v108, v0
	v_mov_b32_e32 v109, v0
	v_mov_b32_e32 v110, v0
	v_mov_b32_e32 v111, v0
	v_mov_b32_e32 v120, v0
	v_mov_b32_e32 v121, v0
	v_mov_b32_e32 v122, v0
	v_mov_b32_e32 v123, v0
	v_mov_b32_e32 v124, v0
	v_mov_b32_e32 v125, v0
	v_mov_b32_e32 v126, v0
	v_mov_b32_e32 v127, v0
	v_add_u32_e32 v159, 0x10000, v143
.LBB0_439:
	s_add_u32 s10, s8, 0x100
	s_addc_u32 s11, s9, 0
	s_add_i32 s48, 0, 0x10000
	s_cmp_eq_u32 s22, 40
	s_cselect_b32 s15, s1, s11
	s_cselect_b32 s14, s0, s10
	s_cselect_b32 s13, s45, s92
	s_cselect_b32 s12, s44, s21
	s_add_i32 s49, 0, 0x14000
	ds_read_b128 v[138:141], v159
	ds_read_b128 v[146:149], v159 offset:1024
	ds_read_b128 v[150:153], v159 offset:2048
	ds_read_b128 v[154:157], v159 offset:3072
	ds_read_b128 v[174:177], v159 offset:16384
	ds_read_b128 v[178:181], v159 offset:17408
	ds_read_b128 v[182:185], v159 offset:18432
	ds_read_b128 v[186:189], v159 offset:19456
	s_add_i32 m0, s29, 0xc000
	ds_read_b128 v[190:193], v145
	ds_read_b128 v[194:197], v145 offset:1024
	ds_read_b128 v[198:201], v145 offset:2048
	ds_read_b128 v[202:205], v145 offset:3072
	ds_read_b128 v[206:209], v145 offset:4096
	ds_read_b128 v[210:213], v145 offset:5120
	ds_read_b128 v[214:217], v145 offset:6144
	global_load_lds_dwordx4 v136, s[8:9]
	s_add_i32 m0, s29, 0xe000
	ds_read_b128 v[238:241], v145 offset:7168
	global_load_lds_dwordx4 v134, s[8:9]
	s_waitcnt vmcnt(8) lgkmcnt(0)
	s_barrier
	v_mfma_f32_16x16x32_bf16 v[124:127], v[138:141], v[190:193], v[124:127]
	v_mfma_f32_16x16x32_bf16 v[120:123], v[150:153], v[190:193], v[120:123]
	v_mfma_f32_16x16x32_bf16 v[108:111], v[138:141], v[198:201], v[108:111]
	v_mfma_f32_16x16x32_bf16 v[104:107], v[150:153], v[198:201], v[104:107]
	v_mfma_f32_16x16x32_bf16 v[92:95], v[138:141], v[206:209], v[92:95]
	v_mfma_f32_16x16x32_bf16 v[88:91], v[150:153], v[206:209], v[88:91]
	v_mfma_f32_16x16x32_bf16 v[76:79], v[138:141], v[214:217], v[76:79]
	v_mfma_f32_16x16x32_bf16 v[72:75], v[150:153], v[214:217], v[72:75]
	v_mfma_f32_16x16x32_bf16 v[124:127], v[146:149], v[194:197], v[124:127]
	v_mfma_f32_16x16x32_bf16 v[120:123], v[154:157], v[194:197], v[120:123]
	v_mfma_f32_16x16x32_bf16 v[108:111], v[146:149], v[202:205], v[108:111]
	v_mfma_f32_16x16x32_bf16 v[104:107], v[154:157], v[202:205], v[104:107]
	v_mfma_f32_16x16x32_bf16 v[92:95], v[146:149], v[210:213], v[92:95]
	v_mfma_f32_16x16x32_bf16 v[88:91], v[154:157], v[210:213], v[88:91]
	v_mfma_f32_16x16x32_bf16 v[76:79], v[146:149], v[238:241], v[76:79]
	v_mfma_f32_16x16x32_bf16 v[72:75], v[154:157], v[238:241], v[72:75]
	v_mfma_f32_16x16x32_bf16 v[116:119], v[174:177], v[190:193], v[116:119]
	v_mfma_f32_16x16x32_bf16 v[112:115], v[182:185], v[190:193], v[112:115]
	v_mfma_f32_16x16x32_bf16 v[100:103], v[174:177], v[198:201], v[100:103]
	v_mfma_f32_16x16x32_bf16 v[96:99], v[182:185], v[198:201], v[96:99]
	v_mfma_f32_16x16x32_bf16 v[84:87], v[174:177], v[206:209], v[84:87]
	v_mfma_f32_16x16x32_bf16 v[80:83], v[182:185], v[206:209], v[80:83]
	v_mfma_f32_16x16x32_bf16 v[68:71], v[174:177], v[214:217], v[68:71]
	v_mfma_f32_16x16x32_bf16 v[64:67], v[182:185], v[214:217], v[64:67]
	v_mfma_f32_16x16x32_bf16 v[116:119], v[178:181], v[194:197], v[116:119]
	v_mfma_f32_16x16x32_bf16 v[112:115], v[186:189], v[194:197], v[112:115]
	v_mfma_f32_16x16x32_bf16 v[100:103], v[178:181], v[202:205], v[100:103]
	v_mfma_f32_16x16x32_bf16 v[96:99], v[186:189], v[202:205], v[96:99]
	v_mfma_f32_16x16x32_bf16 v[84:87], v[178:181], v[210:213], v[84:87]
	v_mfma_f32_16x16x32_bf16 v[80:83], v[186:189], v[210:213], v[80:83]
	v_mfma_f32_16x16x32_bf16 v[68:71], v[178:181], v[238:241], v[68:71]
	v_mfma_f32_16x16x32_bf16 v[64:67], v[186:189], v[238:241], v[64:67]
	s_barrier
	s_add_i32 s8, s48, s28
	s_mov_b32 m0, s8
	ds_read_b128 v[190:193], v145 offset:16384
	ds_read_b128 v[194:197], v145 offset:17408
	ds_read_b128 v[198:201], v145 offset:18432
	ds_read_b128 v[202:205], v145 offset:19456
	global_load_lds_dwordx4 v160, s[12:13]
	s_add_i32 m0, s8, 0x2000
	s_add_u32 s8, s12, 0xb0000
	s_addc_u32 s9, s13, 0
	s_add_i32 s48, s49, s28
	global_load_lds_dwordx4 v132, s[12:13]
	s_mov_b32 m0, s48
	ds_read_b128 v[238:241], v145 offset:23552
	global_load_lds_dwordx4 v160, s[8:9]
	s_add_i32 m0, s48, 0x2000
	ds_read_b128 v[214:217], v145 offset:22528
	global_load_lds_dwordx4 v132, s[8:9]
	s_mov_b32 m0, s29
	ds_read_b128 v[210:213], v145 offset:21504
	global_load_lds_dwordx4 v128, s[14:15]
	s_mov_b32 m0, s30
	ds_read_b128 v[206:209], v145 offset:20480
	global_load_lds_dwordx4 v130, s[14:15]
	s_waitcnt vmcnt(8) lgkmcnt(0)
	s_barrier
	v_mfma_f32_16x16x32_bf16 v[60:63], v[138:141], v[190:193], v[60:63]
	v_mfma_f32_16x16x32_bf16 v[56:59], v[150:153], v[190:193], v[56:59]
	v_mfma_f32_16x16x32_bf16 v[44:47], v[138:141], v[198:201], v[44:47]
	v_mfma_f32_16x16x32_bf16 v[40:43], v[150:153], v[198:201], v[40:43]
	v_mfma_f32_16x16x32_bf16 v[28:31], v[138:141], v[206:209], v[28:31]
	v_mfma_f32_16x16x32_bf16 v[24:27], v[150:153], v[206:209], v[24:27]
	v_mfma_f32_16x16x32_bf16 v[12:15], v[138:141], v[214:217], v[12:15]
	v_mfma_f32_16x16x32_bf16 v[8:11], v[150:153], v[214:217], v[8:11]
	v_mfma_f32_16x16x32_bf16 v[60:63], v[146:149], v[194:197], v[60:63]
	v_mfma_f32_16x16x32_bf16 v[56:59], v[154:157], v[194:197], v[56:59]
	v_mfma_f32_16x16x32_bf16 v[44:47], v[146:149], v[202:205], v[44:47]
	v_mfma_f32_16x16x32_bf16 v[40:43], v[154:157], v[202:205], v[40:43]
	v_mfma_f32_16x16x32_bf16 v[28:31], v[146:149], v[210:213], v[28:31]
	v_mfma_f32_16x16x32_bf16 v[24:27], v[154:157], v[210:213], v[24:27]
	v_mfma_f32_16x16x32_bf16 v[12:15], v[146:149], v[238:241], v[12:15]
	v_mfma_f32_16x16x32_bf16 v[8:11], v[154:157], v[238:241], v[8:11]
	v_mfma_f32_16x16x32_bf16 v[52:55], v[174:177], v[190:193], v[52:55]
	v_mfma_f32_16x16x32_bf16 v[48:51], v[182:185], v[190:193], v[48:51]
	v_mfma_f32_16x16x32_bf16 v[36:39], v[174:177], v[198:201], v[36:39]
	v_mfma_f32_16x16x32_bf16 v[32:35], v[182:185], v[198:201], v[32:35]
	v_mfma_f32_16x16x32_bf16 v[20:23], v[174:177], v[206:209], v[20:23]
	v_mfma_f32_16x16x32_bf16 v[16:19], v[182:185], v[206:209], v[16:19]
	v_mfma_f32_16x16x32_bf16 v[4:7], v[174:177], v[214:217], v[4:7]
	v_mfma_f32_16x16x32_bf16 v[0:3], v[182:185], v[214:217], v[0:3]
	v_mfma_f32_16x16x32_bf16 v[52:55], v[178:181], v[194:197], v[52:55]
	v_mfma_f32_16x16x32_bf16 v[48:51], v[186:189], v[194:197], v[48:51]
	v_mfma_f32_16x16x32_bf16 v[36:39], v[178:181], v[202:205], v[36:39]
	v_mfma_f32_16x16x32_bf16 v[32:35], v[186:189], v[202:205], v[32:35]
	v_mfma_f32_16x16x32_bf16 v[20:23], v[178:181], v[210:213], v[20:23]
	v_mfma_f32_16x16x32_bf16 v[16:19], v[186:189], v[210:213], v[16:19]
	v_mfma_f32_16x16x32_bf16 v[4:7], v[178:181], v[238:241], v[4:7]
	v_mfma_f32_16x16x32_bf16 v[0:3], v[186:189], v[238:241], v[0:3]
	s_barrier
	s_add_i32 s48, 0, 0x18000
	s_add_i32 s49, 0, 0x1c000
	ds_read_b128 v[138:141], v159 offset:32768
	ds_read_b128 v[146:149], v159 offset:33792
	ds_read_b128 v[150:153], v159 offset:34816
	ds_read_b128 v[154:157], v159 offset:35840
	ds_read_b128 v[174:177], v159 offset:49152
	ds_read_b128 v[178:181], v159 offset:50176
	ds_read_b128 v[182:185], v159 offset:51200
	ds_read_b128 v[186:189], v159 offset:52224
	s_add_u32 s8, s14, 0xb0000
	s_addc_u32 s9, s15, 0
	s_mov_b32 m0, s31
	ds_read_b128 v[190:193], v145 offset:32768
	ds_read_b128 v[194:197], v145 offset:33792
	ds_read_b128 v[198:201], v145 offset:34816
	ds_read_b128 v[202:205], v145 offset:35840
	ds_read_b128 v[206:209], v145 offset:36864
	ds_read_b128 v[210:213], v145 offset:37888
	ds_read_b128 v[214:217], v145 offset:38912
	global_load_lds_dwordx4 v128, s[8:9]
	s_mov_b32 m0, s33
	ds_read_b128 v[238:241], v145 offset:39936
	global_load_lds_dwordx4 v130, s[8:9]
	s_waitcnt vmcnt(8) lgkmcnt(0)
	s_barrier
	v_mfma_f32_16x16x32_bf16 v[124:127], v[138:141], v[190:193], v[124:127]
	v_mfma_f32_16x16x32_bf16 v[120:123], v[150:153], v[190:193], v[120:123]
	v_mfma_f32_16x16x32_bf16 v[108:111], v[138:141], v[198:201], v[108:111]
	v_mfma_f32_16x16x32_bf16 v[104:107], v[150:153], v[198:201], v[104:107]
	v_mfma_f32_16x16x32_bf16 v[92:95], v[138:141], v[206:209], v[92:95]
	v_mfma_f32_16x16x32_bf16 v[88:91], v[150:153], v[206:209], v[88:91]
	v_mfma_f32_16x16x32_bf16 v[76:79], v[138:141], v[214:217], v[76:79]
	v_mfma_f32_16x16x32_bf16 v[72:75], v[150:153], v[214:217], v[72:75]
	v_mfma_f32_16x16x32_bf16 v[124:127], v[146:149], v[194:197], v[124:127]
	v_mfma_f32_16x16x32_bf16 v[120:123], v[154:157], v[194:197], v[120:123]
	v_mfma_f32_16x16x32_bf16 v[108:111], v[146:149], v[202:205], v[108:111]
	v_mfma_f32_16x16x32_bf16 v[104:107], v[154:157], v[202:205], v[104:107]
	v_mfma_f32_16x16x32_bf16 v[92:95], v[146:149], v[210:213], v[92:95]
	v_mfma_f32_16x16x32_bf16 v[88:91], v[154:157], v[210:213], v[88:91]
	v_mfma_f32_16x16x32_bf16 v[76:79], v[146:149], v[238:241], v[76:79]
	v_mfma_f32_16x16x32_bf16 v[72:75], v[154:157], v[238:241], v[72:75]
	v_mfma_f32_16x16x32_bf16 v[116:119], v[174:177], v[190:193], v[116:119]
	v_mfma_f32_16x16x32_bf16 v[112:115], v[182:185], v[190:193], v[112:115]
	v_mfma_f32_16x16x32_bf16 v[100:103], v[174:177], v[198:201], v[100:103]
	v_mfma_f32_16x16x32_bf16 v[96:99], v[182:185], v[198:201], v[96:99]
	v_mfma_f32_16x16x32_bf16 v[84:87], v[174:177], v[206:209], v[84:87]
	v_mfma_f32_16x16x32_bf16 v[80:83], v[182:185], v[206:209], v[80:83]
	v_mfma_f32_16x16x32_bf16 v[68:71], v[174:177], v[214:217], v[68:71]
	v_mfma_f32_16x16x32_bf16 v[64:67], v[182:185], v[214:217], v[64:67]
	v_mfma_f32_16x16x32_bf16 v[116:119], v[178:181], v[194:197], v[116:119]
	v_mfma_f32_16x16x32_bf16 v[112:115], v[186:189], v[194:197], v[112:115]
	v_mfma_f32_16x16x32_bf16 v[100:103], v[178:181], v[202:205], v[100:103]
	v_mfma_f32_16x16x32_bf16 v[96:99], v[186:189], v[202:205], v[96:99]
	v_mfma_f32_16x16x32_bf16 v[84:87], v[178:181], v[210:213], v[84:87]
	v_mfma_f32_16x16x32_bf16 v[80:83], v[186:189], v[210:213], v[80:83]
	v_mfma_f32_16x16x32_bf16 v[68:71], v[178:181], v[238:241], v[68:71]
	v_mfma_f32_16x16x32_bf16 v[64:67], v[186:189], v[238:241], v[64:67]
	s_barrier
	s_add_i32 s8, s48, s28
	s_add_i32 m0, s8, 0xffffff80
	ds_read_b128 v[190:193], v145 offset:49152
	ds_read_b128 v[194:197], v145 offset:50176
	ds_read_b128 v[198:201], v145 offset:51200
	ds_read_b128 v[202:205], v145 offset:52224
	global_load_lds_dwordx4 v160, s[12:13] offset:128
	s_add_i32 m0, s8, 0x1f80
	s_add_u32 s8, s12, 0xb0080
	s_addc_u32 s9, s13, 0
	global_load_lds_dwordx4 v132, s[12:13] offset:128
	s_add_i32 s12, s49, s28
	s_mov_b32 m0, s12
	ds_read_b128 v[238:241], v145 offset:56320
	global_load_lds_dwordx4 v160, s[8:9]
	s_add_i32 m0, s12, 0x2000
	ds_read_b128 v[214:217], v145 offset:55296
	global_load_lds_dwordx4 v132, s[8:9]
	s_add_i32 m0, s34, 0xffffff80
	ds_read_b128 v[210:213], v145 offset:54272
	global_load_lds_dwordx4 v128, s[14:15] offset:128
	s_add_i32 m0, s35, 0xffffff80
	ds_read_b128 v[206:209], v145 offset:53248
	global_load_lds_dwordx4 v130, s[14:15] offset:128
	s_waitcnt vmcnt(8) lgkmcnt(0)
	s_barrier
	v_mfma_f32_16x16x32_bf16 v[60:63], v[138:141], v[190:193], v[60:63]
	v_mfma_f32_16x16x32_bf16 v[56:59], v[150:153], v[190:193], v[56:59]
	v_mfma_f32_16x16x32_bf16 v[44:47], v[138:141], v[198:201], v[44:47]
	v_mfma_f32_16x16x32_bf16 v[40:43], v[150:153], v[198:201], v[40:43]
	v_mfma_f32_16x16x32_bf16 v[28:31], v[138:141], v[206:209], v[28:31]
	v_mfma_f32_16x16x32_bf16 v[24:27], v[150:153], v[206:209], v[24:27]
	v_mfma_f32_16x16x32_bf16 v[12:15], v[138:141], v[214:217], v[12:15]
	v_mfma_f32_16x16x32_bf16 v[8:11], v[150:153], v[214:217], v[8:11]
	v_mfma_f32_16x16x32_bf16 v[60:63], v[146:149], v[194:197], v[60:63]
	v_mfma_f32_16x16x32_bf16 v[56:59], v[154:157], v[194:197], v[56:59]
	v_mfma_f32_16x16x32_bf16 v[44:47], v[146:149], v[202:205], v[44:47]
	v_mfma_f32_16x16x32_bf16 v[40:43], v[154:157], v[202:205], v[40:43]
	v_mfma_f32_16x16x32_bf16 v[28:31], v[146:149], v[210:213], v[28:31]
	v_mfma_f32_16x16x32_bf16 v[24:27], v[154:157], v[210:213], v[24:27]
	v_mfma_f32_16x16x32_bf16 v[12:15], v[146:149], v[238:241], v[12:15]
	v_mfma_f32_16x16x32_bf16 v[8:11], v[154:157], v[238:241], v[8:11]
	v_mfma_f32_16x16x32_bf16 v[52:55], v[174:177], v[190:193], v[52:55]
	v_mfma_f32_16x16x32_bf16 v[48:51], v[182:185], v[190:193], v[48:51]
	v_mfma_f32_16x16x32_bf16 v[36:39], v[174:177], v[198:201], v[36:39]
	v_mfma_f32_16x16x32_bf16 v[32:35], v[182:185], v[198:201], v[32:35]
	v_mfma_f32_16x16x32_bf16 v[20:23], v[174:177], v[206:209], v[20:23]
	v_mfma_f32_16x16x32_bf16 v[16:19], v[182:185], v[206:209], v[16:19]
	v_mfma_f32_16x16x32_bf16 v[4:7], v[174:177], v[214:217], v[4:7]
	v_mfma_f32_16x16x32_bf16 v[0:3], v[182:185], v[214:217], v[0:3]
	v_mfma_f32_16x16x32_bf16 v[52:55], v[178:181], v[194:197], v[52:55]
	v_mfma_f32_16x16x32_bf16 v[48:51], v[186:189], v[194:197], v[48:51]
	v_mfma_f32_16x16x32_bf16 v[36:39], v[178:181], v[202:205], v[36:39]
	v_mfma_f32_16x16x32_bf16 v[32:35], v[186:189], v[202:205], v[32:35]
	v_mfma_f32_16x16x32_bf16 v[20:23], v[178:181], v[210:213], v[20:23]
	v_mfma_f32_16x16x32_bf16 v[16:19], v[186:189], v[210:213], v[16:19]
	v_mfma_f32_16x16x32_bf16 v[4:7], v[178:181], v[238:241], v[4:7]
	v_mfma_f32_16x16x32_bf16 v[0:3], v[186:189], v[238:241], v[0:3]
	s_barrier
	s_add_i32 s22, s22, 2
	s_add_u32 s21, s21, 0x100
	s_addc_u32 s92, s92, 0
	s_cmp_gt_u32 s22, 41
	s_mov_b64 s[8:9], s[10:11]
	s_cbranch_scc0 .LBB0_439
	v_lshl_add_u32 v140, s20, 8, v142
	v_lshl_or_b32 v138, s91, 8, v144
	v_lshlrev_b32_e32 v141, 11, v140
	v_lshl_add_u32 v138, v138, 1, v141
	v_lshlrev_b32_e32 v139, 3, v140
	s_mov_b64 s[8:9], s[4:5]
	global_load_dwordx4 v[146:149], v138, s[8:9]
	global_load_dwordx4 v[150:153], v138, s[8:9] offset:256
	s_add_u32 s8, s8, 0x8000
	s_addc_u32 s9, s9, 0
	global_load_dwordx4 v[154:157], v138, s[8:9]
	global_load_dwordx4 v[162:165], v138, s[8:9] offset:256
	s_add_u32 s8, s8, 0x8000
	s_addc_u32 s9, s9, 0
	global_load_dwordx4 v[166:169], v138, s[8:9]
	global_load_dwordx4 v[174:177], v138, s[8:9] offset:256
	s_add_u32 s8, s8, 0x8000
	s_addc_u32 s9, s9, 0
	global_load_dwordx4 v[178:181], v138, s[8:9]
	global_load_dwordx4 v[182:185], v138, s[8:9] offset:256
	s_add_u32 s8, s8, 0x28000
	s_addc_u32 s9, s9, 0
	global_load_dwordx4 v[186:189], v138, s[8:9]
	global_load_dwordx4 v[190:193], v138, s[8:9] offset:256
	s_add_u32 s8, s8, 0x8000
	s_addc_u32 s9, s9, 0
	global_load_dwordx4 v[194:197], v138, s[8:9]
	global_load_dwordx4 v[198:201], v138, s[8:9] offset:256
	s_add_u32 s8, s8, 0x8000
	s_addc_u32 s9, s9, 0
	global_load_dwordx4 v[202:205], v138, s[8:9]
	global_load_dwordx4 v[206:209], v138, s[8:9] offset:256
	s_add_u32 s8, s8, 0x8000
	s_addc_u32 s9, s9, 0
	global_load_dwordx4 v[210:213], v138, s[8:9]
	global_load_dwordx4 v[214:217], v138, s[8:9] offset:256
	s_and_b64 vcc, exec, s[36:37]
	s_cbranch_vccz .LBB0_442
	s_barrier

.LBB0_473:
	s_ashr_i32 s37, s36, 31
	s_lshl_b64 s[14:15], s[36:37], 19
	s_add_u32 s44, s24, s14
	s_addc_u32 s45, s25, s15
	s_and_b64 s[14:15], s[38:39], exec
	s_cselect_b32 s20, s45, s13
	s_cselect_b32 s37, s44, s12
	s_ashr_i32 s41, s40, 31
	s_lshl_b64 s[14:15], s[40:41], 19
	s_add_u32 s46, s26, s14
	s_addc_u32 s47, s27, s15
	s_and_b64 s[14:15], s[38:39], exec
	s_cselect_b32 s41, s47, s11
	s_cselect_b32 s91, s46, s10
	s_add_u32 s92, s10, 0x100
	s_addc_u32 s93, s11, 0
	s_add_u32 s10, s12, 0x40080
	v_mov_b32_e32 v4, 0
	s_addc_u32 s11, s13, 0
	s_mov_b32 s21, -2
	v_mov_b32_e32 v5, v4
	v_mov_b32_e32 v6, v4
	v_mov_b32_e32 v7, v4
	v_mov_b32_e32 v8, v4
	v_mov_b32_e32 v9, v4
	v_mov_b32_e32 v10, v4
	v_mov_b32_e32 v11, v4
	v_mov_b32_e32 v20, v4
	v_mov_b32_e32 v21, v4
	v_mov_b32_e32 v22, v4
	v_mov_b32_e32 v23, v4
	v_mov_b32_e32 v24, v4
	v_mov_b32_e32 v25, v4
	v_mov_b32_e32 v26, v4
	v_mov_b32_e32 v27, v4
	v_mov_b32_e32 v36, v4
	v_mov_b32_e32 v37, v4
	v_mov_b32_e32 v38, v4
	v_mov_b32_e32 v39, v4
	v_mov_b32_e32 v40, v4
	v_mov_b32_e32 v41, v4
	v_mov_b32_e32 v42, v4
	v_mov_b32_e32 v43, v4
	v_mov_b32_e32 v52, v4
	v_mov_b32_e32 v53, v4
	v_mov_b32_e32 v54, v4
	v_mov_b32_e32 v55, v4
	v_mov_b32_e32 v56, v4
	v_mov_b32_e32 v57, v4
	v_mov_b32_e32 v58, v4
	v_mov_b32_e32 v59, v4
	v_mov_b32_e32 v0, v4
	v_mov_b32_e32 v1, v4
	v_mov_b32_e32 v2, v4
	v_mov_b32_e32 v3, v4
	v_mov_b32_e32 v12, v4
	v_mov_b32_e32 v13, v4
	v_mov_b32_e32 v14, v4
	v_mov_b32_e32 v15, v4
	v_mov_b32_e32 v16, v4
	v_mov_b32_e32 v17, v4
	v_mov_b32_e32 v18, v4
	v_mov_b32_e32 v19, v4
	v_mov_b32_e32 v28, v4
	v_mov_b32_e32 v29, v4
	v_mov_b32_e32 v30, v4
	v_mov_b32_e32 v31, v4
	v_mov_b32_e32 v32, v4
	v_mov_b32_e32 v33, v4
	v_mov_b32_e32 v34, v4
	v_mov_b32_e32 v35, v4
	v_mov_b32_e32 v44, v4
	v_mov_b32_e32 v45, v4
	v_mov_b32_e32 v46, v4
	v_mov_b32_e32 v47, v4
	v_mov_b32_e32 v48, v4
	v_mov_b32_e32 v49, v4
	v_mov_b32_e32 v50, v4
	v_mov_b32_e32 v51, v4
	v_mov_b32_e32 v60, v4
	v_mov_b32_e32 v61, v4
	v_mov_b32_e32 v62, v4
	v_mov_b32_e32 v63, v4
	v_mov_b32_e32 v68, v4
	v_mov_b32_e32 v69, v4
	v_mov_b32_e32 v70, v4
	v_mov_b32_e32 v71, v4
	v_mov_b32_e32 v72, v4
	v_mov_b32_e32 v73, v4
	v_mov_b32_e32 v74, v4
	v_mov_b32_e32 v75, v4
	v_mov_b32_e32 v80, v4
	v_mov_b32_e32 v81, v4
	v_mov_b32_e32 v82, v4
	v_mov_b32_e32 v83, v4
	v_mov_b32_e32 v88, v4
	v_mov_b32_e32 v89, v4
	v_mov_b32_e32 v90, v4
	v_mov_b32_e32 v91, v4
	v_mov_b32_e32 v96, v4
	v_mov_b32_e32 v97, v4
	v_mov_b32_e32 v98, v4
	v_mov_b32_e32 v99, v4
	v_mov_b32_e32 v104, v4
	v_mov_b32_e32 v105, v4
	v_mov_b32_e32 v106, v4
	v_mov_b32_e32 v107, v4
	v_mov_b32_e32 v112, v4
	v_mov_b32_e32 v113, v4
	v_mov_b32_e32 v114, v4
	v_mov_b32_e32 v115, v4
	v_mov_b32_e32 v120, v4
	v_mov_b32_e32 v121, v4
	v_mov_b32_e32 v122, v4
	v_mov_b32_e32 v123, v4
	v_mov_b32_e32 v64, v4
	v_mov_b32_e32 v65, v4
	v_mov_b32_e32 v66, v4
	v_mov_b32_e32 v67, v4
	v_mov_b32_e32 v76, v4
	v_mov_b32_e32 v77, v4
	v_mov_b32_e32 v78, v4
	v_mov_b32_e32 v79, v4
	v_mov_b32_e32 v84, v4
	v_mov_b32_e32 v85, v4
	v_mov_b32_e32 v86, v4
	v_mov_b32_e32 v87, v4
	v_mov_b32_e32 v92, v4
	v_mov_b32_e32 v93, v4
	v_mov_b32_e32 v94, v4
	v_mov_b32_e32 v95, v4
	v_mov_b32_e32 v100, v4
	v_mov_b32_e32 v101, v4
	v_mov_b32_e32 v102, v4
	v_mov_b32_e32 v103, v4
	v_mov_b32_e32 v108, v4
	v_mov_b32_e32 v109, v4
	v_mov_b32_e32 v110, v4
	v_mov_b32_e32 v111, v4
	v_mov_b32_e32 v116, v4
	v_mov_b32_e32 v117, v4
	v_mov_b32_e32 v118, v4
	v_mov_b32_e32 v119, v4
	v_mov_b32_e32 v124, v4
	v_mov_b32_e32 v125, v4
	v_mov_b32_e32 v126, v4
	v_mov_b32_e32 v127, v4
	v_add_u32_e32 v159, 0x10000, v147
.LBB0_474:
	s_add_u32 s12, s10, 0xfffc0080
	s_addc_u32 s13, s11, -1
	s_add_i32 s22, 0, 0x10000
	s_cmp_eq_u32 s21, 12
	s_cselect_b32 s15, s20, s13
	s_cselect_b32 s14, s37, s12
	s_cselect_b32 s13, s41, s93
	s_cselect_b32 s12, s91, s92
	s_add_i32 s48, 0, 0x14000
	ds_read_b128 v[138:141], v159
	ds_read_b128 v[142:145], v159 offset:1024
	ds_read_b128 v[150:153], v159 offset:2048
	ds_read_b128 v[154:157], v159 offset:3072
	ds_read_b128 v[174:177], v159 offset:16384
	ds_read_b128 v[178:181], v159 offset:17408
	ds_read_b128 v[182:185], v159 offset:18432
	ds_read_b128 v[186:189], v159 offset:19456
	s_add_i32 m0, s30, 0xc000
	ds_read_b128 v[190:193], v149
	ds_read_b128 v[194:197], v149 offset:1024
	ds_read_b128 v[198:201], v149 offset:2048
	ds_read_b128 v[202:205], v149 offset:3072
	ds_read_b128 v[206:209], v149 offset:4096
	ds_read_b128 v[210:213], v149 offset:5120
	ds_read_b128 v[214:217], v149 offset:6144
	global_load_lds_dwordx4 v136, s[10:11]
	s_add_i32 m0, s30, 0xe000
	ds_read_b128 v[238:241], v149 offset:7168
	global_load_lds_dwordx4 v134, s[10:11]
	s_waitcnt vmcnt(8) lgkmcnt(0)
	s_barrier
	v_mfma_f32_16x16x32_bf16 v[124:127], v[138:141], v[190:193], v[124:127]
	v_mfma_f32_16x16x32_bf16 v[116:119], v[150:153], v[190:193], v[116:119]
	v_mfma_f32_16x16x32_bf16 v[108:111], v[138:141], v[198:201], v[108:111]
	v_mfma_f32_16x16x32_bf16 v[100:103], v[150:153], v[198:201], v[100:103]
	v_mfma_f32_16x16x32_bf16 v[92:95], v[138:141], v[206:209], v[92:95]
	v_mfma_f32_16x16x32_bf16 v[84:87], v[150:153], v[206:209], v[84:87]
	v_mfma_f32_16x16x32_bf16 v[76:79], v[138:141], v[214:217], v[76:79]
	v_mfma_f32_16x16x32_bf16 v[64:67], v[150:153], v[214:217], v[64:67]
	v_mfma_f32_16x16x32_bf16 v[124:127], v[142:145], v[194:197], v[124:127]
	v_mfma_f32_16x16x32_bf16 v[116:119], v[154:157], v[194:197], v[116:119]
	v_mfma_f32_16x16x32_bf16 v[108:111], v[142:145], v[202:205], v[108:111]
	v_mfma_f32_16x16x32_bf16 v[100:103], v[154:157], v[202:205], v[100:103]
	v_mfma_f32_16x16x32_bf16 v[92:95], v[142:145], v[210:213], v[92:95]
	v_mfma_f32_16x16x32_bf16 v[84:87], v[154:157], v[210:213], v[84:87]
	v_mfma_f32_16x16x32_bf16 v[76:79], v[142:145], v[238:241], v[76:79]
	v_mfma_f32_16x16x32_bf16 v[64:67], v[154:157], v[238:241], v[64:67]
	v_mfma_f32_16x16x32_bf16 v[120:123], v[174:177], v[190:193], v[120:123]
	v_mfma_f32_16x16x32_bf16 v[112:115], v[182:185], v[190:193], v[112:115]
	v_mfma_f32_16x16x32_bf16 v[104:107], v[174:177], v[198:201], v[104:107]
	v_mfma_f32_16x16x32_bf16 v[96:99], v[182:185], v[198:201], v[96:99]
	v_mfma_f32_16x16x32_bf16 v[88:91], v[174:177], v[206:209], v[88:91]
	v_mfma_f32_16x16x32_bf16 v[80:83], v[182:185], v[206:209], v[80:83]
	v_mfma_f32_16x16x32_bf16 v[72:75], v[174:177], v[214:217], v[72:75]
	v_mfma_f32_16x16x32_bf16 v[68:71], v[182:185], v[214:217], v[68:71]
	v_mfma_f32_16x16x32_bf16 v[120:123], v[178:181], v[194:197], v[120:123]
	v_mfma_f32_16x16x32_bf16 v[112:115], v[186:189], v[194:197], v[112:115]
	v_mfma_f32_16x16x32_bf16 v[104:107], v[178:181], v[202:205], v[104:107]
	v_mfma_f32_16x16x32_bf16 v[96:99], v[186:189], v[202:205], v[96:99]
	v_mfma_f32_16x16x32_bf16 v[88:91], v[178:181], v[210:213], v[88:91]
	v_mfma_f32_16x16x32_bf16 v[80:83], v[186:189], v[210:213], v[80:83]
	v_mfma_f32_16x16x32_bf16 v[72:75], v[178:181], v[238:241], v[72:75]
	v_mfma_f32_16x16x32_bf16 v[68:71], v[186:189], v[238:241], v[68:71]
	s_barrier
	s_add_i32 s22, s22, s28
	s_mov_b32 m0, s22
	ds_read_b128 v[190:193], v149 offset:16384
	ds_read_b128 v[194:197], v149 offset:17408
	ds_read_b128 v[198:201], v149 offset:18432
	ds_read_b128 v[202:205], v149 offset:19456
	global_load_lds_dwordx4 v160, s[12:13]
	s_add_i32 m0, s22, 0x2000
	s_add_u32 s96, s12, 0x40000
	s_addc_u32 s97, s13, 0
	s_add_i32 s22, s48, s28
	global_load_lds_dwordx4 v128, s[12:13]
	s_mov_b32 m0, s22
	ds_read_b128 v[238:241], v149 offset:23552
	global_load_lds_dwordx4 v160, s[96:97]
	s_add_i32 m0, s22, 0x2000
	ds_read_b128 v[214:217], v149 offset:22528
	global_load_lds_dwordx4 v128, s[96:97]
	s_mov_b32 m0, s30
	ds_read_b128 v[210:213], v149 offset:21504
	global_load_lds_dwordx4 v132, s[14:15]
	s_mov_b32 m0, s31
	ds_read_b128 v[206:209], v149 offset:20480
	global_load_lds_dwordx4 v130, s[14:15]
	s_waitcnt vmcnt(8) lgkmcnt(0)
	s_barrier
	v_mfma_f32_16x16x32_bf16 v[60:63], v[138:141], v[190:193], v[60:63]
	v_mfma_f32_16x16x32_bf16 v[48:51], v[150:153], v[190:193], v[48:51]
	v_mfma_f32_16x16x32_bf16 v[44:47], v[138:141], v[198:201], v[44:47]
	v_mfma_f32_16x16x32_bf16 v[32:35], v[150:153], v[198:201], v[32:35]
	v_mfma_f32_16x16x32_bf16 v[28:31], v[138:141], v[206:209], v[28:31]
	v_mfma_f32_16x16x32_bf16 v[16:19], v[150:153], v[206:209], v[16:19]
	v_mfma_f32_16x16x32_bf16 v[12:15], v[138:141], v[214:217], v[12:15]
	v_mfma_f32_16x16x32_bf16 v[0:3], v[150:153], v[214:217], v[0:3]
	v_mfma_f32_16x16x32_bf16 v[60:63], v[142:145], v[194:197], v[60:63]
	v_mfma_f32_16x16x32_bf16 v[48:51], v[154:157], v[194:197], v[48:51]
	v_mfma_f32_16x16x32_bf16 v[44:47], v[142:145], v[202:205], v[44:47]
	v_mfma_f32_16x16x32_bf16 v[32:35], v[154:157], v[202:205], v[32:35]
	v_mfma_f32_16x16x32_bf16 v[28:31], v[142:145], v[210:213], v[28:31]
	v_mfma_f32_16x16x32_bf16 v[16:19], v[154:157], v[210:213], v[16:19]
	v_mfma_f32_16x16x32_bf16 v[12:15], v[142:145], v[238:241], v[12:15]
	v_mfma_f32_16x16x32_bf16 v[0:3], v[154:157], v[238:241], v[0:3]
	v_mfma_f32_16x16x32_bf16 v[56:59], v[174:177], v[190:193], v[56:59]
	v_mfma_f32_16x16x32_bf16 v[52:55], v[182:185], v[190:193], v[52:55]
	v_mfma_f32_16x16x32_bf16 v[40:43], v[174:177], v[198:201], v[40:43]
	v_mfma_f32_16x16x32_bf16 v[36:39], v[182:185], v[198:201], v[36:39]
	v_mfma_f32_16x16x32_bf16 v[24:27], v[174:177], v[206:209], v[24:27]
	v_mfma_f32_16x16x32_bf16 v[20:23], v[182:185], v[206:209], v[20:23]
	v_mfma_f32_16x16x32_bf16 v[8:11], v[174:177], v[214:217], v[8:11]
	v_mfma_f32_16x16x32_bf16 v[4:7], v[182:185], v[214:217], v[4:7]
	v_mfma_f32_16x16x32_bf16 v[56:59], v[178:181], v[194:197], v[56:59]
	v_mfma_f32_16x16x32_bf16 v[52:55], v[186:189], v[194:197], v[52:55]
	v_mfma_f32_16x16x32_bf16 v[40:43], v[178:181], v[202:205], v[40:43]
	v_mfma_f32_16x16x32_bf16 v[36:39], v[186:189], v[202:205], v[36:39]
	v_mfma_f32_16x16x32_bf16 v[24:27], v[178:181], v[210:213], v[24:27]
	v_mfma_f32_16x16x32_bf16 v[20:23], v[186:189], v[210:213], v[20:23]
	v_mfma_f32_16x16x32_bf16 v[8:11], v[178:181], v[238:241], v[8:11]
	v_mfma_f32_16x16x32_bf16 v[4:7], v[186:189], v[238:241], v[4:7]
	s_barrier
	s_add_i32 s22, 0, 0x18000
	s_add_i32 s48, 0, 0x1c000
	ds_read_b128 v[138:141], v159 offset:32768
	ds_read_b128 v[142:145], v159 offset:33792
	ds_read_b128 v[150:153], v159 offset:34816
	ds_read_b128 v[154:157], v159 offset:35840
	ds_read_b128 v[174:177], v159 offset:49152
	ds_read_b128 v[178:181], v159 offset:50176
	ds_read_b128 v[182:185], v159 offset:51200
	ds_read_b128 v[186:189], v159 offset:52224
	s_mov_b64 s[100:101], s[14:15]
	s_add_u32 s14, s14, 0x40000
	s_addc_u32 s15, s15, 0
	s_mov_b32 m0, s33
	ds_read_b128 v[190:193], v149 offset:32768
	ds_read_b128 v[194:197], v149 offset:33792
	ds_read_b128 v[198:201], v149 offset:34816
	ds_read_b128 v[202:205], v149 offset:35840
	ds_read_b128 v[206:209], v149 offset:36864
	ds_read_b128 v[210:213], v149 offset:37888
	ds_read_b128 v[214:217], v149 offset:38912
	global_load_lds_dwordx4 v132, s[14:15]
	s_mov_b32 m0, s34
	ds_read_b128 v[238:241], v149 offset:39936
	global_load_lds_dwordx4 v130, s[14:15]
	s_waitcnt vmcnt(8) lgkmcnt(0)
	s_barrier
	v_mfma_f32_16x16x32_bf16 v[124:127], v[138:141], v[190:193], v[124:127]
	v_mfma_f32_16x16x32_bf16 v[116:119], v[150:153], v[190:193], v[116:119]
	v_mfma_f32_16x16x32_bf16 v[108:111], v[138:141], v[198:201], v[108:111]
	v_mfma_f32_16x16x32_bf16 v[100:103], v[150:153], v[198:201], v[100:103]
	v_mfma_f32_16x16x32_bf16 v[92:95], v[138:141], v[206:209], v[92:95]
	v_mfma_f32_16x16x32_bf16 v[84:87], v[150:153], v[206:209], v[84:87]
	v_mfma_f32_16x16x32_bf16 v[76:79], v[138:141], v[214:217], v[76:79]
	v_mfma_f32_16x16x32_bf16 v[64:67], v[150:153], v[214:217], v[64:67]
	v_mfma_f32_16x16x32_bf16 v[124:127], v[142:145], v[194:197], v[124:127]
	v_mfma_f32_16x16x32_bf16 v[116:119], v[154:157], v[194:197], v[116:119]
	v_mfma_f32_16x16x32_bf16 v[108:111], v[142:145], v[202:205], v[108:111]
	v_mfma_f32_16x16x32_bf16 v[100:103], v[154:157], v[202:205], v[100:103]
	v_mfma_f32_16x16x32_bf16 v[92:95], v[142:145], v[210:213], v[92:95]
	v_mfma_f32_16x16x32_bf16 v[84:87], v[154:157], v[210:213], v[84:87]
	v_mfma_f32_16x16x32_bf16 v[76:79], v[142:145], v[238:241], v[76:79]
	v_mfma_f32_16x16x32_bf16 v[64:67], v[154:157], v[238:241], v[64:67]
	v_mfma_f32_16x16x32_bf16 v[120:123], v[174:177], v[190:193], v[120:123]
	v_mfma_f32_16x16x32_bf16 v[112:115], v[182:185], v[190:193], v[112:115]
	v_mfma_f32_16x16x32_bf16 v[104:107], v[174:177], v[198:201], v[104:107]
	v_mfma_f32_16x16x32_bf16 v[96:99], v[182:185], v[198:201], v[96:99]
	v_mfma_f32_16x16x32_bf16 v[88:91], v[174:177], v[206:209], v[88:91]
	v_mfma_f32_16x16x32_bf16 v[80:83], v[182:185], v[206:209], v[80:83]
	v_mfma_f32_16x16x32_bf16 v[72:75], v[174:177], v[214:217], v[72:75]
	v_mfma_f32_16x16x32_bf16 v[68:71], v[182:185], v[214:217], v[68:71]
	v_mfma_f32_16x16x32_bf16 v[120:123], v[178:181], v[194:197], v[120:123]
	v_mfma_f32_16x16x32_bf16 v[112:115], v[186:189], v[194:197], v[112:115]
	v_mfma_f32_16x16x32_bf16 v[104:107], v[178:181], v[202:205], v[104:107]
	v_mfma_f32_16x16x32_bf16 v[96:99], v[186:189], v[202:205], v[96:99]
	v_mfma_f32_16x16x32_bf16 v[88:91], v[178:181], v[210:213], v[88:91]
	v_mfma_f32_16x16x32_bf16 v[80:83], v[186:189], v[210:213], v[80:83]
	v_mfma_f32_16x16x32_bf16 v[72:75], v[178:181], v[238:241], v[72:75]
	v_mfma_f32_16x16x32_bf16 v[68:71], v[186:189], v[238:241], v[68:71]
	s_barrier
	s_add_i32 s14, s22, s28
	s_add_i32 m0, s14, 0xffffff80
	ds_read_b128 v[190:193], v149 offset:49152
	ds_read_b128 v[194:197], v149 offset:50176
	ds_read_b128 v[198:201], v149 offset:51200
	global_load_lds_dwordx4 v160, s[12:13] offset:128
	s_add_i32 m0, s14, 0x1f80
	ds_read_b128 v[238:241], v149 offset:56320
	global_load_lds_dwordx4 v128, s[12:13] offset:128
	s_add_u32 s12, s12, 0x40080
	s_addc_u32 s13, s13, 0
	s_add_i32 s14, s48, s28
	s_mov_b32 m0, s14
	ds_read_b128 v[214:217], v149 offset:55296
	global_load_lds_dwordx4 v160, s[12:13]
	s_add_i32 m0, s14, 0x2000
	ds_read_b128 v[210:213], v149 offset:54272
	global_load_lds_dwordx4 v128, s[12:13]
	s_add_i32 m0, s35, 0xffffff80
	ds_read_b128 v[206:209], v149 offset:53248
	global_load_lds_dwordx4 v132, s[100:101] offset:128
	s_add_i32 m0, s90, 0xffffff80
	ds_read_b128 v[202:205], v149 offset:52224
	global_load_lds_dwordx4 v130, s[100:101] offset:128
	s_waitcnt vmcnt(8) lgkmcnt(0)
	s_barrier
	v_mfma_f32_16x16x32_bf16 v[60:63], v[138:141], v[190:193], v[60:63]
	v_mfma_f32_16x16x32_bf16 v[48:51], v[150:153], v[190:193], v[48:51]
	v_mfma_f32_16x16x32_bf16 v[44:47], v[138:141], v[198:201], v[44:47]
	v_mfma_f32_16x16x32_bf16 v[32:35], v[150:153], v[198:201], v[32:35]
	v_mfma_f32_16x16x32_bf16 v[28:31], v[138:141], v[206:209], v[28:31]
	v_mfma_f32_16x16x32_bf16 v[16:19], v[150:153], v[206:209], v[16:19]
	v_mfma_f32_16x16x32_bf16 v[12:15], v[138:141], v[214:217], v[12:15]
	v_mfma_f32_16x16x32_bf16 v[0:3], v[150:153], v[214:217], v[0:3]
	v_mfma_f32_16x16x32_bf16 v[60:63], v[142:145], v[194:197], v[60:63]
	v_mfma_f32_16x16x32_bf16 v[48:51], v[154:157], v[194:197], v[48:51]
	v_mfma_f32_16x16x32_bf16 v[44:47], v[142:145], v[202:205], v[44:47]
	v_mfma_f32_16x16x32_bf16 v[32:35], v[154:157], v[202:205], v[32:35]
	v_mfma_f32_16x16x32_bf16 v[28:31], v[142:145], v[210:213], v[28:31]
	v_mfma_f32_16x16x32_bf16 v[16:19], v[154:157], v[210:213], v[16:19]
	v_mfma_f32_16x16x32_bf16 v[12:15], v[142:145], v[238:241], v[12:15]
	v_mfma_f32_16x16x32_bf16 v[0:3], v[154:157], v[238:241], v[0:3]
	v_mfma_f32_16x16x32_bf16 v[56:59], v[174:177], v[190:193], v[56:59]
	v_mfma_f32_16x16x32_bf16 v[52:55], v[182:185], v[190:193], v[52:55]
	v_mfma_f32_16x16x32_bf16 v[40:43], v[174:177], v[198:201], v[40:43]
	v_mfma_f32_16x16x32_bf16 v[36:39], v[182:185], v[198:201], v[36:39]
	v_mfma_f32_16x16x32_bf16 v[24:27], v[174:177], v[206:209], v[24:27]
	v_mfma_f32_16x16x32_bf16 v[20:23], v[182:185], v[206:209], v[20:23]
	v_mfma_f32_16x16x32_bf16 v[8:11], v[174:177], v[214:217], v[8:11]
	v_mfma_f32_16x16x32_bf16 v[4:7], v[182:185], v[214:217], v[4:7]
	v_mfma_f32_16x16x32_bf16 v[56:59], v[178:181], v[194:197], v[56:59]
	v_mfma_f32_16x16x32_bf16 v[52:55], v[186:189], v[194:197], v[52:55]
	v_mfma_f32_16x16x32_bf16 v[40:43], v[178:181], v[202:205], v[40:43]
	v_mfma_f32_16x16x32_bf16 v[36:39], v[186:189], v[202:205], v[36:39]
	v_mfma_f32_16x16x32_bf16 v[24:27], v[178:181], v[210:213], v[24:27]
	v_mfma_f32_16x16x32_bf16 v[20:23], v[186:189], v[210:213], v[20:23]
	v_mfma_f32_16x16x32_bf16 v[8:11], v[178:181], v[238:241], v[8:11]
	v_mfma_f32_16x16x32_bf16 v[4:7], v[186:189], v[238:241], v[4:7]
	s_barrier
	s_add_i32 s21, s21, 2
	s_add_u32 s92, s92, 0x100
	s_addc_u32 s93, s93, 0
	s_add_u32 s10, s10, 0x100
	s_addc_u32 s11, s11, 0
	s_cmp_gt_u32 s21, 13
	s_cbranch_scc0 .LBB0_474
	v_lshl_add_u32 v192, s8, 8, v146
	v_lshlrev_b32_e32 v192, 3, v192
	global_load_dwordx2 v[176:177], v192, s[4:5]
	global_load_dwordx2 v[178:179], v192, s[4:5] offset:128
	global_load_dwordx2 v[180:181], v192, s[4:5] offset:256
	global_load_dwordx2 v[182:183], v192, s[4:5] offset:384
	global_load_dwordx2 v[184:185], v192, s[4:5] offset:1024
	global_load_dwordx2 v[186:187], v192, s[4:5] offset:1152
	global_load_dwordx2 v[188:189], v192, s[4:5] offset:1280
	global_load_dwordx2 v[190:191], v192, s[4:5] offset:1408
	s_and_b64 vcc, exec, s[6:7]
	s_cbranch_vccz .LBB0_477
	s_barrier
